# EpiConv: halo rows merged through the LDS read address (per-lane select) instead of separate halo reads + v_cndmask: 32 fewer VALU and 32 fewer LDS reads per wave-unit
# speedup vs baseline: 1.0031x; 1.0031x over previous
;     __device__ __forceinline__ void operator()(const f32x4 (&acc)[2][2][4][2], const Unit& u, int wr, int wc, int fr, int fq) const {
;     ...
;         if (u.pm < 132) { const int b = u.pm / 33, i = u.pm - b * 33; seqrow = b * 8192; tstart = 254 * i - 1; T = 8192; vlo = 1; vhi = 255; }
;         else { seqrow = 32768 + (u.pm - 132) * 256; tstart = 0; T = 256; vlo = 0; vhi = 256; }
;         const bool edge = (tstart <= 0) || (tstart + 256 >= T);
;         const int ch0 = 128 * u.pn + 32 * wc + 8 * fq;
;         f32x4 w0[2], w1[2], w2[2], bb[2];
; #pragma unroll
;         for (int bj = 0; bj < 2; ++bj) { const int col = bj * 2816 + ch0;
;             w0[bj] = *(const f32x4*)(cw + col); w1[bj] = *(const f32x4*)(cw + 5632 + col); w2[bj] = *(const f32x4*)(cw + 11264 + col); bb[bj] = *(const f32x4*)(cb + col); }
; #pragma unroll
;         for (int ai = 0; ai < 2; ++ai) { const int blk = ai * 2 + wr;
;             if (fr == 0) {
; #pragma unroll
;                 for (int bj = 0; bj < 2; ++bj)
; #pragma unroll
;                     for (int n = 0; n < 2; ++n) *(PG8_LAS f32x4*)(xb + ((((blk * 2 + 0) * 4 + wc) * 4 + fq) * 16 + (bj * 2 + n) * 4)) = acc[ai][bj][0][n]; }
;             if (fr == 15) {
; #pragma unroll
;                 for (int bj = 0; bj < 2; ++bj)
; #pragma unroll
;                     for (int n = 0; n < 2; ++n) *(PG8_LAS f32x4*)(xb + ((((blk * 2 + 1) * 4 + wc) * 4 + fq) * 16 + (bj * 2 + n) * 4)) = acc[ai][bj][3][n]; } }
;         asm volatile("s_waitcnt lgkmcnt(0)" ::: "memory"); __builtin_amdgcn_s_barrier(); asm volatile("" ::: "memory");
;         const f32x4 zero4 = {0.f, 0.f, 0.f, 0.f};
; #pragma unroll
;         for (int n = 0; n < 2; ++n) {
;             if (n == 1) {
; #pragma unroll
;                 for (int bj = 0; bj < 2; ++bj) { const int col = bj * 2816 + ch0 + 4;
;                     w0[bj] = *(const f32x4*)(cw + col); w1[bj] = *(const f32x4*)(cw + 5632 + col); w2[bj] = *(const f32x4*)(cw + 11264 + col); bb[bj] = *(const f32x4*)(cb + col); } }
; #pragma unroll
;             for (int ai = 0; ai < 2; ++ai) { const int blk = ai * 2 + wr;
; #pragma unroll
;                 for (int m = 0; m < 4; ++m) { const int r = 128 * ai + 64 * wr + 16 * m + fr, t = tstart + r;
;                     const bool upok = t >= 1, dnok = (t + 1) < T, store_ok = (r >= vlo) && (r < vhi) && (t < T);
;                     f32x4 res[2];
; #pragma unroll
.LBB0_705:
	v_lshl_or_b32 v248, s2, 7, v229
	v_lshlrev_b32_e32 v247, 1, v248
	v_lshlrev_b32_e32 v248, 2, v248
	v_add_u32_e32 v249, 0x2c00, v248
	global_load_dwordx4 v[106:109], v248, s[62:63]
	global_load_dwordx4 v[110:113], v248, s[66:67]
	global_load_dwordx4 v[114:117], v248, s[68:69]
	global_load_dwordx4 v[118:121], v248, s[64:65]
	global_load_dwordx4 v[122:125], v249, s[62:63]
	global_load_dwordx4 v[126:129], v249, s[66:67]
	global_load_dwordx4 v[130:133], v249, s[68:69]
	global_load_dwordx4 v[134:137], v249, s[64:65]
	v_readlane_b32 s10, v254, 4
	v_readlane_b32 s11, v254, 5
	s_add_i32 s0, s78, s48
	s_mulk_i32 s0, 0x1600
	s_movk_i32 s29, 0x1600
	s_add_i32 s28, s93, -1
	v_add_u32_e32 v247, s0, v247
	v_mov_b32_e32 v202, 0
	v_mov_b32_e32 v203, 0
	v_and_b32_e32 v250, 7, v226
	v_lshlrev_b32_e32 v250, 3, v250
	v_add_u32_e32 v250, 0x27000, v250
	ds_write_b64 v250, v[202:203]
	s_mov_b64 exec, s[6:7]
	ds_write_b128 v238, v[166:169]
	ds_write_b128 v238, v[70:73] offset:16
	ds_write_b128 v238, v[162:165] offset:32
	ds_write_b128 v238, v[66:69] offset:48
	ds_write_b128 v239, v[102:105]
	ds_write_b128 v239, v[30:33] offset:16
	ds_write_b128 v239, v[98:101] offset:32
	ds_write_b128 v239, v[26:29] offset:48
	s_mov_b64 exec, s[4:5]
	ds_write_b128 v238, v[142:145] offset:1024
	ds_write_b128 v238, v[46:49] offset:1040
	ds_write_b128 v238, v[138:141] offset:1056
	ds_write_b128 v238, v[42:45] offset:1072
	ds_write_b128 v239, v[78:81] offset:1024
	ds_write_b128 v239, v[6:9] offset:1040
	ds_write_b128 v239, v[74:77] offset:1056
	ds_write_b128 v239, v[2:5] offset:1072
	s_mov_b64 exec, -1
	v_and_b32_e32 v250, 0xb80, v238
	v_lshlrev_b32_e32 v250, 3, v250
	v_bfe_u32 v251, v238, 6, 1
	v_lshl_add_u32 v250, v251, 3, v250
	v_lshl_add_u32 v250, v226, 4, v250
	v_add_u32_e32 v243, 0x20000, v250
	v_add_u32_e32 v244, 0xfffffff0, v243
	v_add_u32_e32 v250, 0xfffffc00, v238
	v_mov_b32_e32 v251, 0x27000
	v_cndmask_b32_e64 v245, v251, v250, s[74:75]
	v_add_u32_e32 v250, 0x800, v239
	v_cndmask_b32_e64 v246, v250, v251, s[74:75]
	v_cndmask_b32_e64 v38, 0, 1, s[6:7]
	v_cndmask_b32_e64 v39, 0, 1, s[4:5]
	v_cndmask_b32_e64 v198, v244, v245, s[6:7]
	v_add_u32_e32 v250, 0xc00, v238
	v_cndmask_b32_e64 v199, v244, v250, s[6:7]
	v_add_u32_e32 v251, 0x310, v243
	v_add_u32_e32 v250, 0x800, v238
	v_cndmask_b32_e64 v200, v251, v250, s[4:5]
	v_cndmask_b32_e64 v201, v251, v246, s[4:5]
	s_waitcnt lgkmcnt(0)
	s_barrier
	s_cmp_lt_i32 s48, 1
	s_cbranch_scc1 .Lec_edge
	s_add_i32 s0, s48, 0x100
	s_cmp_ge_i32 s0, s93
	s_cbranch_scc1 .Lec_edge
	v_cmp_le_i32_e64 s[12:13], s54, v227
	v_cmp_gt_i32_e32 vcc, s55, v227
	s_and_b64 s[12:13], s[12:13], vcc
	v_cmp_le_i32_e64 s[14:15], s54, v231
	v_cmp_gt_i32_e32 vcc, s55, v231
	s_and_b64 s[14:15], s[14:15], vcc
	v_cmp_le_i32_e64 s[16:17], s54, v232
	v_cmp_gt_i32_e32 vcc, s55, v232
	s_and_b64 s[16:17], s[16:17], vcc
	v_cmp_le_i32_e64 s[18:19], s54, v233
	v_cmp_gt_i32_e32 vcc, s55, v233
	s_and_b64 s[18:19], s[18:19], vcc
	v_cmp_le_i32_e64 s[20:21], s54, v234
	v_cmp_gt_i32_e32 vcc, s55, v234
	s_and_b64 s[20:21], s[20:21], vcc
	v_cmp_le_i32_e64 s[22:23], s54, v235
	v_cmp_gt_i32_e32 vcc, s55, v235
	s_and_b64 s[22:23], s[22:23], vcc
	v_cmp_le_i32_e64 s[24:25], s54, v236
	v_cmp_gt_i32_e32 vcc, s55, v236
	s_and_b64 s[24:25], s[24:25], vcc
	v_cmp_le_i32_e64 s[26:27], s54, v237
	v_cmp_gt_i32_e32 vcc, s55, v237
	s_and_b64 s[26:27], s[26:27], vcc
	ds_write_b64 v243, v[166:167]
	ds_write_b64 v243, v[158:159] offset:256
	ds_write_b64 v243, v[150:151] offset:512
	ds_write_b64 v243, v[142:143] offset:768
	v_mad_u32_u24 v250, v38, 0, v198
	ds_read_b64 v[170:171], v250
	ds_read_b64 v[178:179], v243 offset:16
	ds_read_b64 v[172:173], v244 offset:256
	ds_read_b64 v[180:181], v243 offset:272
	ds_read_b64 v[174:175], v244 offset:512
	ds_read_b64 v[194:195], v243 offset:528
	ds_read_b64 v[176:177], v244 offset:768
	v_mad_u32_u24 v251, v39, 0, v200
	ds_read_b64 v[196:197], v251
	s_waitcnt vmcnt(0)
	ds_write_b64 v243, v[168:169]
	ds_write_b64 v243, v[160:161] offset:256
	ds_write_b64 v243, v[152:153] offset:512
	ds_write_b64 v243, v[144:145] offset:768
	s_waitcnt lgkmcnt(10)
	v_pk_fma_f32 v[202:203], v[106:107], v[170:171], v[118:119]
	v_pk_fma_f32 v[166:167], v[166:167], v[110:111], v[202:203]
	v_pk_fma_f32 v[166:167], v[114:115], v[178:179], v[166:167]
	v_mad_u32_u24 v250, v38, 8, v198
	ds_read_b64 v[170:171], v250
	ds_read_b64 v[178:179], v243 offset:16
	s_waitcnt lgkmcnt(10)
	v_pk_fma_f32 v[202:203], v[106:107], v[172:173], v[118:119]
	v_pk_fma_f32 v[158:159], v[158:159], v[110:111], v[202:203]
	v_pk_fma_f32 v[158:159], v[114:115], v[180:181], v[158:159]
	ds_read_b64 v[172:173], v244 offset:256
	ds_read_b64 v[180:181], v243 offset:272
	s_waitcnt lgkmcnt(10)
	v_pk_fma_f32 v[202:203], v[106:107], v[174:175], v[118:119]
	v_pk_fma_f32 v[150:151], v[150:151], v[110:111], v[202:203]
	v_pk_fma_f32 v[150:151], v[114:115], v[194:195], v[150:151]
	ds_read_b64 v[174:175], v244 offset:512
	ds_read_b64 v[194:195], v243 offset:528
	s_waitcnt lgkmcnt(10)
	v_pk_fma_f32 v[202:203], v[106:107], v[176:177], v[118:119]
	v_pk_fma_f32 v[142:143], v[142:143], v[110:111], v[202:203]
	v_pk_fma_f32 v[142:143], v[114:115], v[196:197], v[142:143]
	ds_read_b64 v[176:177], v244 offset:768
	v_mad_u32_u24 v251, v39, 8, v200
	ds_read_b64 v[196:197], v251
	ds_write_b64 v243, v[162:163]
	ds_write_b64 v243, v[154:155] offset:256
	ds_write_b64 v243, v[146:147] offset:512
	ds_write_b64 v243, v[138:139] offset:768
	s_waitcnt lgkmcnt(10)
	v_pk_fma_f32 v[202:203], v[108:109], v[170:171], v[120:121]
	v_pk_fma_f32 v[168:169], v[168:169], v[112:113], v[202:203]
	v_pk_fma_f32 v[168:169], v[116:117], v[178:179], v[168:169]
	v_mad_u32_u24 v250, v38, 32, v198
	ds_read_b64 v[170:171], v250
	ds_read_b64 v[178:179], v243 offset:16
	s_waitcnt lgkmcnt(10)
; #define PG8_LAS __attribute__((address_space(3)))
; __device__ __forceinline__ unsigned cvt_pk_bf16(float lo, float hi) { unsigned r; asm volatile("v_cvt_pk_bf16_f32 %0, %1, %2" : "=v"(r) : "v"(lo), "v"(hi)); return r; }
; __device__ __forceinline__ float dpp_ror1(float v) { return __builtin_bit_cast(float, __builtin_amdgcn_update_dpp(0, __builtin_bit_cast(int, v), 0x121, 0xf, 0xf, false)); }
; __device__ __forceinline__ float dpp_ror15(float v) { return __builtin_bit_cast(float, __builtin_amdgcn_update_dpp(0, __builtin_bit_cast(int, v), 0x12F, 0xf, 0xf, false)); }
;     __device__ __forceinline__ void operator()(const f32x4 (&acc)[2][2][4][2], const Unit& u, int wr, int wc, int fr, int fq) const {
;     ...
;                     for (int bj = 0; bj < 2; ++bj) { const f32x4 cur = acc[ai][bj][m][n];
;                         f32x4 su = cur, sd = cur;
;                         if (m > 0) { if (fr == 15) su = acc[ai][bj][m > 0 ? m - 1 : 0][n]; }
;                         if (m < 3) { if (fr == 0) sd = acc[ai][bj][m < 3 ? m + 1 : 3][n]; }
;                         f32x4 up, dn;
;                         up[0] = dpp_ror1(su[0]); up[1] = dpp_ror1(su[1]); up[2] = dpp_ror1(su[2]); up[3] = dpp_ror1(su[3]);
;                         dn[0] = dpp_ror15(sd[0]); dn[1] = dpp_ror15(sd[1]); dn[2] = dpp_ror15(sd[2]); dn[3] = dpp_ror15(sd[3]);
;                         if (m == 0) { f32x4 halo = zero4; if (blk > 0) halo = *(const PG8_LAS f32x4*)(xb + (((((blk - 1) * 2 + 1) * 4 + wc) * 4 + fq) * 16 + (bj * 2 + n) * 4)); if (fr == 0) up = halo; }
;                         if (m == 3) { f32x4 halo = zero4; if (blk < 3) halo = *(const PG8_LAS f32x4*)(xb + (((((blk + 1) * 2 + 0) * 4 + wc) * 4 + fq) * 16 + (bj * 2 + n) * 4)); if (fr == 15) dn = halo; }
;                         if (edge) { if (!upok) up = zero4; if (!dnok) dn = zero4; }
;                         res[bj] = bb[bj] + w0[bj] * up + w1[bj] * cur + w2[bj] * dn; }
;                     if (store_ok) {
;                         float o[4];
; #pragma unroll
;                         for (int j = 0; j < 4; ++j) { const float gg = res[1][j]; o[j] = gg * __builtin_amdgcn_rcpf(1.f + __expf(-gg)) * res[0][j]; }
;                         u32x2 w; w.x = cvt_pk_bf16(o[0], o[1]); w.y = cvt_pk_bf16(o[2], o[3]);
;                         *(u32x2*)(ACT + (size_t)(seqrow + t) * 2816 + ch0 + 4 * n) = w; } } }
	v_pk_fma_f32 v[202:203], v[108:109], v[172:173], v[120:121]
	v_pk_fma_f32 v[160:161], v[160:161], v[112:113], v[202:203]
	v_pk_fma_f32 v[160:161], v[116:117], v[180:181], v[160:161]
	ds_read_b64 v[172:173], v244 offset:256
	ds_read_b64 v[180:181], v243 offset:272
	s_waitcnt lgkmcnt(10)
	v_pk_fma_f32 v[202:203], v[108:109], v[174:175], v[120:121]
	v_pk_fma_f32 v[152:153], v[152:153], v[112:113], v[202:203]
	v_pk_fma_f32 v[152:153], v[116:117], v[194:195], v[152:153]
	ds_read_b64 v[174:175], v244 offset:512
	ds_read_b64 v[194:195], v243 offset:528
	s_waitcnt lgkmcnt(10)
	v_pk_fma_f32 v[202:203], v[108:109], v[176:177], v[120:121]
	v_pk_fma_f32 v[144:145], v[144:145], v[112:113], v[202:203]
	v_pk_fma_f32 v[144:145], v[116:117], v[196:197], v[144:145]
	ds_read_b64 v[176:177], v244 offset:768
	v_mad_u32_u24 v251, v39, 32, v200
	ds_read_b64 v[196:197], v251
	ds_write_b64 v243, v[164:165]
	ds_write_b64 v243, v[156:157] offset:256
	ds_write_b64 v243, v[148:149] offset:512
	ds_write_b64 v243, v[140:141] offset:768
	s_waitcnt lgkmcnt(10)
	v_pk_fma_f32 v[202:203], v[122:123], v[170:171], v[134:135]
	v_pk_fma_f32 v[162:163], v[162:163], v[126:127], v[202:203]
	v_pk_fma_f32 v[162:163], v[130:131], v[178:179], v[162:163]
	v_mad_u32_u24 v250, v38, 40, v198
	ds_read_b64 v[170:171], v250
	ds_read_b64 v[178:179], v243 offset:16
	s_waitcnt lgkmcnt(10)
	v_pk_fma_f32 v[202:203], v[122:123], v[172:173], v[134:135]
	v_pk_fma_f32 v[154:155], v[154:155], v[126:127], v[202:203]
	v_pk_fma_f32 v[154:155], v[130:131], v[180:181], v[154:155]
	ds_read_b64 v[172:173], v244 offset:256
	ds_read_b64 v[180:181], v243 offset:272
	s_waitcnt lgkmcnt(10)
	v_pk_fma_f32 v[202:203], v[122:123], v[174:175], v[134:135]
	v_pk_fma_f32 v[146:147], v[146:147], v[126:127], v[202:203]
	v_pk_fma_f32 v[146:147], v[130:131], v[194:195], v[146:147]
	ds_read_b64 v[174:175], v244 offset:512
	ds_read_b64 v[194:195], v243 offset:528
	s_waitcnt lgkmcnt(10)
	v_pk_fma_f32 v[202:203], v[122:123], v[176:177], v[134:135]
	v_pk_fma_f32 v[138:139], v[138:139], v[126:127], v[202:203]
	v_pk_fma_f32 v[138:139], v[130:131], v[196:197], v[138:139]
	ds_read_b64 v[176:177], v244 offset:768
	v_mad_u32_u24 v251, v39, 40, v200
	ds_read_b64 v[196:197], v251
	ds_write_b64 v243, v[102:103]
	ds_write_b64 v243, v[94:95] offset:256
	ds_write_b64 v243, v[86:87] offset:512
	ds_write_b64 v243, v[78:79] offset:768
	s_waitcnt lgkmcnt(10)
	v_pk_fma_f32 v[202:203], v[124:125], v[170:171], v[136:137]
	v_pk_fma_f32 v[164:165], v[164:165], v[128:129], v[202:203]
	v_pk_fma_f32 v[164:165], v[132:133], v[178:179], v[164:165]
	v_mad_u32_u24 v250, v38, 0, v199
	ds_read_b64 v[170:171], v250
	ds_read_b64 v[178:179], v243 offset:16
	s_waitcnt lgkmcnt(10)
	v_pk_fma_f32 v[202:203], v[124:125], v[172:173], v[136:137]
	v_pk_fma_f32 v[156:157], v[156:157], v[128:129], v[202:203]
	v_pk_fma_f32 v[156:157], v[132:133], v[180:181], v[156:157]
	ds_read_b64 v[172:173], v244 offset:256
	ds_read_b64 v[180:181], v243 offset:272
	s_waitcnt lgkmcnt(10)
	v_pk_fma_f32 v[202:203], v[124:125], v[174:175], v[136:137]
	v_pk_fma_f32 v[148:149], v[148:149], v[128:129], v[202:203]
	v_pk_fma_f32 v[148:149], v[132:133], v[194:195], v[148:149]
	ds_read_b64 v[174:175], v244 offset:512
	ds_read_b64 v[194:195], v243 offset:528
	s_waitcnt lgkmcnt(10)
	v_pk_fma_f32 v[202:203], v[124:125], v[176:177], v[136:137]
	v_pk_fma_f32 v[140:141], v[140:141], v[128:129], v[202:203]
	v_pk_fma_f32 v[140:141], v[132:133], v[196:197], v[140:141]
	ds_read_b64 v[176:177], v244 offset:768
	v_mad_u32_u24 v251, v39, 0, v201
	ds_read_b64 v[196:197], v251
	v_mul_f32_e32 v208, 0xbfb8aa3b, v162
	v_mul_f32_e32 v209, 0xbfb8aa3b, v163
	v_mul_f32_e32 v210, 0xbfb8aa3b, v164
	v_mul_f32_e32 v211, 0xbfb8aa3b, v165
	v_exp_f32_e32 v208, v208
	v_exp_f32_e32 v209, v209
	v_exp_f32_e32 v210, v210
	v_exp_f32_e32 v211, v211
	v_add_f32_e32 v208, 1.0, v208
	v_add_f32_e32 v209, 1.0, v209
	v_add_f32_e32 v210, 1.0, v210
	v_add_f32_e32 v211, 1.0, v211
	v_rcp_f32_e32 v208, v208
	v_rcp_f32_e32 v209, v209
	v_rcp_f32_e32 v210, v210
	v_rcp_f32_e32 v211, v211
	v_mul_f32_e32 v162, v162, v208
	v_mul_f32_e32 v163, v163, v209
	v_mul_f32_e32 v164, v164, v210
	v_mul_f32_e32 v165, v165, v211
	v_mul_f32_e32 v162, v166, v162
	v_mul_f32_e32 v163, v167, v163
	v_mul_f32_e32 v164, v168, v164
	v_mul_f32_e32 v165, v169, v165
	v_cvt_pk_bf16_f32 v212, v162, v163
	v_cvt_pk_bf16_f32 v213, v164, v165
	v_mad_u32_u24 v221, v227, s29, v247
	s_and_saveexec_b64 s[30:31], s[12:13]
	global_store_dwordx2 v221, v[212:213], s[10:11]
	s_mov_b64 exec, s[30:31]
	v_mul_f32_e32 v208, 0xbfb8aa3b, v154
	v_mul_f32_e32 v209, 0xbfb8aa3b, v155
	v_mul_f32_e32 v210, 0xbfb8aa3b, v156
	v_mul_f32_e32 v211, 0xbfb8aa3b, v157
	v_exp_f32_e32 v208, v208
	v_exp_f32_e32 v209, v209
	v_exp_f32_e32 v210, v210
	v_exp_f32_e32 v211, v211
	v_add_f32_e32 v208, 1.0, v208
	v_add_f32_e32 v209, 1.0, v209
	v_add_f32_e32 v210, 1.0, v210
	v_add_f32_e32 v211, 1.0, v211
	v_rcp_f32_e32 v208, v208
	v_rcp_f32_e32 v209, v209
	v_rcp_f32_e32 v210, v210
	v_rcp_f32_e32 v211, v211
	v_mul_f32_e32 v154, v154, v208
	v_mul_f32_e32 v155, v155, v209
	v_mul_f32_e32 v156, v156, v210
	v_mul_f32_e32 v157, v157, v211
	v_mul_f32_e32 v154, v158, v154
	v_mul_f32_e32 v155, v159, v155
	v_mul_f32_e32 v156, v160, v156
	v_mul_f32_e32 v157, v161, v157
	v_cvt_pk_bf16_f32 v218, v154, v155
	v_cvt_pk_bf16_f32 v219, v156, v157
	v_mad_u32_u24 v40, v231, s29, v247
	s_and_saveexec_b64 s[30:31], s[14:15]
	global_store_dwordx2 v40, v[218:219], s[10:11]
	s_mov_b64 exec, s[30:31]
	v_mul_f32_e32 v208, 0xbfb8aa3b, v146
	v_mul_f32_e32 v209, 0xbfb8aa3b, v147
	v_mul_f32_e32 v210, 0xbfb8aa3b, v148
	v_mul_f32_e32 v211, 0xbfb8aa3b, v149
;     __device__ __forceinline__ void operator()(const f32x4 (&acc)[2][2][4][2], const Unit& u, int wr, int wc, int fr, int fq) const {
;     ...
;                 for (int bj = 0; bj < 2; ++bj) { const int col = bj * 2816 + ch0 + 4;
;                     w0[bj] = *(const f32x4*)(cw + col); w1[bj] = *(const f32x4*)(cw + 5632 + col); w2[bj] = *(const f32x4*)(cw + 11264 + col); bb[bj] = *(const f32x4*)(cb + col); } }
; #pragma unroll
;             for (int ai = 0; ai < 2; ++ai) { const int blk = ai * 2 + wr;
; #pragma unroll
;                 for (int m = 0; m < 4; ++m) { const int r = 128 * ai + 64 * wr + 16 * m + fr, t = tstart + r;
;                     const bool upok = t >= 1, dnok = (t + 1) < T, store_ok = (r >= vlo) && (r < vhi) && (t < T);
;                     f32x4 res[2];
; #pragma unroll
;                     for (int bj = 0; bj < 2; ++bj) { const f32x4 cur = acc[ai][bj][m][n];
;                         f32x4 su = cur, sd = cur;
;                         if (m > 0) { if (fr == 15) su = acc[ai][bj][m > 0 ? m - 1 : 0][n]; }
;                         if (m < 3) { if (fr == 0) sd = acc[ai][bj][m < 3 ? m + 1 : 3][n]; }
;                         f32x4 up, dn;
;                         up[0] = dpp_ror1(su[0]); up[1] = dpp_ror1(su[1]); up[2] = dpp_ror1(su[2]); up[3] = dpp_ror1(su[3]);
;                         dn[0] = dpp_ror15(sd[0]); dn[1] = dpp_ror15(sd[1]); dn[2] = dpp_ror15(sd[2]); dn[3] = dpp_ror15(sd[3]);
;                         if (m == 0) { f32x4 halo = zero4; if (blk > 0) halo = *(const PG8_LAS f32x4*)(xb + (((((blk - 1) * 2 + 1) * 4 + wc) * 4 + fq) * 16 + (bj * 2 + n) * 4)); if (fr == 0) up = halo; }
;                         if (m == 3) { f32x4 halo = zero4; if (blk < 3) halo = *(const PG8_LAS f32x4*)(xb + (((((blk + 1) * 2 + 0) * 4 + wc) * 4 + fq) * 16 + (bj * 2 + n) * 4)); if (fr == 15) dn = halo; }
;                         if (edge) { if (!upok) up = zero4; if (!dnok) dn = zero4; }
;                         res[bj] = bb[bj] + w0[bj] * up + w1[bj] * cur + w2[bj] * dn; }
;                     if (store_ok) {
;                         float o[4];
; #pragma unroll
;                         for (int j = 0; j < 4; ++j) { const float gg = res[1][j]; o[j] = gg * __builtin_amdgcn_rcpf(1.f + __expf(-gg)) * res[0][j]; }
;                         u32x2 w; w.x = cvt_pk_bf16(o[0], o[1]); w.y = cvt_pk_bf16(o[2], o[3]);
	v_exp_f32_e32 v208, v208
	v_exp_f32_e32 v209, v209
	v_exp_f32_e32 v210, v210
	v_exp_f32_e32 v211, v211
	v_add_f32_e32 v208, 1.0, v208
	v_add_f32_e32 v209, 1.0, v209
	v_add_f32_e32 v210, 1.0, v210
	v_add_f32_e32 v211, 1.0, v211
	v_rcp_f32_e32 v208, v208
	v_rcp_f32_e32 v209, v209
	v_rcp_f32_e32 v210, v210
	v_rcp_f32_e32 v211, v211
	v_mul_f32_e32 v146, v146, v208
	v_mul_f32_e32 v147, v147, v209
	v_mul_f32_e32 v148, v148, v210
	v_mul_f32_e32 v149, v149, v211
	v_mul_f32_e32 v146, v150, v146
	v_mul_f32_e32 v147, v151, v147
	v_mul_f32_e32 v148, v152, v148
	v_mul_f32_e32 v149, v153, v149
	v_cvt_pk_bf16_f32 v212, v146, v147
	v_cvt_pk_bf16_f32 v213, v148, v149
	v_mad_u32_u24 v221, v232, s29, v247
	s_and_saveexec_b64 s[30:31], s[16:17]
	global_store_dwordx2 v221, v[212:213], s[10:11]
	s_mov_b64 exec, s[30:31]
	v_mul_f32_e32 v208, 0xbfb8aa3b, v138
	v_mul_f32_e32 v209, 0xbfb8aa3b, v139
	v_mul_f32_e32 v210, 0xbfb8aa3b, v140
	v_mul_f32_e32 v211, 0xbfb8aa3b, v141
	v_exp_f32_e32 v208, v208
	v_exp_f32_e32 v209, v209
	v_exp_f32_e32 v210, v210
	v_exp_f32_e32 v211, v211
	v_add_f32_e32 v208, 1.0, v208
	v_add_f32_e32 v209, 1.0, v209
	v_add_f32_e32 v210, 1.0, v210
	v_add_f32_e32 v211, 1.0, v211
	v_rcp_f32_e32 v208, v208
	v_rcp_f32_e32 v209, v209
	v_rcp_f32_e32 v210, v210
	v_rcp_f32_e32 v211, v211
	v_mul_f32_e32 v138, v138, v208
	v_mul_f32_e32 v139, v139, v209
	v_mul_f32_e32 v140, v140, v210
	v_mul_f32_e32 v141, v141, v211
	v_mul_f32_e32 v138, v142, v138
	v_mul_f32_e32 v139, v143, v139
	v_mul_f32_e32 v140, v144, v140
	v_mul_f32_e32 v141, v145, v141
	v_cvt_pk_bf16_f32 v218, v138, v139
	v_cvt_pk_bf16_f32 v219, v140, v141
	v_mad_u32_u24 v40, v233, s29, v247
	s_and_saveexec_b64 s[30:31], s[18:19]
	global_store_dwordx2 v40, v[218:219], s[10:11]
	s_mov_b64 exec, s[30:31]
	global_load_dwordx4 v[138:141], v248, s[62:63] offset:16
	global_load_dwordx4 v[142:145], v248, s[66:67] offset:16
	global_load_dwordx4 v[146:149], v248, s[68:69] offset:16
	global_load_dwordx4 v[150:153], v248, s[64:65] offset:16
	global_load_dwordx4 v[154:157], v249, s[62:63] offset:16
	global_load_dwordx4 v[158:161], v249, s[66:67] offset:16
	global_load_dwordx4 v[162:165], v249, s[68:69] offset:16
	global_load_dwordx4 v[166:169], v249, s[64:65] offset:16
	ds_write_b64 v243, v[104:105]
	ds_write_b64 v243, v[96:97] offset:256
	ds_write_b64 v243, v[88:89] offset:512
	ds_write_b64 v243, v[80:81] offset:768
	s_waitcnt lgkmcnt(10)
	v_pk_fma_f32 v[202:203], v[106:107], v[170:171], v[118:119]
	v_pk_fma_f32 v[102:103], v[102:103], v[110:111], v[202:203]
	v_pk_fma_f32 v[102:103], v[114:115], v[178:179], v[102:103]
	v_mad_u32_u24 v250, v38, 8, v199
	ds_read_b64 v[170:171], v250
	ds_read_b64 v[178:179], v243 offset:16
	s_waitcnt lgkmcnt(10)
	v_pk_fma_f32 v[202:203], v[106:107], v[172:173], v[118:119]
	v_pk_fma_f32 v[94:95], v[94:95], v[110:111], v[202:203]
	v_pk_fma_f32 v[94:95], v[114:115], v[180:181], v[94:95]
	ds_read_b64 v[172:173], v244 offset:256
	ds_read_b64 v[180:181], v243 offset:272
	s_waitcnt lgkmcnt(10)
	v_pk_fma_f32 v[202:203], v[106:107], v[174:175], v[118:119]
	v_pk_fma_f32 v[86:87], v[86:87], v[110:111], v[202:203]
	v_pk_fma_f32 v[86:87], v[114:115], v[194:195], v[86:87]
	ds_read_b64 v[174:175], v244 offset:512
	ds_read_b64 v[194:195], v243 offset:528
	s_waitcnt lgkmcnt(10)
	v_pk_fma_f32 v[202:203], v[106:107], v[176:177], v[118:119]
	v_pk_fma_f32 v[78:79], v[78:79], v[110:111], v[202:203]
	v_pk_fma_f32 v[78:79], v[114:115], v[196:197], v[78:79]
	ds_read_b64 v[176:177], v244 offset:768
	v_mad_u32_u24 v251, v39, 8, v201
	ds_read_b64 v[196:197], v251
	ds_write_b64 v243, v[98:99]
	ds_write_b64 v243, v[90:91] offset:256
	ds_write_b64 v243, v[82:83] offset:512
	ds_write_b64 v243, v[74:75] offset:768
	s_waitcnt lgkmcnt(10)
	v_pk_fma_f32 v[202:203], v[108:109], v[170:171], v[120:121]
	v_pk_fma_f32 v[104:105], v[104:105], v[112:113], v[202:203]
	v_pk_fma_f32 v[104:105], v[116:117], v[178:179], v[104:105]
	v_mad_u32_u24 v250, v38, 32, v199
	ds_read_b64 v[170:171], v250
	ds_read_b64 v[178:179], v243 offset:16
	s_waitcnt lgkmcnt(10)
	v_pk_fma_f32 v[202:203], v[108:109], v[172:173], v[120:121]
	v_pk_fma_f32 v[96:97], v[96:97], v[112:113], v[202:203]
	v_pk_fma_f32 v[96:97], v[116:117], v[180:181], v[96:97]
	ds_read_b64 v[172:173], v244 offset:256
	ds_read_b64 v[180:181], v243 offset:272
	s_waitcnt lgkmcnt(10)
	v_pk_fma_f32 v[202:203], v[108:109], v[174:175], v[120:121]
	v_pk_fma_f32 v[88:89], v[88:89], v[112:113], v[202:203]
	v_pk_fma_f32 v[88:89], v[116:117], v[194:195], v[88:89]
	ds_read_b64 v[174:175], v244 offset:512
	ds_read_b64 v[194:195], v243 offset:528
	s_waitcnt lgkmcnt(10)
	v_pk_fma_f32 v[202:203], v[108:109], v[176:177], v[120:121]
	v_pk_fma_f32 v[80:81], v[80:81], v[112:113], v[202:203]
	v_pk_fma_f32 v[80:81], v[116:117], v[196:197], v[80:81]
	ds_read_b64 v[176:177], v244 offset:768
	v_mad_u32_u24 v251, v39, 32, v201
	ds_read_b64 v[196:197], v251
	ds_write_b64 v243, v[100:101]
	ds_write_b64 v243, v[92:93] offset:256
	ds_write_b64 v243, v[84:85] offset:512
	ds_write_b64 v243, v[76:77] offset:768
	s_waitcnt lgkmcnt(10)
	v_pk_fma_f32 v[202:203], v[122:123], v[170:171], v[134:135]
	v_pk_fma_f32 v[98:99], v[98:99], v[126:127], v[202:203]
	v_pk_fma_f32 v[98:99], v[130:131], v[178:179], v[98:99]
	v_mad_u32_u24 v250, v38, 40, v199
	ds_read_b64 v[170:171], v250
	ds_read_b64 v[178:179], v243 offset:16
	s_waitcnt lgkmcnt(10)
	v_pk_fma_f32 v[202:203], v[122:123], v[172:173], v[134:135]
	v_pk_fma_f32 v[90:91], v[90:91], v[126:127], v[202:203]
	v_pk_fma_f32 v[90:91], v[130:131], v[180:181], v[90:91]
	ds_read_b64 v[172:173], v244 offset:256
	ds_read_b64 v[180:181], v243 offset:272
	s_waitcnt lgkmcnt(10)
; #define PG8_LAS __attribute__((address_space(3)))
; __device__ __forceinline__ unsigned cvt_pk_bf16(float lo, float hi) { unsigned r; asm volatile("v_cvt_pk_bf16_f32 %0, %1, %2" : "=v"(r) : "v"(lo), "v"(hi)); return r; }
; __device__ __forceinline__ float dpp_ror1(float v) { return __builtin_bit_cast(float, __builtin_amdgcn_update_dpp(0, __builtin_bit_cast(int, v), 0x121, 0xf, 0xf, false)); }
; __device__ __forceinline__ float dpp_ror15(float v) { return __builtin_bit_cast(float, __builtin_amdgcn_update_dpp(0, __builtin_bit_cast(int, v), 0x12F, 0xf, 0xf, false)); }
;     __device__ __forceinline__ void operator()(const f32x4 (&acc)[2][2][4][2], const Unit& u, int wr, int wc, int fr, int fq) const {
;     ...
;                     for (int bj = 0; bj < 2; ++bj) { const f32x4 cur = acc[ai][bj][m][n];
;                         f32x4 su = cur, sd = cur;
;                         if (m > 0) { if (fr == 15) su = acc[ai][bj][m > 0 ? m - 1 : 0][n]; }
;                         if (m < 3) { if (fr == 0) sd = acc[ai][bj][m < 3 ? m + 1 : 3][n]; }
;                         f32x4 up, dn;
;                         up[0] = dpp_ror1(su[0]); up[1] = dpp_ror1(su[1]); up[2] = dpp_ror1(su[2]); up[3] = dpp_ror1(su[3]);
;                         dn[0] = dpp_ror15(sd[0]); dn[1] = dpp_ror15(sd[1]); dn[2] = dpp_ror15(sd[2]); dn[3] = dpp_ror15(sd[3]);
;                         if (m == 0) { f32x4 halo = zero4; if (blk > 0) halo = *(const PG8_LAS f32x4*)(xb + (((((blk - 1) * 2 + 1) * 4 + wc) * 4 + fq) * 16 + (bj * 2 + n) * 4)); if (fr == 0) up = halo; }
;                         if (m == 3) { f32x4 halo = zero4; if (blk < 3) halo = *(const PG8_LAS f32x4*)(xb + (((((blk + 1) * 2 + 0) * 4 + wc) * 4 + fq) * 16 + (bj * 2 + n) * 4)); if (fr == 15) dn = halo; }
;                         if (edge) { if (!upok) up = zero4; if (!dnok) dn = zero4; }
;                         res[bj] = bb[bj] + w0[bj] * up + w1[bj] * cur + w2[bj] * dn; }
;                     if (store_ok) {
;                         float o[4];
; #pragma unroll
;                         for (int j = 0; j < 4; ++j) { const float gg = res[1][j]; o[j] = gg * __builtin_amdgcn_rcpf(1.f + __expf(-gg)) * res[0][j]; }
;                         u32x2 w; w.x = cvt_pk_bf16(o[0], o[1]); w.y = cvt_pk_bf16(o[2], o[3]);
;                         *(u32x2*)(ACT + (size_t)(seqrow + t) * 2816 + ch0 + 4 * n) = w; } } }
	v_pk_fma_f32 v[202:203], v[122:123], v[174:175], v[134:135]
	v_pk_fma_f32 v[82:83], v[82:83], v[126:127], v[202:203]
	v_pk_fma_f32 v[82:83], v[130:131], v[194:195], v[82:83]
	ds_read_b64 v[174:175], v244 offset:512
	ds_read_b64 v[194:195], v243 offset:528
	s_waitcnt lgkmcnt(10)
	v_pk_fma_f32 v[202:203], v[122:123], v[176:177], v[134:135]
	v_pk_fma_f32 v[74:75], v[74:75], v[126:127], v[202:203]
	v_pk_fma_f32 v[74:75], v[130:131], v[196:197], v[74:75]
	ds_read_b64 v[176:177], v244 offset:768
	v_mad_u32_u24 v251, v39, 40, v201
	ds_read_b64 v[196:197], v251
	ds_write_b64 v243, v[70:71]
	ds_write_b64 v243, v[62:63] offset:256
	ds_write_b64 v243, v[54:55] offset:512
	ds_write_b64 v243, v[46:47] offset:768
	s_waitcnt lgkmcnt(10)
	v_pk_fma_f32 v[202:203], v[124:125], v[170:171], v[136:137]
	v_pk_fma_f32 v[100:101], v[100:101], v[128:129], v[202:203]
	v_pk_fma_f32 v[100:101], v[132:133], v[178:179], v[100:101]
	v_mad_u32_u24 v250, v38, 16, v198
	ds_read_b64 v[170:171], v250
	ds_read_b64 v[178:179], v243 offset:16
	s_waitcnt lgkmcnt(10)
	v_pk_fma_f32 v[202:203], v[124:125], v[172:173], v[136:137]
	v_pk_fma_f32 v[92:93], v[92:93], v[128:129], v[202:203]
	v_pk_fma_f32 v[92:93], v[132:133], v[180:181], v[92:93]
	ds_read_b64 v[172:173], v244 offset:256
	ds_read_b64 v[180:181], v243 offset:272
	s_waitcnt lgkmcnt(10)
	v_pk_fma_f32 v[202:203], v[124:125], v[174:175], v[136:137]
	v_pk_fma_f32 v[84:85], v[84:85], v[128:129], v[202:203]
	v_pk_fma_f32 v[84:85], v[132:133], v[194:195], v[84:85]
	ds_read_b64 v[174:175], v244 offset:512
	ds_read_b64 v[194:195], v243 offset:528
	s_waitcnt lgkmcnt(10)
	v_pk_fma_f32 v[202:203], v[124:125], v[176:177], v[136:137]
	v_pk_fma_f32 v[76:77], v[76:77], v[128:129], v[202:203]
	v_pk_fma_f32 v[76:77], v[132:133], v[196:197], v[76:77]
	ds_read_b64 v[176:177], v244 offset:768
	v_mad_u32_u24 v251, v39, 16, v200
	ds_read_b64 v[196:197], v251
	v_mul_f32_e32 v208, 0xbfb8aa3b, v98
	v_mul_f32_e32 v209, 0xbfb8aa3b, v99
	v_mul_f32_e32 v210, 0xbfb8aa3b, v100
	v_mul_f32_e32 v211, 0xbfb8aa3b, v101
	v_exp_f32_e32 v208, v208
	v_exp_f32_e32 v209, v209
	v_exp_f32_e32 v210, v210
	v_exp_f32_e32 v211, v211
	v_add_f32_e32 v208, 1.0, v208
	v_add_f32_e32 v209, 1.0, v209
	v_add_f32_e32 v210, 1.0, v210
	v_add_f32_e32 v211, 1.0, v211
	v_rcp_f32_e32 v208, v208
	v_rcp_f32_e32 v209, v209
	v_rcp_f32_e32 v210, v210
	v_rcp_f32_e32 v211, v211
	v_mul_f32_e32 v98, v98, v208
	v_mul_f32_e32 v99, v99, v209
	v_mul_f32_e32 v100, v100, v210
	v_mul_f32_e32 v101, v101, v211
	v_mul_f32_e32 v98, v102, v98
	v_mul_f32_e32 v99, v103, v99
	v_mul_f32_e32 v100, v104, v100
	v_mul_f32_e32 v101, v105, v101
	v_cvt_pk_bf16_f32 v212, v98, v99
	v_cvt_pk_bf16_f32 v213, v100, v101
	v_mad_u32_u24 v221, v234, s29, v247
	s_and_saveexec_b64 s[30:31], s[20:21]
	global_store_dwordx2 v221, v[212:213], s[10:11]
	s_mov_b64 exec, s[30:31]
	v_mul_f32_e32 v208, 0xbfb8aa3b, v90
	v_mul_f32_e32 v209, 0xbfb8aa3b, v91
	v_mul_f32_e32 v210, 0xbfb8aa3b, v92
	v_mul_f32_e32 v211, 0xbfb8aa3b, v93
	v_exp_f32_e32 v208, v208
	v_exp_f32_e32 v209, v209
	v_exp_f32_e32 v210, v210
	v_exp_f32_e32 v211, v211
	v_add_f32_e32 v208, 1.0, v208
	v_add_f32_e32 v209, 1.0, v209
	v_add_f32_e32 v210, 1.0, v210
	v_add_f32_e32 v211, 1.0, v211
	v_rcp_f32_e32 v208, v208
	v_rcp_f32_e32 v209, v209
	v_rcp_f32_e32 v210, v210
	v_rcp_f32_e32 v211, v211
	v_mul_f32_e32 v90, v90, v208
	v_mul_f32_e32 v91, v91, v209
	v_mul_f32_e32 v92, v92, v210
	v_mul_f32_e32 v93, v93, v211
	v_mul_f32_e32 v90, v94, v90
	v_mul_f32_e32 v91, v95, v91
	v_mul_f32_e32 v92, v96, v92
	v_mul_f32_e32 v93, v97, v93
	v_cvt_pk_bf16_f32 v218, v90, v91
	v_cvt_pk_bf16_f32 v219, v92, v93
	v_mad_u32_u24 v40, v235, s29, v247
	s_and_saveexec_b64 s[30:31], s[22:23]
	global_store_dwordx2 v40, v[218:219], s[10:11]
	s_mov_b64 exec, s[30:31]
	v_mul_f32_e32 v208, 0xbfb8aa3b, v82
	v_mul_f32_e32 v209, 0xbfb8aa3b, v83
	v_mul_f32_e32 v210, 0xbfb8aa3b, v84
	v_mul_f32_e32 v211, 0xbfb8aa3b, v85
	v_exp_f32_e32 v208, v208
	v_exp_f32_e32 v209, v209
	v_exp_f32_e32 v210, v210
	v_exp_f32_e32 v211, v211
	v_add_f32_e32 v208, 1.0, v208
	v_add_f32_e32 v209, 1.0, v209
	v_add_f32_e32 v210, 1.0, v210
	v_add_f32_e32 v211, 1.0, v211
	v_rcp_f32_e32 v208, v208
	v_rcp_f32_e32 v209, v209
	v_rcp_f32_e32 v210, v210
	v_rcp_f32_e32 v211, v211
	v_mul_f32_e32 v82, v82, v208
	v_mul_f32_e32 v83, v83, v209
	v_mul_f32_e32 v84, v84, v210
	v_mul_f32_e32 v85, v85, v211
	v_mul_f32_e32 v82, v86, v82
	v_mul_f32_e32 v83, v87, v83
	v_mul_f32_e32 v84, v88, v84
	v_mul_f32_e32 v85, v89, v85
	v_cvt_pk_bf16_f32 v212, v82, v83
	v_cvt_pk_bf16_f32 v213, v84, v85
	v_mad_u32_u24 v221, v236, s29, v247
	s_and_saveexec_b64 s[30:31], s[24:25]
	global_store_dwordx2 v221, v[212:213], s[10:11]
	s_mov_b64 exec, s[30:31]
	v_mul_f32_e32 v208, 0xbfb8aa3b, v74
	v_mul_f32_e32 v209, 0xbfb8aa3b, v75
	v_mul_f32_e32 v210, 0xbfb8aa3b, v76
	v_mul_f32_e32 v211, 0xbfb8aa3b, v77
	v_exp_f32_e32 v208, v208
	v_exp_f32_e32 v209, v209
	v_exp_f32_e32 v210, v210
	v_exp_f32_e32 v211, v211
	v_add_f32_e32 v208, 1.0, v208
	v_add_f32_e32 v209, 1.0, v209
	v_add_f32_e32 v210, 1.0, v210
	v_add_f32_e32 v211, 1.0, v211
	v_rcp_f32_e32 v208, v208
	v_rcp_f32_e32 v209, v209
	v_rcp_f32_e32 v210, v210
	v_rcp_f32_e32 v211, v211
	v_mul_f32_e32 v74, v74, v208
	v_mul_f32_e32 v75, v75, v209
	v_mul_f32_e32 v76, v76, v210
	v_mul_f32_e32 v77, v77, v211
	v_mul_f32_e32 v74, v78, v74
	v_mul_f32_e32 v75, v79, v75
	v_mul_f32_e32 v76, v80, v76
	v_mul_f32_e32 v77, v81, v77
	v_cvt_pk_bf16_f32 v218, v74, v75
	v_cvt_pk_bf16_f32 v219, v76, v77
	v_mad_u32_u24 v40, v237, s29, v247
	s_and_saveexec_b64 s[30:31], s[26:27]
	global_store_dwordx2 v40, v[218:219], s[10:11]
	s_mov_b64 exec, s[30:31]
	s_waitcnt vmcnt(4)
; #define PG8_LAS __attribute__((address_space(3)))
; __device__ __forceinline__ float dpp_ror1(float v) { return __builtin_bit_cast(float, __builtin_amdgcn_update_dpp(0, __builtin_bit_cast(int, v), 0x121, 0xf, 0xf, false)); }
; __device__ __forceinline__ float dpp_ror15(float v) { return __builtin_bit_cast(float, __builtin_amdgcn_update_dpp(0, __builtin_bit_cast(int, v), 0x12F, 0xf, 0xf, false)); }
;     __device__ __forceinline__ void operator()(const f32x4 (&acc)[2][2][4][2], const Unit& u, int wr, int wc, int fr, int fq) const {
;     ...
;                     for (int bj = 0; bj < 2; ++bj) { const f32x4 cur = acc[ai][bj][m][n];
;                         f32x4 su = cur, sd = cur;
;                         if (m > 0) { if (fr == 15) su = acc[ai][bj][m > 0 ? m - 1 : 0][n]; }
;                         if (m < 3) { if (fr == 0) sd = acc[ai][bj][m < 3 ? m + 1 : 3][n]; }
;                         f32x4 up, dn;
;                         up[0] = dpp_ror1(su[0]); up[1] = dpp_ror1(su[1]); up[2] = dpp_ror1(su[2]); up[3] = dpp_ror1(su[3]);
;                         dn[0] = dpp_ror15(sd[0]); dn[1] = dpp_ror15(sd[1]); dn[2] = dpp_ror15(sd[2]); dn[3] = dpp_ror15(sd[3]);
;                         if (m == 0) { f32x4 halo = zero4; if (blk > 0) halo = *(const PG8_LAS f32x4*)(xb + (((((blk - 1) * 2 + 1) * 4 + wc) * 4 + fq) * 16 + (bj * 2 + n) * 4)); if (fr == 0) up = halo; }
;                         if (m == 3) { f32x4 halo = zero4; if (blk < 3) halo = *(const PG8_LAS f32x4*)(xb + (((((blk + 1) * 2 + 0) * 4 + wc) * 4 + fq) * 16 + (bj * 2 + n) * 4)); if (fr == 15) dn = halo; }
;                         if (edge) { if (!upok) up = zero4; if (!dnok) dn = zero4; }
;                         res[bj] = bb[bj] + w0[bj] * up + w1[bj] * cur + w2[bj] * dn; }
	ds_write_b64 v243, v[72:73]
	ds_write_b64 v243, v[64:65] offset:256
	ds_write_b64 v243, v[56:57] offset:512
	ds_write_b64 v243, v[48:49] offset:768
	s_waitcnt lgkmcnt(10)
	v_pk_fma_f32 v[202:203], v[138:139], v[170:171], v[150:151]
	v_pk_fma_f32 v[70:71], v[70:71], v[142:143], v[202:203]
	v_pk_fma_f32 v[70:71], v[146:147], v[178:179], v[70:71]
	v_mad_u32_u24 v250, v38, 24, v198
	ds_read_b64 v[170:171], v250
	ds_read_b64 v[178:179], v243 offset:16
	s_waitcnt lgkmcnt(10)
	v_pk_fma_f32 v[202:203], v[138:139], v[172:173], v[150:151]
	v_pk_fma_f32 v[62:63], v[62:63], v[142:143], v[202:203]
	v_pk_fma_f32 v[62:63], v[146:147], v[180:181], v[62:63]
	ds_read_b64 v[172:173], v244 offset:256
	ds_read_b64 v[180:181], v243 offset:272
	s_waitcnt lgkmcnt(10)
	v_pk_fma_f32 v[202:203], v[138:139], v[174:175], v[150:151]
	v_pk_fma_f32 v[54:55], v[54:55], v[142:143], v[202:203]
	v_pk_fma_f32 v[54:55], v[146:147], v[194:195], v[54:55]
	ds_read_b64 v[174:175], v244 offset:512
	ds_read_b64 v[194:195], v243 offset:528
	s_waitcnt lgkmcnt(10)
	v_pk_fma_f32 v[202:203], v[138:139], v[176:177], v[150:151]
	v_pk_fma_f32 v[46:47], v[46:47], v[142:143], v[202:203]
	v_pk_fma_f32 v[46:47], v[146:147], v[196:197], v[46:47]
	ds_read_b64 v[176:177], v244 offset:768
	v_mad_u32_u24 v251, v39, 24, v200
	ds_read_b64 v[196:197], v251
	ds_write_b64 v243, v[66:67]
	ds_write_b64 v243, v[58:59] offset:256
	ds_write_b64 v243, v[50:51] offset:512
	ds_write_b64 v243, v[42:43] offset:768
	s_waitcnt lgkmcnt(10)
	v_pk_fma_f32 v[202:203], v[140:141], v[170:171], v[152:153]
	v_pk_fma_f32 v[72:73], v[72:73], v[144:145], v[202:203]
	v_pk_fma_f32 v[72:73], v[148:149], v[178:179], v[72:73]
	v_mad_u32_u24 v250, v38, 48, v198
	ds_read_b64 v[170:171], v250
	ds_read_b64 v[178:179], v243 offset:16
	s_waitcnt lgkmcnt(10)
	v_pk_fma_f32 v[202:203], v[140:141], v[172:173], v[152:153]
	v_pk_fma_f32 v[64:65], v[64:65], v[144:145], v[202:203]
	v_pk_fma_f32 v[64:65], v[148:149], v[180:181], v[64:65]
	ds_read_b64 v[172:173], v244 offset:256
	ds_read_b64 v[180:181], v243 offset:272
	s_waitcnt lgkmcnt(10)
	v_pk_fma_f32 v[202:203], v[140:141], v[174:175], v[152:153]
	v_pk_fma_f32 v[56:57], v[56:57], v[144:145], v[202:203]
	v_pk_fma_f32 v[56:57], v[148:149], v[194:195], v[56:57]
	ds_read_b64 v[174:175], v244 offset:512
	ds_read_b64 v[194:195], v243 offset:528
	s_waitcnt lgkmcnt(10)
	v_pk_fma_f32 v[202:203], v[140:141], v[176:177], v[152:153]
	v_pk_fma_f32 v[48:49], v[48:49], v[144:145], v[202:203]
	v_pk_fma_f32 v[48:49], v[148:149], v[196:197], v[48:49]
	ds_read_b64 v[176:177], v244 offset:768
	v_mad_u32_u24 v251, v39, 48, v200
	ds_read_b64 v[196:197], v251
	ds_write_b64 v243, v[68:69]
	ds_write_b64 v243, v[60:61] offset:256
	ds_write_b64 v243, v[52:53] offset:512
	ds_write_b64 v243, v[44:45] offset:768
	s_waitcnt lgkmcnt(10)
	v_pk_fma_f32 v[202:203], v[154:155], v[170:171], v[166:167]
	v_pk_fma_f32 v[66:67], v[66:67], v[158:159], v[202:203]
	v_pk_fma_f32 v[66:67], v[162:163], v[178:179], v[66:67]
	v_mad_u32_u24 v250, v38, 56, v198
	ds_read_b64 v[170:171], v250
	ds_read_b64 v[178:179], v243 offset:16
	s_waitcnt lgkmcnt(10)
	v_pk_fma_f32 v[202:203], v[154:155], v[172:173], v[166:167]
	v_pk_fma_f32 v[58:59], v[58:59], v[158:159], v[202:203]
	v_pk_fma_f32 v[58:59], v[162:163], v[180:181], v[58:59]
	ds_read_b64 v[172:173], v244 offset:256
	ds_read_b64 v[180:181], v243 offset:272
	s_waitcnt lgkmcnt(10)
	v_pk_fma_f32 v[202:203], v[154:155], v[174:175], v[166:167]
	v_pk_fma_f32 v[50:51], v[50:51], v[158:159], v[202:203]
	v_pk_fma_f32 v[50:51], v[162:163], v[194:195], v[50:51]
	ds_read_b64 v[174:175], v244 offset:512
	ds_read_b64 v[194:195], v243 offset:528
	s_waitcnt lgkmcnt(10)
	v_pk_fma_f32 v[202:203], v[154:155], v[176:177], v[166:167]
	v_pk_fma_f32 v[42:43], v[42:43], v[158:159], v[202:203]
	v_pk_fma_f32 v[42:43], v[162:163], v[196:197], v[42:43]
	ds_read_b64 v[176:177], v244 offset:768
	v_mad_u32_u24 v251, v39, 56, v200
	ds_read_b64 v[196:197], v251
	ds_write_b64 v243, v[30:31]
	ds_write_b64 v243, v[22:23] offset:256
	ds_write_b64 v243, v[14:15] offset:512
	ds_write_b64 v243, v[6:7] offset:768
	s_waitcnt lgkmcnt(10)
	v_pk_fma_f32 v[202:203], v[156:157], v[170:171], v[168:169]
	v_pk_fma_f32 v[68:69], v[68:69], v[160:161], v[202:203]
	v_pk_fma_f32 v[68:69], v[164:165], v[178:179], v[68:69]
	v_mad_u32_u24 v250, v38, 16, v199
	ds_read_b64 v[170:171], v250
	ds_read_b64 v[178:179], v243 offset:16
	s_waitcnt lgkmcnt(10)
	v_pk_fma_f32 v[202:203], v[156:157], v[172:173], v[168:169]
	v_pk_fma_f32 v[60:61], v[60:61], v[160:161], v[202:203]
	v_pk_fma_f32 v[60:61], v[164:165], v[180:181], v[60:61]
	ds_read_b64 v[172:173], v244 offset:256
	ds_read_b64 v[180:181], v243 offset:272
	s_waitcnt lgkmcnt(10)
	v_pk_fma_f32 v[202:203], v[156:157], v[174:175], v[168:169]
	v_pk_fma_f32 v[52:53], v[52:53], v[160:161], v[202:203]
	v_pk_fma_f32 v[52:53], v[164:165], v[194:195], v[52:53]
	ds_read_b64 v[174:175], v244 offset:512
	ds_read_b64 v[194:195], v243 offset:528
	s_waitcnt lgkmcnt(10)
; #define PG8_LAS __attribute__((address_space(3)))
; __device__ __forceinline__ unsigned cvt_pk_bf16(float lo, float hi) { unsigned r; asm volatile("v_cvt_pk_bf16_f32 %0, %1, %2" : "=v"(r) : "v"(lo), "v"(hi)); return r; }
; __device__ __forceinline__ float dpp_ror1(float v) { return __builtin_bit_cast(float, __builtin_amdgcn_update_dpp(0, __builtin_bit_cast(int, v), 0x121, 0xf, 0xf, false)); }
; __device__ __forceinline__ float dpp_ror15(float v) { return __builtin_bit_cast(float, __builtin_amdgcn_update_dpp(0, __builtin_bit_cast(int, v), 0x12F, 0xf, 0xf, false)); }
;     __device__ __forceinline__ void operator()(const f32x4 (&acc)[2][2][4][2], const Unit& u, int wr, int wc, int fr, int fq) const {
;     ...
;                     for (int bj = 0; bj < 2; ++bj) { const f32x4 cur = acc[ai][bj][m][n];
;                         f32x4 su = cur, sd = cur;
;                         if (m > 0) { if (fr == 15) su = acc[ai][bj][m > 0 ? m - 1 : 0][n]; }
;                         if (m < 3) { if (fr == 0) sd = acc[ai][bj][m < 3 ? m + 1 : 3][n]; }
;                         f32x4 up, dn;
;                         up[0] = dpp_ror1(su[0]); up[1] = dpp_ror1(su[1]); up[2] = dpp_ror1(su[2]); up[3] = dpp_ror1(su[3]);
;                         dn[0] = dpp_ror15(sd[0]); dn[1] = dpp_ror15(sd[1]); dn[2] = dpp_ror15(sd[2]); dn[3] = dpp_ror15(sd[3]);
;                         if (m == 0) { f32x4 halo = zero4; if (blk > 0) halo = *(const PG8_LAS f32x4*)(xb + (((((blk - 1) * 2 + 1) * 4 + wc) * 4 + fq) * 16 + (bj * 2 + n) * 4)); if (fr == 0) up = halo; }
;                         if (m == 3) { f32x4 halo = zero4; if (blk < 3) halo = *(const PG8_LAS f32x4*)(xb + (((((blk + 1) * 2 + 0) * 4 + wc) * 4 + fq) * 16 + (bj * 2 + n) * 4)); if (fr == 15) dn = halo; }
;                         if (edge) { if (!upok) up = zero4; if (!dnok) dn = zero4; }
;                         res[bj] = bb[bj] + w0[bj] * up + w1[bj] * cur + w2[bj] * dn; }
;                     if (store_ok) {
;                         float o[4];
; #pragma unroll
;                         for (int j = 0; j < 4; ++j) { const float gg = res[1][j]; o[j] = gg * __builtin_amdgcn_rcpf(1.f + __expf(-gg)) * res[0][j]; }
;                         u32x2 w; w.x = cvt_pk_bf16(o[0], o[1]); w.y = cvt_pk_bf16(o[2], o[3]);
;                         *(u32x2*)(ACT + (size_t)(seqrow + t) * 2816 + ch0 + 4 * n) = w; } } }
	v_pk_fma_f32 v[202:203], v[156:157], v[176:177], v[168:169]
	v_pk_fma_f32 v[44:45], v[44:45], v[160:161], v[202:203]
	v_pk_fma_f32 v[44:45], v[164:165], v[196:197], v[44:45]
	ds_read_b64 v[176:177], v244 offset:768
	v_mad_u32_u24 v251, v39, 16, v201
	ds_read_b64 v[196:197], v251
	v_mul_f32_e32 v208, 0xbfb8aa3b, v66
	v_mul_f32_e32 v209, 0xbfb8aa3b, v67
	v_mul_f32_e32 v210, 0xbfb8aa3b, v68
	v_mul_f32_e32 v211, 0xbfb8aa3b, v69
	v_exp_f32_e32 v208, v208
	v_exp_f32_e32 v209, v209
	v_exp_f32_e32 v210, v210
	v_exp_f32_e32 v211, v211
	v_add_f32_e32 v208, 1.0, v208
	v_add_f32_e32 v209, 1.0, v209
	v_add_f32_e32 v210, 1.0, v210
	v_add_f32_e32 v211, 1.0, v211
	v_rcp_f32_e32 v208, v208
	v_rcp_f32_e32 v209, v209
	v_rcp_f32_e32 v210, v210
	v_rcp_f32_e32 v211, v211
	v_mul_f32_e32 v66, v66, v208
	v_mul_f32_e32 v67, v67, v209
	v_mul_f32_e32 v68, v68, v210
	v_mul_f32_e32 v69, v69, v211
	v_mul_f32_e32 v66, v70, v66
	v_mul_f32_e32 v67, v71, v67
	v_mul_f32_e32 v68, v72, v68
	v_mul_f32_e32 v69, v73, v69
	v_cvt_pk_bf16_f32 v212, v66, v67
	v_cvt_pk_bf16_f32 v213, v68, v69
	v_mad_u32_u24 v221, v227, s29, v247
	s_and_saveexec_b64 s[30:31], s[12:13]
	global_store_dwordx2 v221, v[212:213], s[10:11] offset:8
	s_mov_b64 exec, s[30:31]
	v_mul_f32_e32 v208, 0xbfb8aa3b, v58
	v_mul_f32_e32 v209, 0xbfb8aa3b, v59
	v_mul_f32_e32 v210, 0xbfb8aa3b, v60
	v_mul_f32_e32 v211, 0xbfb8aa3b, v61
	v_exp_f32_e32 v208, v208
	v_exp_f32_e32 v209, v209
	v_exp_f32_e32 v210, v210
	v_exp_f32_e32 v211, v211
	v_add_f32_e32 v208, 1.0, v208
	v_add_f32_e32 v209, 1.0, v209
	v_add_f32_e32 v210, 1.0, v210
	v_add_f32_e32 v211, 1.0, v211
	v_rcp_f32_e32 v208, v208
	v_rcp_f32_e32 v209, v209
	v_rcp_f32_e32 v210, v210
	v_rcp_f32_e32 v211, v211
	v_mul_f32_e32 v58, v58, v208
	v_mul_f32_e32 v59, v59, v209
	v_mul_f32_e32 v60, v60, v210
	v_mul_f32_e32 v61, v61, v211
	v_mul_f32_e32 v58, v62, v58
	v_mul_f32_e32 v59, v63, v59
	v_mul_f32_e32 v60, v64, v60
	v_mul_f32_e32 v61, v65, v61
	v_cvt_pk_bf16_f32 v218, v58, v59
	v_cvt_pk_bf16_f32 v219, v60, v61
	v_mad_u32_u24 v40, v231, s29, v247
	s_and_saveexec_b64 s[30:31], s[14:15]
	global_store_dwordx2 v40, v[218:219], s[10:11] offset:8
	s_mov_b64 exec, s[30:31]
	v_mul_f32_e32 v208, 0xbfb8aa3b, v50
	v_mul_f32_e32 v209, 0xbfb8aa3b, v51
	v_mul_f32_e32 v210, 0xbfb8aa3b, v52
	v_mul_f32_e32 v211, 0xbfb8aa3b, v53
	v_exp_f32_e32 v208, v208
	v_exp_f32_e32 v209, v209
	v_exp_f32_e32 v210, v210
	v_exp_f32_e32 v211, v211
	v_add_f32_e32 v208, 1.0, v208
	v_add_f32_e32 v209, 1.0, v209
	v_add_f32_e32 v210, 1.0, v210
	v_add_f32_e32 v211, 1.0, v211
	v_rcp_f32_e32 v208, v208
	v_rcp_f32_e32 v209, v209
	v_rcp_f32_e32 v210, v210
	v_rcp_f32_e32 v211, v211
	v_mul_f32_e32 v50, v50, v208
	v_mul_f32_e32 v51, v51, v209
	v_mul_f32_e32 v52, v52, v210
	v_mul_f32_e32 v53, v53, v211
	v_mul_f32_e32 v50, v54, v50
	v_mul_f32_e32 v51, v55, v51
	v_mul_f32_e32 v52, v56, v52
	v_mul_f32_e32 v53, v57, v53
	v_cvt_pk_bf16_f32 v212, v50, v51
	v_cvt_pk_bf16_f32 v213, v52, v53
	v_mad_u32_u24 v221, v232, s29, v247
	s_and_saveexec_b64 s[30:31], s[16:17]
	global_store_dwordx2 v221, v[212:213], s[10:11] offset:8
	s_mov_b64 exec, s[30:31]
	v_mul_f32_e32 v208, 0xbfb8aa3b, v42
	v_mul_f32_e32 v209, 0xbfb8aa3b, v43
	v_mul_f32_e32 v210, 0xbfb8aa3b, v44
	v_mul_f32_e32 v211, 0xbfb8aa3b, v45
	v_exp_f32_e32 v208, v208
	v_exp_f32_e32 v209, v209
	v_exp_f32_e32 v210, v210
	v_exp_f32_e32 v211, v211
	v_add_f32_e32 v208, 1.0, v208
	v_add_f32_e32 v209, 1.0, v209
	v_add_f32_e32 v210, 1.0, v210
	v_add_f32_e32 v211, 1.0, v211
	v_rcp_f32_e32 v208, v208
	v_rcp_f32_e32 v209, v209
	v_rcp_f32_e32 v210, v210
	v_rcp_f32_e32 v211, v211
	v_mul_f32_e32 v42, v42, v208
	v_mul_f32_e32 v43, v43, v209
	v_mul_f32_e32 v44, v44, v210
	v_mul_f32_e32 v45, v45, v211
	v_mul_f32_e32 v42, v46, v42
	v_mul_f32_e32 v43, v47, v43
	v_mul_f32_e32 v44, v48, v44
	v_mul_f32_e32 v45, v49, v45
	v_cvt_pk_bf16_f32 v218, v42, v43
	v_cvt_pk_bf16_f32 v219, v44, v45
	v_mad_u32_u24 v40, v233, s29, v247
	s_and_saveexec_b64 s[30:31], s[18:19]
	global_store_dwordx2 v40, v[218:219], s[10:11] offset:8
	s_mov_b64 exec, s[30:31]
	ds_write_b64 v243, v[32:33]
	ds_write_b64 v243, v[24:25] offset:256
	ds_write_b64 v243, v[16:17] offset:512
	ds_write_b64 v243, v[8:9] offset:768
	s_waitcnt lgkmcnt(10)
	v_pk_fma_f32 v[202:203], v[138:139], v[170:171], v[150:151]
	v_pk_fma_f32 v[30:31], v[30:31], v[142:143], v[202:203]
	v_pk_fma_f32 v[30:31], v[146:147], v[178:179], v[30:31]
	v_mad_u32_u24 v250, v38, 24, v199
	ds_read_b64 v[170:171], v250
	ds_read_b64 v[178:179], v243 offset:16
	s_waitcnt lgkmcnt(10)
	v_pk_fma_f32 v[202:203], v[138:139], v[172:173], v[150:151]
	v_pk_fma_f32 v[22:23], v[22:23], v[142:143], v[202:203]
	v_pk_fma_f32 v[22:23], v[146:147], v[180:181], v[22:23]
	ds_read_b64 v[172:173], v244 offset:256
	ds_read_b64 v[180:181], v243 offset:272
	s_waitcnt lgkmcnt(10)
	v_pk_fma_f32 v[202:203], v[138:139], v[174:175], v[150:151]
	v_pk_fma_f32 v[14:15], v[14:15], v[142:143], v[202:203]
	v_pk_fma_f32 v[14:15], v[146:147], v[194:195], v[14:15]
	ds_read_b64 v[174:175], v244 offset:512
	ds_read_b64 v[194:195], v243 offset:528
	s_waitcnt lgkmcnt(10)
	v_pk_fma_f32 v[202:203], v[138:139], v[176:177], v[150:151]
	v_pk_fma_f32 v[6:7], v[6:7], v[142:143], v[202:203]
	v_pk_fma_f32 v[6:7], v[146:147], v[196:197], v[6:7]
	ds_read_b64 v[176:177], v244 offset:768
	v_mad_u32_u24 v251, v39, 24, v201
	ds_read_b64 v[196:197], v251
	ds_write_b64 v243, v[26:27]
	ds_write_b64 v243, v[18:19] offset:256
	ds_write_b64 v243, v[10:11] offset:512
	ds_write_b64 v243, v[2:3] offset:768
	s_waitcnt lgkmcnt(10)
; #define PG8_LAS __attribute__((address_space(3)))
; __device__ __forceinline__ unsigned cvt_pk_bf16(float lo, float hi) { unsigned r; asm volatile("v_cvt_pk_bf16_f32 %0, %1, %2" : "=v"(r) : "v"(lo), "v"(hi)); return r; }
; __device__ __forceinline__ float dpp_ror1(float v) { return __builtin_bit_cast(float, __builtin_amdgcn_update_dpp(0, __builtin_bit_cast(int, v), 0x121, 0xf, 0xf, false)); }
; __device__ __forceinline__ float dpp_ror15(float v) { return __builtin_bit_cast(float, __builtin_amdgcn_update_dpp(0, __builtin_bit_cast(int, v), 0x12F, 0xf, 0xf, false)); }
;     __device__ __forceinline__ void operator()(const f32x4 (&acc)[2][2][4][2], const Unit& u, int wr, int wc, int fr, int fq) const {
;     ...
;                     for (int bj = 0; bj < 2; ++bj) { const f32x4 cur = acc[ai][bj][m][n];
;                         f32x4 su = cur, sd = cur;
;                         if (m > 0) { if (fr == 15) su = acc[ai][bj][m > 0 ? m - 1 : 0][n]; }
;                         if (m < 3) { if (fr == 0) sd = acc[ai][bj][m < 3 ? m + 1 : 3][n]; }
;                         f32x4 up, dn;
;                         up[0] = dpp_ror1(su[0]); up[1] = dpp_ror1(su[1]); up[2] = dpp_ror1(su[2]); up[3] = dpp_ror1(su[3]);
;                         dn[0] = dpp_ror15(sd[0]); dn[1] = dpp_ror15(sd[1]); dn[2] = dpp_ror15(sd[2]); dn[3] = dpp_ror15(sd[3]);
;                         if (m == 0) { f32x4 halo = zero4; if (blk > 0) halo = *(const PG8_LAS f32x4*)(xb + (((((blk - 1) * 2 + 1) * 4 + wc) * 4 + fq) * 16 + (bj * 2 + n) * 4)); if (fr == 0) up = halo; }
;                         if (m == 3) { f32x4 halo = zero4; if (blk < 3) halo = *(const PG8_LAS f32x4*)(xb + (((((blk + 1) * 2 + 0) * 4 + wc) * 4 + fq) * 16 + (bj * 2 + n) * 4)); if (fr == 15) dn = halo; }
;                         if (edge) { if (!upok) up = zero4; if (!dnok) dn = zero4; }
;                         res[bj] = bb[bj] + w0[bj] * up + w1[bj] * cur + w2[bj] * dn; }
;                     if (store_ok) {
;                         float o[4];
; #pragma unroll
;                         for (int j = 0; j < 4; ++j) { const float gg = res[1][j]; o[j] = gg * __builtin_amdgcn_rcpf(1.f + __expf(-gg)) * res[0][j]; }
;                         u32x2 w; w.x = cvt_pk_bf16(o[0], o[1]); w.y = cvt_pk_bf16(o[2], o[3]);
;                         *(u32x2*)(ACT + (size_t)(seqrow + t) * 2816 + ch0 + 4 * n) = w; } } }
	v_pk_fma_f32 v[202:203], v[140:141], v[170:171], v[152:153]
	v_pk_fma_f32 v[32:33], v[32:33], v[144:145], v[202:203]
	v_pk_fma_f32 v[32:33], v[148:149], v[178:179], v[32:33]
	v_mad_u32_u24 v250, v38, 48, v199
	ds_read_b64 v[170:171], v250
	ds_read_b64 v[178:179], v243 offset:16
	s_waitcnt lgkmcnt(10)
	v_pk_fma_f32 v[202:203], v[140:141], v[172:173], v[152:153]
	v_pk_fma_f32 v[24:25], v[24:25], v[144:145], v[202:203]
	v_pk_fma_f32 v[24:25], v[148:149], v[180:181], v[24:25]
	ds_read_b64 v[172:173], v244 offset:256
	ds_read_b64 v[180:181], v243 offset:272
	s_waitcnt lgkmcnt(10)
	v_pk_fma_f32 v[202:203], v[140:141], v[174:175], v[152:153]
	v_pk_fma_f32 v[16:17], v[16:17], v[144:145], v[202:203]
	v_pk_fma_f32 v[16:17], v[148:149], v[194:195], v[16:17]
	ds_read_b64 v[174:175], v244 offset:512
	ds_read_b64 v[194:195], v243 offset:528
	s_waitcnt lgkmcnt(10)
	v_pk_fma_f32 v[202:203], v[140:141], v[176:177], v[152:153]
	v_pk_fma_f32 v[8:9], v[8:9], v[144:145], v[202:203]
	v_pk_fma_f32 v[8:9], v[148:149], v[196:197], v[8:9]
	ds_read_b64 v[176:177], v244 offset:768
	v_mad_u32_u24 v251, v39, 48, v201
	ds_read_b64 v[196:197], v251
	ds_write_b64 v243, v[28:29]
	ds_write_b64 v243, v[20:21] offset:256
	ds_write_b64 v243, v[12:13] offset:512
	ds_write_b64 v243, v[4:5] offset:768
	s_waitcnt lgkmcnt(10)
	v_pk_fma_f32 v[202:203], v[154:155], v[170:171], v[166:167]
	v_pk_fma_f32 v[26:27], v[26:27], v[158:159], v[202:203]
	v_pk_fma_f32 v[26:27], v[162:163], v[178:179], v[26:27]
	v_mad_u32_u24 v250, v38, 56, v199
	ds_read_b64 v[170:171], v250
	ds_read_b64 v[178:179], v243 offset:16
	s_waitcnt lgkmcnt(10)
	v_pk_fma_f32 v[202:203], v[154:155], v[172:173], v[166:167]
	v_pk_fma_f32 v[18:19], v[18:19], v[158:159], v[202:203]
	v_pk_fma_f32 v[18:19], v[162:163], v[180:181], v[18:19]
	ds_read_b64 v[172:173], v244 offset:256
	ds_read_b64 v[180:181], v243 offset:272
	s_waitcnt lgkmcnt(10)
	v_pk_fma_f32 v[202:203], v[154:155], v[174:175], v[166:167]
	v_pk_fma_f32 v[10:11], v[10:11], v[158:159], v[202:203]
	v_pk_fma_f32 v[10:11], v[162:163], v[194:195], v[10:11]
	ds_read_b64 v[174:175], v244 offset:512
	ds_read_b64 v[194:195], v243 offset:528
	s_waitcnt lgkmcnt(10)
	v_pk_fma_f32 v[202:203], v[154:155], v[176:177], v[166:167]
	v_pk_fma_f32 v[2:3], v[2:3], v[158:159], v[202:203]
	v_pk_fma_f32 v[2:3], v[162:163], v[196:197], v[2:3]
	ds_read_b64 v[176:177], v244 offset:768
	v_mad_u32_u24 v251, v39, 56, v201
	ds_read_b64 v[196:197], v251
	s_waitcnt lgkmcnt(6)
	v_pk_fma_f32 v[202:203], v[156:157], v[170:171], v[168:169]
	v_pk_fma_f32 v[28:29], v[28:29], v[160:161], v[202:203]
	v_pk_fma_f32 v[28:29], v[164:165], v[178:179], v[28:29]
	s_waitcnt lgkmcnt(4)
	v_pk_fma_f32 v[202:203], v[156:157], v[172:173], v[168:169]
	v_pk_fma_f32 v[20:21], v[20:21], v[160:161], v[202:203]
	v_pk_fma_f32 v[20:21], v[164:165], v[180:181], v[20:21]
	s_waitcnt lgkmcnt(2)
	v_pk_fma_f32 v[202:203], v[156:157], v[174:175], v[168:169]
	v_pk_fma_f32 v[12:13], v[12:13], v[160:161], v[202:203]
	v_pk_fma_f32 v[12:13], v[164:165], v[194:195], v[12:13]
	s_waitcnt lgkmcnt(0)
	v_pk_fma_f32 v[202:203], v[156:157], v[176:177], v[168:169]
	v_pk_fma_f32 v[4:5], v[4:5], v[160:161], v[202:203]
	v_pk_fma_f32 v[4:5], v[164:165], v[196:197], v[4:5]
	v_mul_f32_e32 v208, 0xbfb8aa3b, v26
	v_mul_f32_e32 v209, 0xbfb8aa3b, v27
	v_mul_f32_e32 v210, 0xbfb8aa3b, v28
	v_mul_f32_e32 v211, 0xbfb8aa3b, v29
	v_exp_f32_e32 v208, v208
	v_exp_f32_e32 v209, v209
	v_exp_f32_e32 v210, v210
	v_exp_f32_e32 v211, v211
	v_add_f32_e32 v208, 1.0, v208
	v_add_f32_e32 v209, 1.0, v209
	v_add_f32_e32 v210, 1.0, v210
	v_add_f32_e32 v211, 1.0, v211
	v_rcp_f32_e32 v208, v208
	v_rcp_f32_e32 v209, v209
	v_rcp_f32_e32 v210, v210
	v_rcp_f32_e32 v211, v211
	v_mul_f32_e32 v26, v26, v208
	v_mul_f32_e32 v27, v27, v209
	v_mul_f32_e32 v28, v28, v210
	v_mul_f32_e32 v29, v29, v211
	v_mul_f32_e32 v26, v30, v26
	v_mul_f32_e32 v27, v31, v27
	v_mul_f32_e32 v28, v32, v28
	v_mul_f32_e32 v29, v33, v29
	v_cvt_pk_bf16_f32 v212, v26, v27
	v_cvt_pk_bf16_f32 v213, v28, v29
	v_mad_u32_u24 v221, v234, s29, v247
	s_and_saveexec_b64 s[30:31], s[20:21]
	global_store_dwordx2 v221, v[212:213], s[10:11] offset:8
	s_mov_b64 exec, s[30:31]
	v_mul_f32_e32 v208, 0xbfb8aa3b, v18
	v_mul_f32_e32 v209, 0xbfb8aa3b, v19
	v_mul_f32_e32 v210, 0xbfb8aa3b, v20
	v_mul_f32_e32 v211, 0xbfb8aa3b, v21
	v_exp_f32_e32 v208, v208
	v_exp_f32_e32 v209, v209
	v_exp_f32_e32 v210, v210
	v_exp_f32_e32 v211, v211
	v_add_f32_e32 v208, 1.0, v208
	v_add_f32_e32 v209, 1.0, v209
	v_add_f32_e32 v210, 1.0, v210
	v_add_f32_e32 v211, 1.0, v211
	v_rcp_f32_e32 v208, v208
	v_rcp_f32_e32 v209, v209
	v_rcp_f32_e32 v210, v210
	v_rcp_f32_e32 v211, v211
	v_mul_f32_e32 v18, v18, v208
	v_mul_f32_e32 v19, v19, v209
	v_mul_f32_e32 v20, v20, v210
	v_mul_f32_e32 v21, v21, v211
	v_mul_f32_e32 v18, v22, v18
	v_mul_f32_e32 v19, v23, v19
	v_mul_f32_e32 v20, v24, v20
	v_mul_f32_e32 v21, v25, v21
	v_cvt_pk_bf16_f32 v218, v18, v19
	v_cvt_pk_bf16_f32 v219, v20, v21
	v_mad_u32_u24 v40, v235, s29, v247
	s_and_saveexec_b64 s[30:31], s[22:23]
	global_store_dwordx2 v40, v[218:219], s[10:11] offset:8
	s_mov_b64 exec, s[30:31]
	v_mul_f32_e32 v208, 0xbfb8aa3b, v10
	v_mul_f32_e32 v209, 0xbfb8aa3b, v11
	v_mul_f32_e32 v210, 0xbfb8aa3b, v12
	v_mul_f32_e32 v211, 0xbfb8aa3b, v13
	v_exp_f32_e32 v208, v208
	v_exp_f32_e32 v209, v209
	v_exp_f32_e32 v210, v210
	v_exp_f32_e32 v211, v211
	v_add_f32_e32 v208, 1.0, v208
	v_add_f32_e32 v209, 1.0, v209
	v_add_f32_e32 v210, 1.0, v210
	v_add_f32_e32 v211, 1.0, v211
	v_rcp_f32_e32 v208, v208
	v_rcp_f32_e32 v209, v209
	v_rcp_f32_e32 v210, v210
	v_rcp_f32_e32 v211, v211
	v_mul_f32_e32 v10, v10, v208
	v_mul_f32_e32 v11, v11, v209
	v_mul_f32_e32 v12, v12, v210
	v_mul_f32_e32 v13, v13, v211
	v_mul_f32_e32 v10, v14, v10
	v_mul_f32_e32 v11, v15, v11
	v_mul_f32_e32 v12, v16, v12
	v_mul_f32_e32 v13, v17, v13
	v_cvt_pk_bf16_f32 v212, v10, v11
	v_cvt_pk_bf16_f32 v213, v12, v13
	v_mad_u32_u24 v221, v236, s29, v247
	s_and_saveexec_b64 s[30:31], s[24:25]
	global_store_dwordx2 v221, v[212:213], s[10:11] offset:8
	s_mov_b64 exec, s[30:31]
	v_mul_f32_e32 v208, 0xbfb8aa3b, v2
	v_mul_f32_e32 v209, 0xbfb8aa3b, v3
	v_mul_f32_e32 v210, 0xbfb8aa3b, v4
	v_mul_f32_e32 v211, 0xbfb8aa3b, v5
	v_exp_f32_e32 v208, v208
	v_exp_f32_e32 v209, v209
	v_exp_f32_e32 v210, v210
	v_exp_f32_e32 v211, v211
	v_add_f32_e32 v208, 1.0, v208
	v_add_f32_e32 v209, 1.0, v209
	v_add_f32_e32 v210, 1.0, v210
	v_add_f32_e32 v211, 1.0, v211
	v_rcp_f32_e32 v208, v208
	v_rcp_f32_e32 v209, v209
	v_rcp_f32_e32 v210, v210
	v_rcp_f32_e32 v211, v211
	v_mul_f32_e32 v2, v2, v208
	v_mul_f32_e32 v3, v3, v209
	v_mul_f32_e32 v4, v4, v210
	v_mul_f32_e32 v5, v5, v211
	v_mul_f32_e32 v2, v6, v2
	v_mul_f32_e32 v3, v7, v3
	v_mul_f32_e32 v4, v8, v4
	v_mul_f32_e32 v5, v9, v5
	v_cvt_pk_bf16_f32 v218, v2, v3
	v_cvt_pk_bf16_f32 v219, v4, v5
	v_mad_u32_u24 v40, v237, s29, v247
	s_and_saveexec_b64 s[30:31], s[26:27]
	global_store_dwordx2 v40, v[218:219], s[10:11] offset:8
	s_mov_b64 exec, s[30:31]
	s_branch .Lec_done
; #define PG8_LAS __attribute__((address_space(3)))
; __device__ __forceinline__ float dpp_ror1(float v) { return __builtin_bit_cast(float, __builtin_amdgcn_update_dpp(0, __builtin_bit_cast(int, v), 0x121, 0xf, 0xf, false)); }
; __device__ __forceinline__ float dpp_ror15(float v) { return __builtin_bit_cast(float, __builtin_amdgcn_update_dpp(0, __builtin_bit_cast(int, v), 0x12F, 0xf, 0xf, false)); }
;     __device__ __forceinline__ void operator()(const f32x4 (&acc)[2][2][4][2], const Unit& u, int wr, int wc, int fr, int fq) const {
;     ...
;                 for (int m = 0; m < 4; ++m) { const int r = 128 * ai + 64 * wr + 16 * m + fr, t = tstart + r;
;                     const bool upok = t >= 1, dnok = (t + 1) < T, store_ok = (r >= vlo) && (r < vhi) && (t < T);
;                     f32x4 res[2];
; #pragma unroll
;                     for (int bj = 0; bj < 2; ++bj) { const f32x4 cur = acc[ai][bj][m][n];
;                         f32x4 su = cur, sd = cur;
;                         if (m > 0) { if (fr == 15) su = acc[ai][bj][m > 0 ? m - 1 : 0][n]; }
;                         if (m < 3) { if (fr == 0) sd = acc[ai][bj][m < 3 ? m + 1 : 3][n]; }
;                         f32x4 up, dn;
;                         up[0] = dpp_ror1(su[0]); up[1] = dpp_ror1(su[1]); up[2] = dpp_ror1(su[2]); up[3] = dpp_ror1(su[3]);
;                         dn[0] = dpp_ror15(sd[0]); dn[1] = dpp_ror15(sd[1]); dn[2] = dpp_ror15(sd[2]); dn[3] = dpp_ror15(sd[3]);
;                         if (m == 0) { f32x4 halo = zero4; if (blk > 0) halo = *(const PG8_LAS f32x4*)(xb + (((((blk - 1) * 2 + 1) * 4 + wc) * 4 + fq) * 16 + (bj * 2 + n) * 4)); if (fr == 0) up = halo; }
;                         if (m == 3) { f32x4 halo = zero4; if (blk < 3) halo = *(const PG8_LAS f32x4*)(xb + (((((blk + 1) * 2 + 0) * 4 + wc) * 4 + fq) * 16 + (bj * 2 + n) * 4)); if (fr == 15) dn = halo; }
;                         if (edge) { if (!upok) up = zero4; if (!dnok) dn = zero4; }
;                         res[bj] = bb[bj] + w0[bj] * up + w1[bj] * cur + w2[bj] * dn; }
.Lec_edge:
	v_cmp_le_i32_e64 s[12:13], s54, v227
	v_cmp_gt_i32_e32 vcc, s55, v227
	s_and_b64 s[12:13], s[12:13], vcc
	v_add_u32_e32 v220, s48, v227
	v_cmp_gt_i32_e32 vcc, s93, v220
	s_and_b64 s[12:13], s[12:13], vcc
	v_cmp_le_i32_e64 s[14:15], s54, v231
	v_cmp_gt_i32_e32 vcc, s55, v231
	s_and_b64 s[14:15], s[14:15], vcc
	v_add_u32_e32 v220, s48, v231
	v_cmp_gt_i32_e32 vcc, s93, v220
	s_and_b64 s[14:15], s[14:15], vcc
	v_cmp_le_i32_e64 s[16:17], s54, v232
	v_cmp_gt_i32_e32 vcc, s55, v232
	s_and_b64 s[16:17], s[16:17], vcc
	v_add_u32_e32 v220, s48, v232
	v_cmp_gt_i32_e32 vcc, s93, v220
	s_and_b64 s[16:17], s[16:17], vcc
	v_cmp_le_i32_e64 s[18:19], s54, v233
	v_cmp_gt_i32_e32 vcc, s55, v233
	s_and_b64 s[18:19], s[18:19], vcc
	v_add_u32_e32 v220, s48, v233
	v_cmp_gt_i32_e32 vcc, s93, v220
	s_and_b64 s[18:19], s[18:19], vcc
	v_cmp_le_i32_e64 s[20:21], s54, v234
	v_cmp_gt_i32_e32 vcc, s55, v234
	s_and_b64 s[20:21], s[20:21], vcc
	v_add_u32_e32 v220, s48, v234
	v_cmp_gt_i32_e32 vcc, s93, v220
	s_and_b64 s[20:21], s[20:21], vcc
	v_cmp_le_i32_e64 s[22:23], s54, v235
	v_cmp_gt_i32_e32 vcc, s55, v235
	s_and_b64 s[22:23], s[22:23], vcc
	v_add_u32_e32 v220, s48, v235
	v_cmp_gt_i32_e32 vcc, s93, v220
	s_and_b64 s[22:23], s[22:23], vcc
	v_cmp_le_i32_e64 s[24:25], s54, v236
	v_cmp_gt_i32_e32 vcc, s55, v236
	s_and_b64 s[24:25], s[24:25], vcc
	v_add_u32_e32 v220, s48, v236
	v_cmp_gt_i32_e32 vcc, s93, v220
	s_and_b64 s[24:25], s[24:25], vcc
	v_cmp_le_i32_e64 s[26:27], s54, v237
	v_cmp_gt_i32_e32 vcc, s55, v237
	s_and_b64 s[26:27], s[26:27], vcc
	v_add_u32_e32 v220, s48, v237
	v_cmp_gt_i32_e32 vcc, s93, v220
	s_and_b64 s[26:27], s[26:27], vcc
	ds_write_b64 v243, v[166:167]
	ds_write_b64 v243, v[158:159] offset:256
	ds_write_b64 v243, v[150:151] offset:512
	ds_write_b64 v243, v[142:143] offset:768
	v_mad_u32_u24 v250, v38, 0, v198
	ds_read_b64 v[170:171], v250
	ds_read_b64 v[178:179], v243 offset:16
	ds_read_b64 v[172:173], v244 offset:256
	ds_read_b64 v[180:181], v243 offset:272
	ds_read_b64 v[174:175], v244 offset:512
	ds_read_b64 v[194:195], v243 offset:528
	ds_read_b64 v[176:177], v244 offset:768
	v_mad_u32_u24 v251, v39, 0, v200
	ds_read_b64 v[196:197], v251
	s_waitcnt vmcnt(0)
	ds_write_b64 v243, v[168:169]
	ds_write_b64 v243, v[160:161] offset:256
	ds_write_b64 v243, v[152:153] offset:512
	ds_write_b64 v243, v[144:145] offset:768
	s_waitcnt lgkmcnt(10)
	v_add_u32_e32 v220, s48, v227
	v_cmp_lt_i32_e32 vcc, 0, v220
	s_nop 1
	v_cndmask_b32_e32 v170, 0, v170, vcc
	v_cndmask_b32_e32 v171, 0, v171, vcc
	v_cmp_gt_i32_e32 vcc, s28, v220
	s_nop 1
	v_cndmask_b32_e32 v178, 0, v178, vcc
	v_cndmask_b32_e32 v179, 0, v179, vcc
	v_pk_fma_f32 v[202:203], v[106:107], v[170:171], v[118:119]
	v_pk_fma_f32 v[166:167], v[166:167], v[110:111], v[202:203]
	v_pk_fma_f32 v[166:167], v[114:115], v[178:179], v[166:167]
	v_mad_u32_u24 v250, v38, 8, v198
	ds_read_b64 v[170:171], v250
	ds_read_b64 v[178:179], v243 offset:16
	s_waitcnt lgkmcnt(10)
	v_add_u32_e32 v220, s48, v231
	v_cmp_lt_i32_e32 vcc, 0, v220
	s_nop 1
	v_cndmask_b32_e32 v172, 0, v172, vcc
	v_cndmask_b32_e32 v173, 0, v173, vcc
	v_cmp_gt_i32_e32 vcc, s28, v220
	s_nop 1
	v_cndmask_b32_e32 v180, 0, v180, vcc
	v_cndmask_b32_e32 v181, 0, v181, vcc
	v_pk_fma_f32 v[202:203], v[106:107], v[172:173], v[118:119]
	v_pk_fma_f32 v[158:159], v[158:159], v[110:111], v[202:203]
	v_pk_fma_f32 v[158:159], v[114:115], v[180:181], v[158:159]
	ds_read_b64 v[172:173], v244 offset:256
	ds_read_b64 v[180:181], v243 offset:272
	s_waitcnt lgkmcnt(10)
	v_add_u32_e32 v220, s48, v232
	v_cmp_lt_i32_e32 vcc, 0, v220
	s_nop 1
	v_cndmask_b32_e32 v174, 0, v174, vcc
	v_cndmask_b32_e32 v175, 0, v175, vcc
	v_cmp_gt_i32_e32 vcc, s28, v220
	s_nop 1
	v_cndmask_b32_e32 v194, 0, v194, vcc
	v_cndmask_b32_e32 v195, 0, v195, vcc
	v_pk_fma_f32 v[202:203], v[106:107], v[174:175], v[118:119]
	v_pk_fma_f32 v[150:151], v[150:151], v[110:111], v[202:203]
	v_pk_fma_f32 v[150:151], v[114:115], v[194:195], v[150:151]
	ds_read_b64 v[174:175], v244 offset:512
	ds_read_b64 v[194:195], v243 offset:528
	s_waitcnt lgkmcnt(10)
	v_add_u32_e32 v220, s48, v233
	v_cmp_lt_i32_e32 vcc, 0, v220
	s_nop 1
	v_cndmask_b32_e32 v176, 0, v176, vcc
	v_cndmask_b32_e32 v177, 0, v177, vcc
	v_cmp_gt_i32_e32 vcc, s28, v220
	s_nop 1
	v_cndmask_b32_e32 v196, 0, v196, vcc
	v_cndmask_b32_e32 v197, 0, v197, vcc
	v_pk_fma_f32 v[202:203], v[106:107], v[176:177], v[118:119]
	v_pk_fma_f32 v[142:143], v[142:143], v[110:111], v[202:203]
	v_pk_fma_f32 v[142:143], v[114:115], v[196:197], v[142:143]
	ds_read_b64 v[176:177], v244 offset:768
	v_mad_u32_u24 v251, v39, 8, v200
	ds_read_b64 v[196:197], v251
	ds_write_b64 v243, v[162:163]
	ds_write_b64 v243, v[154:155] offset:256
	ds_write_b64 v243, v[146:147] offset:512
	ds_write_b64 v243, v[138:139] offset:768
	s_waitcnt lgkmcnt(10)
	v_add_u32_e32 v220, s48, v227
	v_cmp_lt_i32_e32 vcc, 0, v220
	s_nop 1
	v_cndmask_b32_e32 v170, 0, v170, vcc
	v_cndmask_b32_e32 v171, 0, v171, vcc
	v_cmp_gt_i32_e32 vcc, s28, v220
	s_nop 1
	v_cndmask_b32_e32 v178, 0, v178, vcc
	v_cndmask_b32_e32 v179, 0, v179, vcc
	v_pk_fma_f32 v[202:203], v[108:109], v[170:171], v[120:121]
	v_pk_fma_f32 v[168:169], v[168:169], v[112:113], v[202:203]
	v_pk_fma_f32 v[168:169], v[116:117], v[178:179], v[168:169]
	v_mad_u32_u24 v250, v38, 32, v198
	ds_read_b64 v[170:171], v250
	ds_read_b64 v[178:179], v243 offset:16
	s_waitcnt lgkmcnt(10)
; #define PG8_LAS __attribute__((address_space(3)))
; __device__ __forceinline__ float dpp_ror1(float v) { return __builtin_bit_cast(float, __builtin_amdgcn_update_dpp(0, __builtin_bit_cast(int, v), 0x121, 0xf, 0xf, false)); }
; __device__ __forceinline__ float dpp_ror15(float v) { return __builtin_bit_cast(float, __builtin_amdgcn_update_dpp(0, __builtin_bit_cast(int, v), 0x12F, 0xf, 0xf, false)); }
;     __device__ __forceinline__ void operator()(const f32x4 (&acc)[2][2][4][2], const Unit& u, int wr, int wc, int fr, int fq) const {
;     ...
;                     for (int bj = 0; bj < 2; ++bj) { const f32x4 cur = acc[ai][bj][m][n];
;                         f32x4 su = cur, sd = cur;
;                         if (m > 0) { if (fr == 15) su = acc[ai][bj][m > 0 ? m - 1 : 0][n]; }
;                         if (m < 3) { if (fr == 0) sd = acc[ai][bj][m < 3 ? m + 1 : 3][n]; }
;                         f32x4 up, dn;
;                         up[0] = dpp_ror1(su[0]); up[1] = dpp_ror1(su[1]); up[2] = dpp_ror1(su[2]); up[3] = dpp_ror1(su[3]);
;                         dn[0] = dpp_ror15(sd[0]); dn[1] = dpp_ror15(sd[1]); dn[2] = dpp_ror15(sd[2]); dn[3] = dpp_ror15(sd[3]);
;                         if (m == 0) { f32x4 halo = zero4; if (blk > 0) halo = *(const PG8_LAS f32x4*)(xb + (((((blk - 1) * 2 + 1) * 4 + wc) * 4 + fq) * 16 + (bj * 2 + n) * 4)); if (fr == 0) up = halo; }
;                         if (m == 3) { f32x4 halo = zero4; if (blk < 3) halo = *(const PG8_LAS f32x4*)(xb + (((((blk + 1) * 2 + 0) * 4 + wc) * 4 + fq) * 16 + (bj * 2 + n) * 4)); if (fr == 15) dn = halo; }
;                         if (edge) { if (!upok) up = zero4; if (!dnok) dn = zero4; }
;                         res[bj] = bb[bj] + w0[bj] * up + w1[bj] * cur + w2[bj] * dn; }
	v_add_u32_e32 v220, s48, v231
	v_cmp_lt_i32_e32 vcc, 0, v220
	s_nop 1
	v_cndmask_b32_e32 v172, 0, v172, vcc
	v_cndmask_b32_e32 v173, 0, v173, vcc
	v_cmp_gt_i32_e32 vcc, s28, v220
	s_nop 1
	v_cndmask_b32_e32 v180, 0, v180, vcc
	v_cndmask_b32_e32 v181, 0, v181, vcc
	v_pk_fma_f32 v[202:203], v[108:109], v[172:173], v[120:121]
	v_pk_fma_f32 v[160:161], v[160:161], v[112:113], v[202:203]
	v_pk_fma_f32 v[160:161], v[116:117], v[180:181], v[160:161]
	ds_read_b64 v[172:173], v244 offset:256
	ds_read_b64 v[180:181], v243 offset:272
	s_waitcnt lgkmcnt(10)
	v_add_u32_e32 v220, s48, v232
	v_cmp_lt_i32_e32 vcc, 0, v220
	s_nop 1
	v_cndmask_b32_e32 v174, 0, v174, vcc
	v_cndmask_b32_e32 v175, 0, v175, vcc
	v_cmp_gt_i32_e32 vcc, s28, v220
	s_nop 1
	v_cndmask_b32_e32 v194, 0, v194, vcc
	v_cndmask_b32_e32 v195, 0, v195, vcc
	v_pk_fma_f32 v[202:203], v[108:109], v[174:175], v[120:121]
	v_pk_fma_f32 v[152:153], v[152:153], v[112:113], v[202:203]
	v_pk_fma_f32 v[152:153], v[116:117], v[194:195], v[152:153]
	ds_read_b64 v[174:175], v244 offset:512
	ds_read_b64 v[194:195], v243 offset:528
	s_waitcnt lgkmcnt(10)
	v_add_u32_e32 v220, s48, v233
	v_cmp_lt_i32_e32 vcc, 0, v220
	s_nop 1
	v_cndmask_b32_e32 v176, 0, v176, vcc
	v_cndmask_b32_e32 v177, 0, v177, vcc
	v_cmp_gt_i32_e32 vcc, s28, v220
	s_nop 1
	v_cndmask_b32_e32 v196, 0, v196, vcc
	v_cndmask_b32_e32 v197, 0, v197, vcc
	v_pk_fma_f32 v[202:203], v[108:109], v[176:177], v[120:121]
	v_pk_fma_f32 v[144:145], v[144:145], v[112:113], v[202:203]
	v_pk_fma_f32 v[144:145], v[116:117], v[196:197], v[144:145]
	ds_read_b64 v[176:177], v244 offset:768
	v_mad_u32_u24 v251, v39, 32, v200
	ds_read_b64 v[196:197], v251
	ds_write_b64 v243, v[164:165]
	ds_write_b64 v243, v[156:157] offset:256
	ds_write_b64 v243, v[148:149] offset:512
	ds_write_b64 v243, v[140:141] offset:768
	s_waitcnt lgkmcnt(10)
	v_add_u32_e32 v220, s48, v227
	v_cmp_lt_i32_e32 vcc, 0, v220
	s_nop 1
	v_cndmask_b32_e32 v170, 0, v170, vcc
	v_cndmask_b32_e32 v171, 0, v171, vcc
	v_cmp_gt_i32_e32 vcc, s28, v220
	s_nop 1
	v_cndmask_b32_e32 v178, 0, v178, vcc
	v_cndmask_b32_e32 v179, 0, v179, vcc
	v_pk_fma_f32 v[202:203], v[122:123], v[170:171], v[134:135]
	v_pk_fma_f32 v[162:163], v[162:163], v[126:127], v[202:203]
	v_pk_fma_f32 v[162:163], v[130:131], v[178:179], v[162:163]
	v_mad_u32_u24 v250, v38, 40, v198
	ds_read_b64 v[170:171], v250
	ds_read_b64 v[178:179], v243 offset:16
	s_waitcnt lgkmcnt(10)
	v_add_u32_e32 v220, s48, v231
	v_cmp_lt_i32_e32 vcc, 0, v220
	s_nop 1
	v_cndmask_b32_e32 v172, 0, v172, vcc
	v_cndmask_b32_e32 v173, 0, v173, vcc
	v_cmp_gt_i32_e32 vcc, s28, v220
	s_nop 1
	v_cndmask_b32_e32 v180, 0, v180, vcc
	v_cndmask_b32_e32 v181, 0, v181, vcc
	v_pk_fma_f32 v[202:203], v[122:123], v[172:173], v[134:135]
	v_pk_fma_f32 v[154:155], v[154:155], v[126:127], v[202:203]
	v_pk_fma_f32 v[154:155], v[130:131], v[180:181], v[154:155]
	ds_read_b64 v[172:173], v244 offset:256
	ds_read_b64 v[180:181], v243 offset:272
	s_waitcnt lgkmcnt(10)
	v_add_u32_e32 v220, s48, v232
	v_cmp_lt_i32_e32 vcc, 0, v220
	s_nop 1
	v_cndmask_b32_e32 v174, 0, v174, vcc
	v_cndmask_b32_e32 v175, 0, v175, vcc
	v_cmp_gt_i32_e32 vcc, s28, v220
	s_nop 1
	v_cndmask_b32_e32 v194, 0, v194, vcc
	v_cndmask_b32_e32 v195, 0, v195, vcc
	v_pk_fma_f32 v[202:203], v[122:123], v[174:175], v[134:135]
	v_pk_fma_f32 v[146:147], v[146:147], v[126:127], v[202:203]
	v_pk_fma_f32 v[146:147], v[130:131], v[194:195], v[146:147]
	ds_read_b64 v[174:175], v244 offset:512
	ds_read_b64 v[194:195], v243 offset:528
	s_waitcnt lgkmcnt(10)
	v_add_u32_e32 v220, s48, v233
	v_cmp_lt_i32_e32 vcc, 0, v220
	s_nop 1
	v_cndmask_b32_e32 v176, 0, v176, vcc
	v_cndmask_b32_e32 v177, 0, v177, vcc
	v_cmp_gt_i32_e32 vcc, s28, v220
	s_nop 1
	v_cndmask_b32_e32 v196, 0, v196, vcc
	v_cndmask_b32_e32 v197, 0, v197, vcc
	v_pk_fma_f32 v[202:203], v[122:123], v[176:177], v[134:135]
	v_pk_fma_f32 v[138:139], v[138:139], v[126:127], v[202:203]
	v_pk_fma_f32 v[138:139], v[130:131], v[196:197], v[138:139]
	ds_read_b64 v[176:177], v244 offset:768
	v_mad_u32_u24 v251, v39, 40, v200
	ds_read_b64 v[196:197], v251
	ds_write_b64 v243, v[102:103]
	ds_write_b64 v243, v[94:95] offset:256
	ds_write_b64 v243, v[86:87] offset:512
	ds_write_b64 v243, v[78:79] offset:768
	s_waitcnt lgkmcnt(10)
	v_add_u32_e32 v220, s48, v227
	v_cmp_lt_i32_e32 vcc, 0, v220
	s_nop 1
	v_cndmask_b32_e32 v170, 0, v170, vcc
	v_cndmask_b32_e32 v171, 0, v171, vcc
	v_cmp_gt_i32_e32 vcc, s28, v220
	s_nop 1
	v_cndmask_b32_e32 v178, 0, v178, vcc
	v_cndmask_b32_e32 v179, 0, v179, vcc
	v_pk_fma_f32 v[202:203], v[124:125], v[170:171], v[136:137]
	v_pk_fma_f32 v[164:165], v[164:165], v[128:129], v[202:203]
	v_pk_fma_f32 v[164:165], v[132:133], v[178:179], v[164:165]
	v_mad_u32_u24 v250, v38, 0, v199
	ds_read_b64 v[170:171], v250
	ds_read_b64 v[178:179], v243 offset:16
	s_waitcnt lgkmcnt(10)
	v_add_u32_e32 v220, s48, v231
	v_cmp_lt_i32_e32 vcc, 0, v220
	s_nop 1
	v_cndmask_b32_e32 v172, 0, v172, vcc
	v_cndmask_b32_e32 v173, 0, v173, vcc
	v_cmp_gt_i32_e32 vcc, s28, v220
	s_nop 1
	v_cndmask_b32_e32 v180, 0, v180, vcc
	v_cndmask_b32_e32 v181, 0, v181, vcc
	v_pk_fma_f32 v[202:203], v[124:125], v[172:173], v[136:137]
	v_pk_fma_f32 v[156:157], v[156:157], v[128:129], v[202:203]
	v_pk_fma_f32 v[156:157], v[132:133], v[180:181], v[156:157]
	ds_read_b64 v[172:173], v244 offset:256
	ds_read_b64 v[180:181], v243 offset:272
	s_waitcnt lgkmcnt(10)
; #define PG8_LAS __attribute__((address_space(3)))
; __device__ __forceinline__ unsigned cvt_pk_bf16(float lo, float hi) { unsigned r; asm volatile("v_cvt_pk_bf16_f32 %0, %1, %2" : "=v"(r) : "v"(lo), "v"(hi)); return r; }
; __device__ __forceinline__ float dpp_ror1(float v) { return __builtin_bit_cast(float, __builtin_amdgcn_update_dpp(0, __builtin_bit_cast(int, v), 0x121, 0xf, 0xf, false)); }
; __device__ __forceinline__ float dpp_ror15(float v) { return __builtin_bit_cast(float, __builtin_amdgcn_update_dpp(0, __builtin_bit_cast(int, v), 0x12F, 0xf, 0xf, false)); }
;     __device__ __forceinline__ void operator()(const f32x4 (&acc)[2][2][4][2], const Unit& u, int wr, int wc, int fr, int fq) const {
;     ...
;                     for (int bj = 0; bj < 2; ++bj) { const f32x4 cur = acc[ai][bj][m][n];
;                         f32x4 su = cur, sd = cur;
;                         if (m > 0) { if (fr == 15) su = acc[ai][bj][m > 0 ? m - 1 : 0][n]; }
;                         if (m < 3) { if (fr == 0) sd = acc[ai][bj][m < 3 ? m + 1 : 3][n]; }
;                         f32x4 up, dn;
;                         up[0] = dpp_ror1(su[0]); up[1] = dpp_ror1(su[1]); up[2] = dpp_ror1(su[2]); up[3] = dpp_ror1(su[3]);
;                         dn[0] = dpp_ror15(sd[0]); dn[1] = dpp_ror15(sd[1]); dn[2] = dpp_ror15(sd[2]); dn[3] = dpp_ror15(sd[3]);
;                         if (m == 0) { f32x4 halo = zero4; if (blk > 0) halo = *(const PG8_LAS f32x4*)(xb + (((((blk - 1) * 2 + 1) * 4 + wc) * 4 + fq) * 16 + (bj * 2 + n) * 4)); if (fr == 0) up = halo; }
;                         if (m == 3) { f32x4 halo = zero4; if (blk < 3) halo = *(const PG8_LAS f32x4*)(xb + (((((blk + 1) * 2 + 0) * 4 + wc) * 4 + fq) * 16 + (bj * 2 + n) * 4)); if (fr == 15) dn = halo; }
;                         if (edge) { if (!upok) up = zero4; if (!dnok) dn = zero4; }
;                         res[bj] = bb[bj] + w0[bj] * up + w1[bj] * cur + w2[bj] * dn; }
;                     if (store_ok) {
;                         float o[4];
; #pragma unroll
;                         for (int j = 0; j < 4; ++j) { const float gg = res[1][j]; o[j] = gg * __builtin_amdgcn_rcpf(1.f + __expf(-gg)) * res[0][j]; }
;                         u32x2 w; w.x = cvt_pk_bf16(o[0], o[1]); w.y = cvt_pk_bf16(o[2], o[3]);
;                         *(u32x2*)(ACT + (size_t)(seqrow + t) * 2816 + ch0 + 4 * n) = w; } } }
	v_add_u32_e32 v220, s48, v232
	v_cmp_lt_i32_e32 vcc, 0, v220
	s_nop 1
	v_cndmask_b32_e32 v174, 0, v174, vcc
	v_cndmask_b32_e32 v175, 0, v175, vcc
	v_cmp_gt_i32_e32 vcc, s28, v220
	s_nop 1
	v_cndmask_b32_e32 v194, 0, v194, vcc
	v_cndmask_b32_e32 v195, 0, v195, vcc
	v_pk_fma_f32 v[202:203], v[124:125], v[174:175], v[136:137]
	v_pk_fma_f32 v[148:149], v[148:149], v[128:129], v[202:203]
	v_pk_fma_f32 v[148:149], v[132:133], v[194:195], v[148:149]
	ds_read_b64 v[174:175], v244 offset:512
	ds_read_b64 v[194:195], v243 offset:528
	s_waitcnt lgkmcnt(10)
	v_add_u32_e32 v220, s48, v233
	v_cmp_lt_i32_e32 vcc, 0, v220
	s_nop 1
	v_cndmask_b32_e32 v176, 0, v176, vcc
	v_cndmask_b32_e32 v177, 0, v177, vcc
	v_cmp_gt_i32_e32 vcc, s28, v220
	s_nop 1
	v_cndmask_b32_e32 v196, 0, v196, vcc
	v_cndmask_b32_e32 v197, 0, v197, vcc
	v_pk_fma_f32 v[202:203], v[124:125], v[176:177], v[136:137]
	v_pk_fma_f32 v[140:141], v[140:141], v[128:129], v[202:203]
	v_pk_fma_f32 v[140:141], v[132:133], v[196:197], v[140:141]
	ds_read_b64 v[176:177], v244 offset:768
	v_mad_u32_u24 v251, v39, 0, v201
	ds_read_b64 v[196:197], v251
	v_mul_f32_e32 v208, 0xbfb8aa3b, v162
	v_mul_f32_e32 v209, 0xbfb8aa3b, v163
	v_mul_f32_e32 v210, 0xbfb8aa3b, v164
	v_mul_f32_e32 v211, 0xbfb8aa3b, v165
	v_exp_f32_e32 v208, v208
	v_exp_f32_e32 v209, v209
	v_exp_f32_e32 v210, v210
	v_exp_f32_e32 v211, v211
	v_add_f32_e32 v208, 1.0, v208
	v_add_f32_e32 v209, 1.0, v209
	v_add_f32_e32 v210, 1.0, v210
	v_add_f32_e32 v211, 1.0, v211
	v_rcp_f32_e32 v208, v208
	v_rcp_f32_e32 v209, v209
	v_rcp_f32_e32 v210, v210
	v_rcp_f32_e32 v211, v211
	v_mul_f32_e32 v162, v162, v208
	v_mul_f32_e32 v163, v163, v209
	v_mul_f32_e32 v164, v164, v210
	v_mul_f32_e32 v165, v165, v211
	v_mul_f32_e32 v162, v166, v162
	v_mul_f32_e32 v163, v167, v163
	v_mul_f32_e32 v164, v168, v164
	v_mul_f32_e32 v165, v169, v165
	v_cvt_pk_bf16_f32 v212, v162, v163
	v_cvt_pk_bf16_f32 v213, v164, v165
	v_mad_u32_u24 v221, v227, s29, v247
	s_and_saveexec_b64 s[30:31], s[12:13]
	global_store_dwordx2 v221, v[212:213], s[10:11]
	s_mov_b64 exec, s[30:31]
	v_mul_f32_e32 v208, 0xbfb8aa3b, v154
	v_mul_f32_e32 v209, 0xbfb8aa3b, v155
	v_mul_f32_e32 v210, 0xbfb8aa3b, v156
	v_mul_f32_e32 v211, 0xbfb8aa3b, v157
	v_exp_f32_e32 v208, v208
	v_exp_f32_e32 v209, v209
	v_exp_f32_e32 v210, v210
	v_exp_f32_e32 v211, v211
	v_add_f32_e32 v208, 1.0, v208
	v_add_f32_e32 v209, 1.0, v209
	v_add_f32_e32 v210, 1.0, v210
	v_add_f32_e32 v211, 1.0, v211
	v_rcp_f32_e32 v208, v208
	v_rcp_f32_e32 v209, v209
	v_rcp_f32_e32 v210, v210
	v_rcp_f32_e32 v211, v211
	v_mul_f32_e32 v154, v154, v208
	v_mul_f32_e32 v155, v155, v209
	v_mul_f32_e32 v156, v156, v210
	v_mul_f32_e32 v157, v157, v211
	v_mul_f32_e32 v154, v158, v154
	v_mul_f32_e32 v155, v159, v155
	v_mul_f32_e32 v156, v160, v156
	v_mul_f32_e32 v157, v161, v157
	v_cvt_pk_bf16_f32 v218, v154, v155
	v_cvt_pk_bf16_f32 v219, v156, v157
	v_mad_u32_u24 v40, v231, s29, v247
	s_and_saveexec_b64 s[30:31], s[14:15]
	global_store_dwordx2 v40, v[218:219], s[10:11]
	s_mov_b64 exec, s[30:31]
	v_mul_f32_e32 v208, 0xbfb8aa3b, v146
	v_mul_f32_e32 v209, 0xbfb8aa3b, v147
	v_mul_f32_e32 v210, 0xbfb8aa3b, v148
	v_mul_f32_e32 v211, 0xbfb8aa3b, v149
	v_exp_f32_e32 v208, v208
	v_exp_f32_e32 v209, v209
	v_exp_f32_e32 v210, v210
	v_exp_f32_e32 v211, v211
	v_add_f32_e32 v208, 1.0, v208
	v_add_f32_e32 v209, 1.0, v209
	v_add_f32_e32 v210, 1.0, v210
	v_add_f32_e32 v211, 1.0, v211
	v_rcp_f32_e32 v208, v208
	v_rcp_f32_e32 v209, v209
	v_rcp_f32_e32 v210, v210
	v_rcp_f32_e32 v211, v211
	v_mul_f32_e32 v146, v146, v208
	v_mul_f32_e32 v147, v147, v209
	v_mul_f32_e32 v148, v148, v210
	v_mul_f32_e32 v149, v149, v211
	v_mul_f32_e32 v146, v150, v146
	v_mul_f32_e32 v147, v151, v147
	v_mul_f32_e32 v148, v152, v148
	v_mul_f32_e32 v149, v153, v149
	v_cvt_pk_bf16_f32 v212, v146, v147
	v_cvt_pk_bf16_f32 v213, v148, v149
	v_mad_u32_u24 v221, v232, s29, v247
	s_and_saveexec_b64 s[30:31], s[16:17]
	global_store_dwordx2 v221, v[212:213], s[10:11]
	s_mov_b64 exec, s[30:31]
	v_mul_f32_e32 v208, 0xbfb8aa3b, v138
	v_mul_f32_e32 v209, 0xbfb8aa3b, v139
	v_mul_f32_e32 v210, 0xbfb8aa3b, v140
	v_mul_f32_e32 v211, 0xbfb8aa3b, v141
	v_exp_f32_e32 v208, v208
	v_exp_f32_e32 v209, v209
	v_exp_f32_e32 v210, v210
	v_exp_f32_e32 v211, v211
	v_add_f32_e32 v208, 1.0, v208
	v_add_f32_e32 v209, 1.0, v209
	v_add_f32_e32 v210, 1.0, v210
	v_add_f32_e32 v211, 1.0, v211
	v_rcp_f32_e32 v208, v208
	v_rcp_f32_e32 v209, v209
	v_rcp_f32_e32 v210, v210
	v_rcp_f32_e32 v211, v211
	v_mul_f32_e32 v138, v138, v208
	v_mul_f32_e32 v139, v139, v209
	v_mul_f32_e32 v140, v140, v210
	v_mul_f32_e32 v141, v141, v211
	v_mul_f32_e32 v138, v142, v138
	v_mul_f32_e32 v139, v143, v139
	v_mul_f32_e32 v140, v144, v140
	v_mul_f32_e32 v141, v145, v141
	v_cvt_pk_bf16_f32 v218, v138, v139
	v_cvt_pk_bf16_f32 v219, v140, v141
	v_mad_u32_u24 v40, v233, s29, v247
	s_and_saveexec_b64 s[30:31], s[18:19]
	global_store_dwordx2 v40, v[218:219], s[10:11]
	s_mov_b64 exec, s[30:31]
	global_load_dwordx4 v[138:141], v248, s[62:63] offset:16
	global_load_dwordx4 v[142:145], v248, s[66:67] offset:16
	global_load_dwordx4 v[146:149], v248, s[68:69] offset:16
	global_load_dwordx4 v[150:153], v248, s[64:65] offset:16
	global_load_dwordx4 v[154:157], v249, s[62:63] offset:16
	global_load_dwordx4 v[158:161], v249, s[66:67] offset:16
	global_load_dwordx4 v[162:165], v249, s[68:69] offset:16
	global_load_dwordx4 v[166:169], v249, s[64:65] offset:16
	ds_write_b64 v243, v[104:105]
	ds_write_b64 v243, v[96:97] offset:256
	ds_write_b64 v243, v[88:89] offset:512
	ds_write_b64 v243, v[80:81] offset:768
	s_waitcnt lgkmcnt(10)
; #define PG8_LAS __attribute__((address_space(3)))
; __device__ __forceinline__ float dpp_ror1(float v) { return __builtin_bit_cast(float, __builtin_amdgcn_update_dpp(0, __builtin_bit_cast(int, v), 0x121, 0xf, 0xf, false)); }
; __device__ __forceinline__ float dpp_ror15(float v) { return __builtin_bit_cast(float, __builtin_amdgcn_update_dpp(0, __builtin_bit_cast(int, v), 0x12F, 0xf, 0xf, false)); }
;     __device__ __forceinline__ void operator()(const f32x4 (&acc)[2][2][4][2], const Unit& u, int wr, int wc, int fr, int fq) const {
;     ...
;                 for (int m = 0; m < 4; ++m) { const int r = 128 * ai + 64 * wr + 16 * m + fr, t = tstart + r;
;                     const bool upok = t >= 1, dnok = (t + 1) < T, store_ok = (r >= vlo) && (r < vhi) && (t < T);
;                     f32x4 res[2];
; #pragma unroll
;                     for (int bj = 0; bj < 2; ++bj) { const f32x4 cur = acc[ai][bj][m][n];
;                         f32x4 su = cur, sd = cur;
;                         if (m > 0) { if (fr == 15) su = acc[ai][bj][m > 0 ? m - 1 : 0][n]; }
;                         if (m < 3) { if (fr == 0) sd = acc[ai][bj][m < 3 ? m + 1 : 3][n]; }
;                         f32x4 up, dn;
;                         up[0] = dpp_ror1(su[0]); up[1] = dpp_ror1(su[1]); up[2] = dpp_ror1(su[2]); up[3] = dpp_ror1(su[3]);
;                         dn[0] = dpp_ror15(sd[0]); dn[1] = dpp_ror15(sd[1]); dn[2] = dpp_ror15(sd[2]); dn[3] = dpp_ror15(sd[3]);
;                         if (m == 0) { f32x4 halo = zero4; if (blk > 0) halo = *(const PG8_LAS f32x4*)(xb + (((((blk - 1) * 2 + 1) * 4 + wc) * 4 + fq) * 16 + (bj * 2 + n) * 4)); if (fr == 0) up = halo; }
;                         if (m == 3) { f32x4 halo = zero4; if (blk < 3) halo = *(const PG8_LAS f32x4*)(xb + (((((blk + 1) * 2 + 0) * 4 + wc) * 4 + fq) * 16 + (bj * 2 + n) * 4)); if (fr == 15) dn = halo; }
;                         if (edge) { if (!upok) up = zero4; if (!dnok) dn = zero4; }
;                         res[bj] = bb[bj] + w0[bj] * up + w1[bj] * cur + w2[bj] * dn; }
	v_add_u32_e32 v220, s48, v234
	v_cmp_lt_i32_e32 vcc, 0, v220
	s_nop 1
	v_cndmask_b32_e32 v170, 0, v170, vcc
	v_cndmask_b32_e32 v171, 0, v171, vcc
	v_cmp_gt_i32_e32 vcc, s28, v220
	s_nop 1
	v_cndmask_b32_e32 v178, 0, v178, vcc
	v_cndmask_b32_e32 v179, 0, v179, vcc
	v_pk_fma_f32 v[202:203], v[106:107], v[170:171], v[118:119]
	v_pk_fma_f32 v[102:103], v[102:103], v[110:111], v[202:203]
	v_pk_fma_f32 v[102:103], v[114:115], v[178:179], v[102:103]
	v_mad_u32_u24 v250, v38, 8, v199
	ds_read_b64 v[170:171], v250
	ds_read_b64 v[178:179], v243 offset:16
	s_waitcnt lgkmcnt(10)
	v_add_u32_e32 v220, s48, v235
	v_cmp_lt_i32_e32 vcc, 0, v220
	s_nop 1
	v_cndmask_b32_e32 v172, 0, v172, vcc
	v_cndmask_b32_e32 v173, 0, v173, vcc
	v_cmp_gt_i32_e32 vcc, s28, v220
	s_nop 1
	v_cndmask_b32_e32 v180, 0, v180, vcc
	v_cndmask_b32_e32 v181, 0, v181, vcc
	v_pk_fma_f32 v[202:203], v[106:107], v[172:173], v[118:119]
	v_pk_fma_f32 v[94:95], v[94:95], v[110:111], v[202:203]
	v_pk_fma_f32 v[94:95], v[114:115], v[180:181], v[94:95]
	ds_read_b64 v[172:173], v244 offset:256
	ds_read_b64 v[180:181], v243 offset:272
	s_waitcnt lgkmcnt(10)
	v_add_u32_e32 v220, s48, v236
	v_cmp_lt_i32_e32 vcc, 0, v220
	s_nop 1
	v_cndmask_b32_e32 v174, 0, v174, vcc
	v_cndmask_b32_e32 v175, 0, v175, vcc
	v_cmp_gt_i32_e32 vcc, s28, v220
	s_nop 1
	v_cndmask_b32_e32 v194, 0, v194, vcc
	v_cndmask_b32_e32 v195, 0, v195, vcc
	v_pk_fma_f32 v[202:203], v[106:107], v[174:175], v[118:119]
	v_pk_fma_f32 v[86:87], v[86:87], v[110:111], v[202:203]
	v_pk_fma_f32 v[86:87], v[114:115], v[194:195], v[86:87]
	ds_read_b64 v[174:175], v244 offset:512
	ds_read_b64 v[194:195], v243 offset:528
	s_waitcnt lgkmcnt(10)
	v_add_u32_e32 v220, s48, v237
	v_cmp_lt_i32_e32 vcc, 0, v220
	s_nop 1
	v_cndmask_b32_e32 v176, 0, v176, vcc
	v_cndmask_b32_e32 v177, 0, v177, vcc
	v_cmp_gt_i32_e32 vcc, s28, v220
	s_nop 1
	v_cndmask_b32_e32 v196, 0, v196, vcc
	v_cndmask_b32_e32 v197, 0, v197, vcc
	v_pk_fma_f32 v[202:203], v[106:107], v[176:177], v[118:119]
	v_pk_fma_f32 v[78:79], v[78:79], v[110:111], v[202:203]
	v_pk_fma_f32 v[78:79], v[114:115], v[196:197], v[78:79]
	ds_read_b64 v[176:177], v244 offset:768
	v_mad_u32_u24 v251, v39, 8, v201
	ds_read_b64 v[196:197], v251
	ds_write_b64 v243, v[98:99]
	ds_write_b64 v243, v[90:91] offset:256
	ds_write_b64 v243, v[82:83] offset:512
	ds_write_b64 v243, v[74:75] offset:768
	s_waitcnt lgkmcnt(10)
	v_add_u32_e32 v220, s48, v234
	v_cmp_lt_i32_e32 vcc, 0, v220
	s_nop 1
	v_cndmask_b32_e32 v170, 0, v170, vcc
	v_cndmask_b32_e32 v171, 0, v171, vcc
	v_cmp_gt_i32_e32 vcc, s28, v220
	s_nop 1
	v_cndmask_b32_e32 v178, 0, v178, vcc
	v_cndmask_b32_e32 v179, 0, v179, vcc
	v_pk_fma_f32 v[202:203], v[108:109], v[170:171], v[120:121]
	v_pk_fma_f32 v[104:105], v[104:105], v[112:113], v[202:203]
	v_pk_fma_f32 v[104:105], v[116:117], v[178:179], v[104:105]
	v_mad_u32_u24 v250, v38, 32, v199
	ds_read_b64 v[170:171], v250
	ds_read_b64 v[178:179], v243 offset:16
	s_waitcnt lgkmcnt(10)
	v_add_u32_e32 v220, s48, v235
	v_cmp_lt_i32_e32 vcc, 0, v220
	s_nop 1
	v_cndmask_b32_e32 v172, 0, v172, vcc
	v_cndmask_b32_e32 v173, 0, v173, vcc
	v_cmp_gt_i32_e32 vcc, s28, v220
	s_nop 1
	v_cndmask_b32_e32 v180, 0, v180, vcc
	v_cndmask_b32_e32 v181, 0, v181, vcc
	v_pk_fma_f32 v[202:203], v[108:109], v[172:173], v[120:121]
	v_pk_fma_f32 v[96:97], v[96:97], v[112:113], v[202:203]
	v_pk_fma_f32 v[96:97], v[116:117], v[180:181], v[96:97]
	ds_read_b64 v[172:173], v244 offset:256
	ds_read_b64 v[180:181], v243 offset:272
	s_waitcnt lgkmcnt(10)
	v_add_u32_e32 v220, s48, v236
	v_cmp_lt_i32_e32 vcc, 0, v220
	s_nop 1
	v_cndmask_b32_e32 v174, 0, v174, vcc
	v_cndmask_b32_e32 v175, 0, v175, vcc
	v_cmp_gt_i32_e32 vcc, s28, v220
	s_nop 1
	v_cndmask_b32_e32 v194, 0, v194, vcc
	v_cndmask_b32_e32 v195, 0, v195, vcc
	v_pk_fma_f32 v[202:203], v[108:109], v[174:175], v[120:121]
	v_pk_fma_f32 v[88:89], v[88:89], v[112:113], v[202:203]
	v_pk_fma_f32 v[88:89], v[116:117], v[194:195], v[88:89]
	ds_read_b64 v[174:175], v244 offset:512
	ds_read_b64 v[194:195], v243 offset:528
	s_waitcnt lgkmcnt(10)
	v_add_u32_e32 v220, s48, v237
	v_cmp_lt_i32_e32 vcc, 0, v220
	s_nop 1
	v_cndmask_b32_e32 v176, 0, v176, vcc
	v_cndmask_b32_e32 v177, 0, v177, vcc
	v_cmp_gt_i32_e32 vcc, s28, v220
	s_nop 1
	v_cndmask_b32_e32 v196, 0, v196, vcc
	v_cndmask_b32_e32 v197, 0, v197, vcc
	v_pk_fma_f32 v[202:203], v[108:109], v[176:177], v[120:121]
	v_pk_fma_f32 v[80:81], v[80:81], v[112:113], v[202:203]
	v_pk_fma_f32 v[80:81], v[116:117], v[196:197], v[80:81]
	ds_read_b64 v[176:177], v244 offset:768
	v_mad_u32_u24 v251, v39, 32, v201
	ds_read_b64 v[196:197], v251
	ds_write_b64 v243, v[100:101]
	ds_write_b64 v243, v[92:93] offset:256
	ds_write_b64 v243, v[84:85] offset:512
	ds_write_b64 v243, v[76:77] offset:768
	s_waitcnt lgkmcnt(10)
	v_add_u32_e32 v220, s48, v234
	v_cmp_lt_i32_e32 vcc, 0, v220
	s_nop 1
	v_cndmask_b32_e32 v170, 0, v170, vcc
	v_cndmask_b32_e32 v171, 0, v171, vcc
	v_cmp_gt_i32_e32 vcc, s28, v220
	s_nop 1
	v_cndmask_b32_e32 v178, 0, v178, vcc
	v_cndmask_b32_e32 v179, 0, v179, vcc
	v_pk_fma_f32 v[202:203], v[122:123], v[170:171], v[134:135]
	v_pk_fma_f32 v[98:99], v[98:99], v[126:127], v[202:203]
	v_pk_fma_f32 v[98:99], v[130:131], v[178:179], v[98:99]
	v_mad_u32_u24 v250, v38, 40, v199
	ds_read_b64 v[170:171], v250
	ds_read_b64 v[178:179], v243 offset:16
	s_waitcnt lgkmcnt(10)
	v_add_u32_e32 v220, s48, v235
	v_cmp_lt_i32_e32 vcc, 0, v220
	s_nop 1
	v_cndmask_b32_e32 v172, 0, v172, vcc
	v_cndmask_b32_e32 v173, 0, v173, vcc
	v_cmp_gt_i32_e32 vcc, s28, v220
	s_nop 1
	v_cndmask_b32_e32 v180, 0, v180, vcc
	v_cndmask_b32_e32 v181, 0, v181, vcc
	v_pk_fma_f32 v[202:203], v[122:123], v[172:173], v[134:135]
	v_pk_fma_f32 v[90:91], v[90:91], v[126:127], v[202:203]
	v_pk_fma_f32 v[90:91], v[130:131], v[180:181], v[90:91]
	ds_read_b64 v[172:173], v244 offset:256
	ds_read_b64 v[180:181], v243 offset:272
	s_waitcnt lgkmcnt(10)
; #define PG8_LAS __attribute__((address_space(3)))
; __device__ __forceinline__ unsigned cvt_pk_bf16(float lo, float hi) { unsigned r; asm volatile("v_cvt_pk_bf16_f32 %0, %1, %2" : "=v"(r) : "v"(lo), "v"(hi)); return r; }
;     __device__ __forceinline__ void operator()(const f32x4 (&acc)[2][2][4][2], const Unit& u, int wr, int wc, int fr, int fq) const {
;     ...
;                 for (int m = 0; m < 4; ++m) { const int r = 128 * ai + 64 * wr + 16 * m + fr, t = tstart + r;
;                     const bool upok = t >= 1, dnok = (t + 1) < T, store_ok = (r >= vlo) && (r < vhi) && (t < T);
;                     f32x4 res[2];
; #pragma unroll
;                     for (int bj = 0; bj < 2; ++bj) { const f32x4 cur = acc[ai][bj][m][n];
;                         f32x4 su = cur, sd = cur;
;                         if (m > 0) { if (fr == 15) su = acc[ai][bj][m > 0 ? m - 1 : 0][n]; }
;                         if (m < 3) { if (fr == 0) sd = acc[ai][bj][m < 3 ? m + 1 : 3][n]; }
;                         f32x4 up, dn;
;                         up[0] = dpp_ror1(su[0]); up[1] = dpp_ror1(su[1]); up[2] = dpp_ror1(su[2]); up[3] = dpp_ror1(su[3]);
;                         dn[0] = dpp_ror15(sd[0]); dn[1] = dpp_ror15(sd[1]); dn[2] = dpp_ror15(sd[2]); dn[3] = dpp_ror15(sd[3]);
;                         if (m == 0) { f32x4 halo = zero4; if (blk > 0) halo = *(const PG8_LAS f32x4*)(xb + (((((blk - 1) * 2 + 1) * 4 + wc) * 4 + fq) * 16 + (bj * 2 + n) * 4)); if (fr == 0) up = halo; }
;                         if (m == 3) { f32x4 halo = zero4; if (blk < 3) halo = *(const PG8_LAS f32x4*)(xb + (((((blk + 1) * 2 + 0) * 4 + wc) * 4 + fq) * 16 + (bj * 2 + n) * 4)); if (fr == 15) dn = halo; }
;                         if (edge) { if (!upok) up = zero4; if (!dnok) dn = zero4; }
;                         res[bj] = bb[bj] + w0[bj] * up + w1[bj] * cur + w2[bj] * dn; }
;                     if (store_ok) {
;                         float o[4];
; #pragma unroll
;                         for (int j = 0; j < 4; ++j) { const float gg = res[1][j]; o[j] = gg * __builtin_amdgcn_rcpf(1.f + __expf(-gg)) * res[0][j]; }
;                         u32x2 w; w.x = cvt_pk_bf16(o[0], o[1]); w.y = cvt_pk_bf16(o[2], o[3]);
;                         *(u32x2*)(ACT + (size_t)(seqrow + t) * 2816 + ch0 + 4 * n) = w; } } }
	v_add_u32_e32 v220, s48, v236
	v_cmp_lt_i32_e32 vcc, 0, v220
	s_nop 1
	v_cndmask_b32_e32 v174, 0, v174, vcc
	v_cndmask_b32_e32 v175, 0, v175, vcc
	v_cmp_gt_i32_e32 vcc, s28, v220
	s_nop 1
	v_cndmask_b32_e32 v194, 0, v194, vcc
	v_cndmask_b32_e32 v195, 0, v195, vcc
	v_pk_fma_f32 v[202:203], v[122:123], v[174:175], v[134:135]
	v_pk_fma_f32 v[82:83], v[82:83], v[126:127], v[202:203]
	v_pk_fma_f32 v[82:83], v[130:131], v[194:195], v[82:83]
	ds_read_b64 v[174:175], v244 offset:512
	ds_read_b64 v[194:195], v243 offset:528
	s_waitcnt lgkmcnt(10)
	v_add_u32_e32 v220, s48, v237
	v_cmp_lt_i32_e32 vcc, 0, v220
	s_nop 1
	v_cndmask_b32_e32 v176, 0, v176, vcc
	v_cndmask_b32_e32 v177, 0, v177, vcc
	v_cmp_gt_i32_e32 vcc, s28, v220
	s_nop 1
	v_cndmask_b32_e32 v196, 0, v196, vcc
	v_cndmask_b32_e32 v197, 0, v197, vcc
	v_pk_fma_f32 v[202:203], v[122:123], v[176:177], v[134:135]
	v_pk_fma_f32 v[74:75], v[74:75], v[126:127], v[202:203]
	v_pk_fma_f32 v[74:75], v[130:131], v[196:197], v[74:75]
	ds_read_b64 v[176:177], v244 offset:768
	v_mad_u32_u24 v251, v39, 40, v201
	ds_read_b64 v[196:197], v251
	ds_write_b64 v243, v[70:71]
	ds_write_b64 v243, v[62:63] offset:256
	ds_write_b64 v243, v[54:55] offset:512
	ds_write_b64 v243, v[46:47] offset:768
	s_waitcnt lgkmcnt(10)
	v_add_u32_e32 v220, s48, v234
	v_cmp_lt_i32_e32 vcc, 0, v220
	s_nop 1
	v_cndmask_b32_e32 v170, 0, v170, vcc
	v_cndmask_b32_e32 v171, 0, v171, vcc
	v_cmp_gt_i32_e32 vcc, s28, v220
	s_nop 1
	v_cndmask_b32_e32 v178, 0, v178, vcc
	v_cndmask_b32_e32 v179, 0, v179, vcc
	v_pk_fma_f32 v[202:203], v[124:125], v[170:171], v[136:137]
	v_pk_fma_f32 v[100:101], v[100:101], v[128:129], v[202:203]
	v_pk_fma_f32 v[100:101], v[132:133], v[178:179], v[100:101]
	v_mad_u32_u24 v250, v38, 16, v198
	ds_read_b64 v[170:171], v250
	ds_read_b64 v[178:179], v243 offset:16
	s_waitcnt lgkmcnt(10)
	v_add_u32_e32 v220, s48, v235
	v_cmp_lt_i32_e32 vcc, 0, v220
	s_nop 1
	v_cndmask_b32_e32 v172, 0, v172, vcc
	v_cndmask_b32_e32 v173, 0, v173, vcc
	v_cmp_gt_i32_e32 vcc, s28, v220
	s_nop 1
	v_cndmask_b32_e32 v180, 0, v180, vcc
	v_cndmask_b32_e32 v181, 0, v181, vcc
	v_pk_fma_f32 v[202:203], v[124:125], v[172:173], v[136:137]
	v_pk_fma_f32 v[92:93], v[92:93], v[128:129], v[202:203]
	v_pk_fma_f32 v[92:93], v[132:133], v[180:181], v[92:93]
	ds_read_b64 v[172:173], v244 offset:256
	ds_read_b64 v[180:181], v243 offset:272
	s_waitcnt lgkmcnt(10)
	v_add_u32_e32 v220, s48, v236
	v_cmp_lt_i32_e32 vcc, 0, v220
	s_nop 1
	v_cndmask_b32_e32 v174, 0, v174, vcc
	v_cndmask_b32_e32 v175, 0, v175, vcc
	v_cmp_gt_i32_e32 vcc, s28, v220
	s_nop 1
	v_cndmask_b32_e32 v194, 0, v194, vcc
	v_cndmask_b32_e32 v195, 0, v195, vcc
	v_pk_fma_f32 v[202:203], v[124:125], v[174:175], v[136:137]
	v_pk_fma_f32 v[84:85], v[84:85], v[128:129], v[202:203]
	v_pk_fma_f32 v[84:85], v[132:133], v[194:195], v[84:85]
	ds_read_b64 v[174:175], v244 offset:512
	ds_read_b64 v[194:195], v243 offset:528
	s_waitcnt lgkmcnt(10)
	v_add_u32_e32 v220, s48, v237
	v_cmp_lt_i32_e32 vcc, 0, v220
	s_nop 1
	v_cndmask_b32_e32 v176, 0, v176, vcc
	v_cndmask_b32_e32 v177, 0, v177, vcc
	v_cmp_gt_i32_e32 vcc, s28, v220
	s_nop 1
	v_cndmask_b32_e32 v196, 0, v196, vcc
	v_cndmask_b32_e32 v197, 0, v197, vcc
	v_pk_fma_f32 v[202:203], v[124:125], v[176:177], v[136:137]
	v_pk_fma_f32 v[76:77], v[76:77], v[128:129], v[202:203]
	v_pk_fma_f32 v[76:77], v[132:133], v[196:197], v[76:77]
	ds_read_b64 v[176:177], v244 offset:768
	v_mad_u32_u24 v251, v39, 16, v200
	ds_read_b64 v[196:197], v251
	v_mul_f32_e32 v208, 0xbfb8aa3b, v98
	v_mul_f32_e32 v209, 0xbfb8aa3b, v99
	v_mul_f32_e32 v210, 0xbfb8aa3b, v100
	v_mul_f32_e32 v211, 0xbfb8aa3b, v101
	v_exp_f32_e32 v208, v208
	v_exp_f32_e32 v209, v209
	v_exp_f32_e32 v210, v210
	v_exp_f32_e32 v211, v211
	v_add_f32_e32 v208, 1.0, v208
	v_add_f32_e32 v209, 1.0, v209
	v_add_f32_e32 v210, 1.0, v210
	v_add_f32_e32 v211, 1.0, v211
	v_rcp_f32_e32 v208, v208
	v_rcp_f32_e32 v209, v209
	v_rcp_f32_e32 v210, v210
	v_rcp_f32_e32 v211, v211
	v_mul_f32_e32 v98, v98, v208
	v_mul_f32_e32 v99, v99, v209
	v_mul_f32_e32 v100, v100, v210
	v_mul_f32_e32 v101, v101, v211
	v_mul_f32_e32 v98, v102, v98
	v_mul_f32_e32 v99, v103, v99
	v_mul_f32_e32 v100, v104, v100
	v_mul_f32_e32 v101, v105, v101
	v_cvt_pk_bf16_f32 v212, v98, v99
	v_cvt_pk_bf16_f32 v213, v100, v101
	v_mad_u32_u24 v221, v234, s29, v247
	s_and_saveexec_b64 s[30:31], s[20:21]
	global_store_dwordx2 v221, v[212:213], s[10:11]
	s_mov_b64 exec, s[30:31]
	v_mul_f32_e32 v208, 0xbfb8aa3b, v90
	v_mul_f32_e32 v209, 0xbfb8aa3b, v91
	v_mul_f32_e32 v210, 0xbfb8aa3b, v92
	v_mul_f32_e32 v211, 0xbfb8aa3b, v93
	v_exp_f32_e32 v208, v208
	v_exp_f32_e32 v209, v209
	v_exp_f32_e32 v210, v210
	v_exp_f32_e32 v211, v211
	v_add_f32_e32 v208, 1.0, v208
	v_add_f32_e32 v209, 1.0, v209
	v_add_f32_e32 v210, 1.0, v210
	v_add_f32_e32 v211, 1.0, v211
	v_rcp_f32_e32 v208, v208
	v_rcp_f32_e32 v209, v209
	v_rcp_f32_e32 v210, v210
	v_rcp_f32_e32 v211, v211
	v_mul_f32_e32 v90, v90, v208
	v_mul_f32_e32 v91, v91, v209
	v_mul_f32_e32 v92, v92, v210
	v_mul_f32_e32 v93, v93, v211
	v_mul_f32_e32 v90, v94, v90
	v_mul_f32_e32 v91, v95, v91
	v_mul_f32_e32 v92, v96, v92
	v_mul_f32_e32 v93, v97, v93
	v_cvt_pk_bf16_f32 v218, v90, v91
	v_cvt_pk_bf16_f32 v219, v92, v93
	v_mad_u32_u24 v40, v235, s29, v247
	s_and_saveexec_b64 s[30:31], s[22:23]
	global_store_dwordx2 v40, v[218:219], s[10:11]
	s_mov_b64 exec, s[30:31]
	v_mul_f32_e32 v208, 0xbfb8aa3b, v82
	v_mul_f32_e32 v209, 0xbfb8aa3b, v83
	v_mul_f32_e32 v210, 0xbfb8aa3b, v84
	v_mul_f32_e32 v211, 0xbfb8aa3b, v85
	v_exp_f32_e32 v208, v208
	v_exp_f32_e32 v209, v209
	v_exp_f32_e32 v210, v210
	v_exp_f32_e32 v211, v211
	v_add_f32_e32 v208, 1.0, v208
; #define PG8_LAS __attribute__((address_space(3)))
; __device__ __forceinline__ unsigned cvt_pk_bf16(float lo, float hi) { unsigned r; asm volatile("v_cvt_pk_bf16_f32 %0, %1, %2" : "=v"(r) : "v"(lo), "v"(hi)); return r; }
;     __device__ __forceinline__ void operator()(const f32x4 (&acc)[2][2][4][2], const Unit& u, int wr, int wc, int fr, int fq) const {
;     ...
;                 for (int m = 0; m < 4; ++m) { const int r = 128 * ai + 64 * wr + 16 * m + fr, t = tstart + r;
;                     const bool upok = t >= 1, dnok = (t + 1) < T, store_ok = (r >= vlo) && (r < vhi) && (t < T);
;                     f32x4 res[2];
; #pragma unroll
;                     for (int bj = 0; bj < 2; ++bj) { const f32x4 cur = acc[ai][bj][m][n];
;                         f32x4 su = cur, sd = cur;
;                         if (m > 0) { if (fr == 15) su = acc[ai][bj][m > 0 ? m - 1 : 0][n]; }
;                         if (m < 3) { if (fr == 0) sd = acc[ai][bj][m < 3 ? m + 1 : 3][n]; }
;                         f32x4 up, dn;
;                         up[0] = dpp_ror1(su[0]); up[1] = dpp_ror1(su[1]); up[2] = dpp_ror1(su[2]); up[3] = dpp_ror1(su[3]);
;                         dn[0] = dpp_ror15(sd[0]); dn[1] = dpp_ror15(sd[1]); dn[2] = dpp_ror15(sd[2]); dn[3] = dpp_ror15(sd[3]);
;                         if (m == 0) { f32x4 halo = zero4; if (blk > 0) halo = *(const PG8_LAS f32x4*)(xb + (((((blk - 1) * 2 + 1) * 4 + wc) * 4 + fq) * 16 + (bj * 2 + n) * 4)); if (fr == 0) up = halo; }
;                         if (m == 3) { f32x4 halo = zero4; if (blk < 3) halo = *(const PG8_LAS f32x4*)(xb + (((((blk + 1) * 2 + 0) * 4 + wc) * 4 + fq) * 16 + (bj * 2 + n) * 4)); if (fr == 15) dn = halo; }
;                         if (edge) { if (!upok) up = zero4; if (!dnok) dn = zero4; }
;                         res[bj] = bb[bj] + w0[bj] * up + w1[bj] * cur + w2[bj] * dn; }
;                     if (store_ok) {
;                         float o[4];
; #pragma unroll
;                         for (int j = 0; j < 4; ++j) { const float gg = res[1][j]; o[j] = gg * __builtin_amdgcn_rcpf(1.f + __expf(-gg)) * res[0][j]; }
;                         u32x2 w; w.x = cvt_pk_bf16(o[0], o[1]); w.y = cvt_pk_bf16(o[2], o[3]);
;                         *(u32x2*)(ACT + (size_t)(seqrow + t) * 2816 + ch0 + 4 * n) = w; } } }
	v_add_f32_e32 v209, 1.0, v209
	v_add_f32_e32 v210, 1.0, v210
	v_add_f32_e32 v211, 1.0, v211
	v_rcp_f32_e32 v208, v208
	v_rcp_f32_e32 v209, v209
	v_rcp_f32_e32 v210, v210
	v_rcp_f32_e32 v211, v211
	v_mul_f32_e32 v82, v82, v208
	v_mul_f32_e32 v83, v83, v209
	v_mul_f32_e32 v84, v84, v210
	v_mul_f32_e32 v85, v85, v211
	v_mul_f32_e32 v82, v86, v82
	v_mul_f32_e32 v83, v87, v83
	v_mul_f32_e32 v84, v88, v84
	v_mul_f32_e32 v85, v89, v85
	v_cvt_pk_bf16_f32 v212, v82, v83
	v_cvt_pk_bf16_f32 v213, v84, v85
	v_mad_u32_u24 v221, v236, s29, v247
	s_and_saveexec_b64 s[30:31], s[24:25]
	global_store_dwordx2 v221, v[212:213], s[10:11]
	s_mov_b64 exec, s[30:31]
	v_mul_f32_e32 v208, 0xbfb8aa3b, v74
	v_mul_f32_e32 v209, 0xbfb8aa3b, v75
	v_mul_f32_e32 v210, 0xbfb8aa3b, v76
	v_mul_f32_e32 v211, 0xbfb8aa3b, v77
	v_exp_f32_e32 v208, v208
	v_exp_f32_e32 v209, v209
	v_exp_f32_e32 v210, v210
	v_exp_f32_e32 v211, v211
	v_add_f32_e32 v208, 1.0, v208
	v_add_f32_e32 v209, 1.0, v209
	v_add_f32_e32 v210, 1.0, v210
	v_add_f32_e32 v211, 1.0, v211
	v_rcp_f32_e32 v208, v208
	v_rcp_f32_e32 v209, v209
	v_rcp_f32_e32 v210, v210
	v_rcp_f32_e32 v211, v211
	v_mul_f32_e32 v74, v74, v208
	v_mul_f32_e32 v75, v75, v209
	v_mul_f32_e32 v76, v76, v210
	v_mul_f32_e32 v77, v77, v211
	v_mul_f32_e32 v74, v78, v74
	v_mul_f32_e32 v75, v79, v75
	v_mul_f32_e32 v76, v80, v76
	v_mul_f32_e32 v77, v81, v77
	v_cvt_pk_bf16_f32 v218, v74, v75
	v_cvt_pk_bf16_f32 v219, v76, v77
	v_mad_u32_u24 v40, v237, s29, v247
	s_and_saveexec_b64 s[30:31], s[26:27]
	global_store_dwordx2 v40, v[218:219], s[10:11]
	s_mov_b64 exec, s[30:31]
	s_waitcnt vmcnt(4)
	ds_write_b64 v243, v[72:73]
	ds_write_b64 v243, v[64:65] offset:256
	ds_write_b64 v243, v[56:57] offset:512
	ds_write_b64 v243, v[48:49] offset:768
	s_waitcnt lgkmcnt(10)
	v_add_u32_e32 v220, s48, v227
	v_cmp_lt_i32_e32 vcc, 0, v220
	s_nop 1
	v_cndmask_b32_e32 v170, 0, v170, vcc
	v_cndmask_b32_e32 v171, 0, v171, vcc
	v_cmp_gt_i32_e32 vcc, s28, v220
	s_nop 1
	v_cndmask_b32_e32 v178, 0, v178, vcc
	v_cndmask_b32_e32 v179, 0, v179, vcc
	v_pk_fma_f32 v[202:203], v[138:139], v[170:171], v[150:151]
	v_pk_fma_f32 v[70:71], v[70:71], v[142:143], v[202:203]
	v_pk_fma_f32 v[70:71], v[146:147], v[178:179], v[70:71]
	v_mad_u32_u24 v250, v38, 24, v198
	ds_read_b64 v[170:171], v250
	ds_read_b64 v[178:179], v243 offset:16
	s_waitcnt lgkmcnt(10)
	v_add_u32_e32 v220, s48, v231
	v_cmp_lt_i32_e32 vcc, 0, v220
	s_nop 1
	v_cndmask_b32_e32 v172, 0, v172, vcc
	v_cndmask_b32_e32 v173, 0, v173, vcc
	v_cmp_gt_i32_e32 vcc, s28, v220
	s_nop 1
	v_cndmask_b32_e32 v180, 0, v180, vcc
	v_cndmask_b32_e32 v181, 0, v181, vcc
	v_pk_fma_f32 v[202:203], v[138:139], v[172:173], v[150:151]
	v_pk_fma_f32 v[62:63], v[62:63], v[142:143], v[202:203]
	v_pk_fma_f32 v[62:63], v[146:147], v[180:181], v[62:63]
	ds_read_b64 v[172:173], v244 offset:256
	ds_read_b64 v[180:181], v243 offset:272
	s_waitcnt lgkmcnt(10)
	v_add_u32_e32 v220, s48, v232
	v_cmp_lt_i32_e32 vcc, 0, v220
	s_nop 1
	v_cndmask_b32_e32 v174, 0, v174, vcc
	v_cndmask_b32_e32 v175, 0, v175, vcc
	v_cmp_gt_i32_e32 vcc, s28, v220
	s_nop 1
	v_cndmask_b32_e32 v194, 0, v194, vcc
	v_cndmask_b32_e32 v195, 0, v195, vcc
	v_pk_fma_f32 v[202:203], v[138:139], v[174:175], v[150:151]
	v_pk_fma_f32 v[54:55], v[54:55], v[142:143], v[202:203]
	v_pk_fma_f32 v[54:55], v[146:147], v[194:195], v[54:55]
	ds_read_b64 v[174:175], v244 offset:512
	ds_read_b64 v[194:195], v243 offset:528
	s_waitcnt lgkmcnt(10)
	v_add_u32_e32 v220, s48, v233
	v_cmp_lt_i32_e32 vcc, 0, v220
	s_nop 1
	v_cndmask_b32_e32 v176, 0, v176, vcc
	v_cndmask_b32_e32 v177, 0, v177, vcc
	v_cmp_gt_i32_e32 vcc, s28, v220
	s_nop 1
	v_cndmask_b32_e32 v196, 0, v196, vcc
	v_cndmask_b32_e32 v197, 0, v197, vcc
	v_pk_fma_f32 v[202:203], v[138:139], v[176:177], v[150:151]
	v_pk_fma_f32 v[46:47], v[46:47], v[142:143], v[202:203]
	v_pk_fma_f32 v[46:47], v[146:147], v[196:197], v[46:47]
	ds_read_b64 v[176:177], v244 offset:768
	v_mad_u32_u24 v251, v39, 24, v200
	ds_read_b64 v[196:197], v251
	ds_write_b64 v243, v[66:67]
	ds_write_b64 v243, v[58:59] offset:256
	ds_write_b64 v243, v[50:51] offset:512
	ds_write_b64 v243, v[42:43] offset:768
	s_waitcnt lgkmcnt(10)
	v_add_u32_e32 v220, s48, v227
	v_cmp_lt_i32_e32 vcc, 0, v220
	s_nop 1
	v_cndmask_b32_e32 v170, 0, v170, vcc
	v_cndmask_b32_e32 v171, 0, v171, vcc
	v_cmp_gt_i32_e32 vcc, s28, v220
	s_nop 1
	v_cndmask_b32_e32 v178, 0, v178, vcc
	v_cndmask_b32_e32 v179, 0, v179, vcc
	v_pk_fma_f32 v[202:203], v[140:141], v[170:171], v[152:153]
	v_pk_fma_f32 v[72:73], v[72:73], v[144:145], v[202:203]
	v_pk_fma_f32 v[72:73], v[148:149], v[178:179], v[72:73]
	v_mad_u32_u24 v250, v38, 48, v198
	ds_read_b64 v[170:171], v250
	ds_read_b64 v[178:179], v243 offset:16
	s_waitcnt lgkmcnt(10)
	v_add_u32_e32 v220, s48, v231
	v_cmp_lt_i32_e32 vcc, 0, v220
	s_nop 1
	v_cndmask_b32_e32 v172, 0, v172, vcc
	v_cndmask_b32_e32 v173, 0, v173, vcc
	v_cmp_gt_i32_e32 vcc, s28, v220
	s_nop 1
	v_cndmask_b32_e32 v180, 0, v180, vcc
	v_cndmask_b32_e32 v181, 0, v181, vcc
	v_pk_fma_f32 v[202:203], v[140:141], v[172:173], v[152:153]
	v_pk_fma_f32 v[64:65], v[64:65], v[144:145], v[202:203]
	v_pk_fma_f32 v[64:65], v[148:149], v[180:181], v[64:65]
	ds_read_b64 v[172:173], v244 offset:256
	ds_read_b64 v[180:181], v243 offset:272
	s_waitcnt lgkmcnt(10)
	v_add_u32_e32 v220, s48, v232
	v_cmp_lt_i32_e32 vcc, 0, v220
	s_nop 1
	v_cndmask_b32_e32 v174, 0, v174, vcc
	v_cndmask_b32_e32 v175, 0, v175, vcc
	v_cmp_gt_i32_e32 vcc, s28, v220
	s_nop 1
	v_cndmask_b32_e32 v194, 0, v194, vcc
	v_cndmask_b32_e32 v195, 0, v195, vcc
	v_pk_fma_f32 v[202:203], v[140:141], v[174:175], v[152:153]
	v_pk_fma_f32 v[56:57], v[56:57], v[144:145], v[202:203]
	v_pk_fma_f32 v[56:57], v[148:149], v[194:195], v[56:57]
	ds_read_b64 v[174:175], v244 offset:512
	ds_read_b64 v[194:195], v243 offset:528
	s_waitcnt lgkmcnt(10)
; #define PG8_LAS __attribute__((address_space(3)))
; __device__ __forceinline__ float dpp_ror1(float v) { return __builtin_bit_cast(float, __builtin_amdgcn_update_dpp(0, __builtin_bit_cast(int, v), 0x121, 0xf, 0xf, false)); }
; __device__ __forceinline__ float dpp_ror15(float v) { return __builtin_bit_cast(float, __builtin_amdgcn_update_dpp(0, __builtin_bit_cast(int, v), 0x12F, 0xf, 0xf, false)); }
;     __device__ __forceinline__ void operator()(const f32x4 (&acc)[2][2][4][2], const Unit& u, int wr, int wc, int fr, int fq) const {
;     ...
;                 for (int m = 0; m < 4; ++m) { const int r = 128 * ai + 64 * wr + 16 * m + fr, t = tstart + r;
;                     const bool upok = t >= 1, dnok = (t + 1) < T, store_ok = (r >= vlo) && (r < vhi) && (t < T);
;                     f32x4 res[2];
; #pragma unroll
;                     for (int bj = 0; bj < 2; ++bj) { const f32x4 cur = acc[ai][bj][m][n];
;                         f32x4 su = cur, sd = cur;
;                         if (m > 0) { if (fr == 15) su = acc[ai][bj][m > 0 ? m - 1 : 0][n]; }
;                         if (m < 3) { if (fr == 0) sd = acc[ai][bj][m < 3 ? m + 1 : 3][n]; }
;                         f32x4 up, dn;
;                         up[0] = dpp_ror1(su[0]); up[1] = dpp_ror1(su[1]); up[2] = dpp_ror1(su[2]); up[3] = dpp_ror1(su[3]);
;                         dn[0] = dpp_ror15(sd[0]); dn[1] = dpp_ror15(sd[1]); dn[2] = dpp_ror15(sd[2]); dn[3] = dpp_ror15(sd[3]);
;                         if (m == 0) { f32x4 halo = zero4; if (blk > 0) halo = *(const PG8_LAS f32x4*)(xb + (((((blk - 1) * 2 + 1) * 4 + wc) * 4 + fq) * 16 + (bj * 2 + n) * 4)); if (fr == 0) up = halo; }
;                         if (m == 3) { f32x4 halo = zero4; if (blk < 3) halo = *(const PG8_LAS f32x4*)(xb + (((((blk + 1) * 2 + 0) * 4 + wc) * 4 + fq) * 16 + (bj * 2 + n) * 4)); if (fr == 15) dn = halo; }
;                         if (edge) { if (!upok) up = zero4; if (!dnok) dn = zero4; }
;                         res[bj] = bb[bj] + w0[bj] * up + w1[bj] * cur + w2[bj] * dn; }
	v_add_u32_e32 v220, s48, v233
	v_cmp_lt_i32_e32 vcc, 0, v220
	s_nop 1
	v_cndmask_b32_e32 v176, 0, v176, vcc
	v_cndmask_b32_e32 v177, 0, v177, vcc
	v_cmp_gt_i32_e32 vcc, s28, v220
	s_nop 1
	v_cndmask_b32_e32 v196, 0, v196, vcc
	v_cndmask_b32_e32 v197, 0, v197, vcc
	v_pk_fma_f32 v[202:203], v[140:141], v[176:177], v[152:153]
	v_pk_fma_f32 v[48:49], v[48:49], v[144:145], v[202:203]
	v_pk_fma_f32 v[48:49], v[148:149], v[196:197], v[48:49]
	ds_read_b64 v[176:177], v244 offset:768
	v_mad_u32_u24 v251, v39, 48, v200
	ds_read_b64 v[196:197], v251
	ds_write_b64 v243, v[68:69]
	ds_write_b64 v243, v[60:61] offset:256
	ds_write_b64 v243, v[52:53] offset:512
	ds_write_b64 v243, v[44:45] offset:768
	s_waitcnt lgkmcnt(10)
	v_add_u32_e32 v220, s48, v227
	v_cmp_lt_i32_e32 vcc, 0, v220
	s_nop 1
	v_cndmask_b32_e32 v170, 0, v170, vcc
	v_cndmask_b32_e32 v171, 0, v171, vcc
	v_cmp_gt_i32_e32 vcc, s28, v220
	s_nop 1
	v_cndmask_b32_e32 v178, 0, v178, vcc
	v_cndmask_b32_e32 v179, 0, v179, vcc
	v_pk_fma_f32 v[202:203], v[154:155], v[170:171], v[166:167]
	v_pk_fma_f32 v[66:67], v[66:67], v[158:159], v[202:203]
	v_pk_fma_f32 v[66:67], v[162:163], v[178:179], v[66:67]
	v_mad_u32_u24 v250, v38, 56, v198
	ds_read_b64 v[170:171], v250
	ds_read_b64 v[178:179], v243 offset:16
	s_waitcnt lgkmcnt(10)
	v_add_u32_e32 v220, s48, v231
	v_cmp_lt_i32_e32 vcc, 0, v220
	s_nop 1
	v_cndmask_b32_e32 v172, 0, v172, vcc
	v_cndmask_b32_e32 v173, 0, v173, vcc
	v_cmp_gt_i32_e32 vcc, s28, v220
	s_nop 1
	v_cndmask_b32_e32 v180, 0, v180, vcc
	v_cndmask_b32_e32 v181, 0, v181, vcc
	v_pk_fma_f32 v[202:203], v[154:155], v[172:173], v[166:167]
	v_pk_fma_f32 v[58:59], v[58:59], v[158:159], v[202:203]
	v_pk_fma_f32 v[58:59], v[162:163], v[180:181], v[58:59]
	ds_read_b64 v[172:173], v244 offset:256
	ds_read_b64 v[180:181], v243 offset:272
	s_waitcnt lgkmcnt(10)
	v_add_u32_e32 v220, s48, v232
	v_cmp_lt_i32_e32 vcc, 0, v220
	s_nop 1
	v_cndmask_b32_e32 v174, 0, v174, vcc
	v_cndmask_b32_e32 v175, 0, v175, vcc
	v_cmp_gt_i32_e32 vcc, s28, v220
	s_nop 1
	v_cndmask_b32_e32 v194, 0, v194, vcc
	v_cndmask_b32_e32 v195, 0, v195, vcc
	v_pk_fma_f32 v[202:203], v[154:155], v[174:175], v[166:167]
	v_pk_fma_f32 v[50:51], v[50:51], v[158:159], v[202:203]
	v_pk_fma_f32 v[50:51], v[162:163], v[194:195], v[50:51]
	ds_read_b64 v[174:175], v244 offset:512
	ds_read_b64 v[194:195], v243 offset:528
	s_waitcnt lgkmcnt(10)
	v_add_u32_e32 v220, s48, v233
	v_cmp_lt_i32_e32 vcc, 0, v220
	s_nop 1
	v_cndmask_b32_e32 v176, 0, v176, vcc
	v_cndmask_b32_e32 v177, 0, v177, vcc
	v_cmp_gt_i32_e32 vcc, s28, v220
	s_nop 1
	v_cndmask_b32_e32 v196, 0, v196, vcc
	v_cndmask_b32_e32 v197, 0, v197, vcc
	v_pk_fma_f32 v[202:203], v[154:155], v[176:177], v[166:167]
	v_pk_fma_f32 v[42:43], v[42:43], v[158:159], v[202:203]
	v_pk_fma_f32 v[42:43], v[162:163], v[196:197], v[42:43]
	ds_read_b64 v[176:177], v244 offset:768
	v_mad_u32_u24 v251, v39, 56, v200
	ds_read_b64 v[196:197], v251
	ds_write_b64 v243, v[30:31]
	ds_write_b64 v243, v[22:23] offset:256
	ds_write_b64 v243, v[14:15] offset:512
	ds_write_b64 v243, v[6:7] offset:768
	s_waitcnt lgkmcnt(10)
	v_add_u32_e32 v220, s48, v227
	v_cmp_lt_i32_e32 vcc, 0, v220
	s_nop 1
	v_cndmask_b32_e32 v170, 0, v170, vcc
	v_cndmask_b32_e32 v171, 0, v171, vcc
	v_cmp_gt_i32_e32 vcc, s28, v220
	s_nop 1
	v_cndmask_b32_e32 v178, 0, v178, vcc
	v_cndmask_b32_e32 v179, 0, v179, vcc
	v_pk_fma_f32 v[202:203], v[156:157], v[170:171], v[168:169]
	v_pk_fma_f32 v[68:69], v[68:69], v[160:161], v[202:203]
	v_pk_fma_f32 v[68:69], v[164:165], v[178:179], v[68:69]
	v_mad_u32_u24 v250, v38, 16, v199
	ds_read_b64 v[170:171], v250
	ds_read_b64 v[178:179], v243 offset:16
	s_waitcnt lgkmcnt(10)
	v_add_u32_e32 v220, s48, v231
	v_cmp_lt_i32_e32 vcc, 0, v220
	s_nop 1
	v_cndmask_b32_e32 v172, 0, v172, vcc
	v_cndmask_b32_e32 v173, 0, v173, vcc
	v_cmp_gt_i32_e32 vcc, s28, v220
	s_nop 1
	v_cndmask_b32_e32 v180, 0, v180, vcc
	v_cndmask_b32_e32 v181, 0, v181, vcc
	v_pk_fma_f32 v[202:203], v[156:157], v[172:173], v[168:169]
	v_pk_fma_f32 v[60:61], v[60:61], v[160:161], v[202:203]
	v_pk_fma_f32 v[60:61], v[164:165], v[180:181], v[60:61]
	ds_read_b64 v[172:173], v244 offset:256
	ds_read_b64 v[180:181], v243 offset:272
	s_waitcnt lgkmcnt(10)
	v_add_u32_e32 v220, s48, v232
	v_cmp_lt_i32_e32 vcc, 0, v220
	s_nop 1
	v_cndmask_b32_e32 v174, 0, v174, vcc
	v_cndmask_b32_e32 v175, 0, v175, vcc
	v_cmp_gt_i32_e32 vcc, s28, v220
	s_nop 1
	v_cndmask_b32_e32 v194, 0, v194, vcc
	v_cndmask_b32_e32 v195, 0, v195, vcc
	v_pk_fma_f32 v[202:203], v[156:157], v[174:175], v[168:169]
	v_pk_fma_f32 v[52:53], v[52:53], v[160:161], v[202:203]
	v_pk_fma_f32 v[52:53], v[164:165], v[194:195], v[52:53]
	ds_read_b64 v[174:175], v244 offset:512
	ds_read_b64 v[194:195], v243 offset:528
	s_waitcnt lgkmcnt(10)
; #define PG8_LAS __attribute__((address_space(3)))
; __device__ __forceinline__ unsigned cvt_pk_bf16(float lo, float hi) { unsigned r; asm volatile("v_cvt_pk_bf16_f32 %0, %1, %2" : "=v"(r) : "v"(lo), "v"(hi)); return r; }
;     __device__ __forceinline__ void operator()(const f32x4 (&acc)[2][2][4][2], const Unit& u, int wr, int wc, int fr, int fq) const {
;     ...
;                 for (int m = 0; m < 4; ++m) { const int r = 128 * ai + 64 * wr + 16 * m + fr, t = tstart + r;
;                     const bool upok = t >= 1, dnok = (t + 1) < T, store_ok = (r >= vlo) && (r < vhi) && (t < T);
;                     f32x4 res[2];
; #pragma unroll
;                     for (int bj = 0; bj < 2; ++bj) { const f32x4 cur = acc[ai][bj][m][n];
;                         f32x4 su = cur, sd = cur;
;                         if (m > 0) { if (fr == 15) su = acc[ai][bj][m > 0 ? m - 1 : 0][n]; }
;                         if (m < 3) { if (fr == 0) sd = acc[ai][bj][m < 3 ? m + 1 : 3][n]; }
;                         f32x4 up, dn;
;                         up[0] = dpp_ror1(su[0]); up[1] = dpp_ror1(su[1]); up[2] = dpp_ror1(su[2]); up[3] = dpp_ror1(su[3]);
;                         dn[0] = dpp_ror15(sd[0]); dn[1] = dpp_ror15(sd[1]); dn[2] = dpp_ror15(sd[2]); dn[3] = dpp_ror15(sd[3]);
;                         if (m == 0) { f32x4 halo = zero4; if (blk > 0) halo = *(const PG8_LAS f32x4*)(xb + (((((blk - 1) * 2 + 1) * 4 + wc) * 4 + fq) * 16 + (bj * 2 + n) * 4)); if (fr == 0) up = halo; }
;                         if (m == 3) { f32x4 halo = zero4; if (blk < 3) halo = *(const PG8_LAS f32x4*)(xb + (((((blk + 1) * 2 + 0) * 4 + wc) * 4 + fq) * 16 + (bj * 2 + n) * 4)); if (fr == 15) dn = halo; }
;                         if (edge) { if (!upok) up = zero4; if (!dnok) dn = zero4; }
;                         res[bj] = bb[bj] + w0[bj] * up + w1[bj] * cur + w2[bj] * dn; }
;                     if (store_ok) {
;                         float o[4];
; #pragma unroll
;                         for (int j = 0; j < 4; ++j) { const float gg = res[1][j]; o[j] = gg * __builtin_amdgcn_rcpf(1.f + __expf(-gg)) * res[0][j]; }
;                         u32x2 w; w.x = cvt_pk_bf16(o[0], o[1]); w.y = cvt_pk_bf16(o[2], o[3]);
;                         *(u32x2*)(ACT + (size_t)(seqrow + t) * 2816 + ch0 + 4 * n) = w; } } }
	v_add_u32_e32 v220, s48, v233
	v_cmp_lt_i32_e32 vcc, 0, v220
	s_nop 1
	v_cndmask_b32_e32 v176, 0, v176, vcc
	v_cndmask_b32_e32 v177, 0, v177, vcc
	v_cmp_gt_i32_e32 vcc, s28, v220
	s_nop 1
	v_cndmask_b32_e32 v196, 0, v196, vcc
	v_cndmask_b32_e32 v197, 0, v197, vcc
	v_pk_fma_f32 v[202:203], v[156:157], v[176:177], v[168:169]
	v_pk_fma_f32 v[44:45], v[44:45], v[160:161], v[202:203]
	v_pk_fma_f32 v[44:45], v[164:165], v[196:197], v[44:45]
	ds_read_b64 v[176:177], v244 offset:768
	v_mad_u32_u24 v251, v39, 16, v201
	ds_read_b64 v[196:197], v251
	v_mul_f32_e32 v208, 0xbfb8aa3b, v66
	v_mul_f32_e32 v209, 0xbfb8aa3b, v67
	v_mul_f32_e32 v210, 0xbfb8aa3b, v68
	v_mul_f32_e32 v211, 0xbfb8aa3b, v69
	v_exp_f32_e32 v208, v208
	v_exp_f32_e32 v209, v209
	v_exp_f32_e32 v210, v210
	v_exp_f32_e32 v211, v211
	v_add_f32_e32 v208, 1.0, v208
	v_add_f32_e32 v209, 1.0, v209
	v_add_f32_e32 v210, 1.0, v210
	v_add_f32_e32 v211, 1.0, v211
	v_rcp_f32_e32 v208, v208
	v_rcp_f32_e32 v209, v209
	v_rcp_f32_e32 v210, v210
	v_rcp_f32_e32 v211, v211
	v_mul_f32_e32 v66, v66, v208
	v_mul_f32_e32 v67, v67, v209
	v_mul_f32_e32 v68, v68, v210
	v_mul_f32_e32 v69, v69, v211
	v_mul_f32_e32 v66, v70, v66
	v_mul_f32_e32 v67, v71, v67
	v_mul_f32_e32 v68, v72, v68
	v_mul_f32_e32 v69, v73, v69
	v_cvt_pk_bf16_f32 v212, v66, v67
	v_cvt_pk_bf16_f32 v213, v68, v69
	v_mad_u32_u24 v221, v227, s29, v247
	s_and_saveexec_b64 s[30:31], s[12:13]
	global_store_dwordx2 v221, v[212:213], s[10:11] offset:8
	s_mov_b64 exec, s[30:31]
	v_mul_f32_e32 v208, 0xbfb8aa3b, v58
	v_mul_f32_e32 v209, 0xbfb8aa3b, v59
	v_mul_f32_e32 v210, 0xbfb8aa3b, v60
	v_mul_f32_e32 v211, 0xbfb8aa3b, v61
	v_exp_f32_e32 v208, v208
	v_exp_f32_e32 v209, v209
	v_exp_f32_e32 v210, v210
	v_exp_f32_e32 v211, v211
	v_add_f32_e32 v208, 1.0, v208
	v_add_f32_e32 v209, 1.0, v209
	v_add_f32_e32 v210, 1.0, v210
	v_add_f32_e32 v211, 1.0, v211
	v_rcp_f32_e32 v208, v208
	v_rcp_f32_e32 v209, v209
	v_rcp_f32_e32 v210, v210
	v_rcp_f32_e32 v211, v211
	v_mul_f32_e32 v58, v58, v208
	v_mul_f32_e32 v59, v59, v209
	v_mul_f32_e32 v60, v60, v210
	v_mul_f32_e32 v61, v61, v211
	v_mul_f32_e32 v58, v62, v58
	v_mul_f32_e32 v59, v63, v59
	v_mul_f32_e32 v60, v64, v60
	v_mul_f32_e32 v61, v65, v61
	v_cvt_pk_bf16_f32 v218, v58, v59
	v_cvt_pk_bf16_f32 v219, v60, v61
	v_mad_u32_u24 v40, v231, s29, v247
	s_and_saveexec_b64 s[30:31], s[14:15]
	global_store_dwordx2 v40, v[218:219], s[10:11] offset:8
	s_mov_b64 exec, s[30:31]
	v_mul_f32_e32 v208, 0xbfb8aa3b, v50
	v_mul_f32_e32 v209, 0xbfb8aa3b, v51
	v_mul_f32_e32 v210, 0xbfb8aa3b, v52
	v_mul_f32_e32 v211, 0xbfb8aa3b, v53
	v_exp_f32_e32 v208, v208
	v_exp_f32_e32 v209, v209
	v_exp_f32_e32 v210, v210
	v_exp_f32_e32 v211, v211
	v_add_f32_e32 v208, 1.0, v208
	v_add_f32_e32 v209, 1.0, v209
	v_add_f32_e32 v210, 1.0, v210
	v_add_f32_e32 v211, 1.0, v211
	v_rcp_f32_e32 v208, v208
	v_rcp_f32_e32 v209, v209
	v_rcp_f32_e32 v210, v210
	v_rcp_f32_e32 v211, v211
	v_mul_f32_e32 v50, v50, v208
	v_mul_f32_e32 v51, v51, v209
	v_mul_f32_e32 v52, v52, v210
	v_mul_f32_e32 v53, v53, v211
	v_mul_f32_e32 v50, v54, v50
	v_mul_f32_e32 v51, v55, v51
	v_mul_f32_e32 v52, v56, v52
	v_mul_f32_e32 v53, v57, v53
	v_cvt_pk_bf16_f32 v212, v50, v51
	v_cvt_pk_bf16_f32 v213, v52, v53
	v_mad_u32_u24 v221, v232, s29, v247
	s_and_saveexec_b64 s[30:31], s[16:17]
	global_store_dwordx2 v221, v[212:213], s[10:11] offset:8
	s_mov_b64 exec, s[30:31]
	v_mul_f32_e32 v208, 0xbfb8aa3b, v42
	v_mul_f32_e32 v209, 0xbfb8aa3b, v43
	v_mul_f32_e32 v210, 0xbfb8aa3b, v44
	v_mul_f32_e32 v211, 0xbfb8aa3b, v45
	v_exp_f32_e32 v208, v208
	v_exp_f32_e32 v209, v209
	v_exp_f32_e32 v210, v210
	v_exp_f32_e32 v211, v211
	v_add_f32_e32 v208, 1.0, v208
	v_add_f32_e32 v209, 1.0, v209
	v_add_f32_e32 v210, 1.0, v210
	v_add_f32_e32 v211, 1.0, v211
	v_rcp_f32_e32 v208, v208
	v_rcp_f32_e32 v209, v209
	v_rcp_f32_e32 v210, v210
	v_rcp_f32_e32 v211, v211
	v_mul_f32_e32 v42, v42, v208
	v_mul_f32_e32 v43, v43, v209
	v_mul_f32_e32 v44, v44, v210
	v_mul_f32_e32 v45, v45, v211
	v_mul_f32_e32 v42, v46, v42
	v_mul_f32_e32 v43, v47, v43
	v_mul_f32_e32 v44, v48, v44
	v_mul_f32_e32 v45, v49, v45
	v_cvt_pk_bf16_f32 v218, v42, v43
	v_cvt_pk_bf16_f32 v219, v44, v45
	v_mad_u32_u24 v40, v233, s29, v247
	s_and_saveexec_b64 s[30:31], s[18:19]
	global_store_dwordx2 v40, v[218:219], s[10:11] offset:8
	s_mov_b64 exec, s[30:31]
	ds_write_b64 v243, v[32:33]
	ds_write_b64 v243, v[24:25] offset:256
	ds_write_b64 v243, v[16:17] offset:512
	ds_write_b64 v243, v[8:9] offset:768
	s_waitcnt lgkmcnt(10)
	v_add_u32_e32 v220, s48, v234
	v_cmp_lt_i32_e32 vcc, 0, v220
	s_nop 1
	v_cndmask_b32_e32 v170, 0, v170, vcc
	v_cndmask_b32_e32 v171, 0, v171, vcc
	v_cmp_gt_i32_e32 vcc, s28, v220
	s_nop 1
	v_cndmask_b32_e32 v178, 0, v178, vcc
	v_cndmask_b32_e32 v179, 0, v179, vcc
	v_pk_fma_f32 v[202:203], v[138:139], v[170:171], v[150:151]
	v_pk_fma_f32 v[30:31], v[30:31], v[142:143], v[202:203]
	v_pk_fma_f32 v[30:31], v[146:147], v[178:179], v[30:31]
	v_mad_u32_u24 v250, v38, 24, v199
	ds_read_b64 v[170:171], v250
	ds_read_b64 v[178:179], v243 offset:16
	s_waitcnt lgkmcnt(10)
	v_add_u32_e32 v220, s48, v235
	v_cmp_lt_i32_e32 vcc, 0, v220
	s_nop 1
	v_cndmask_b32_e32 v172, 0, v172, vcc
	v_cndmask_b32_e32 v173, 0, v173, vcc
	v_cmp_gt_i32_e32 vcc, s28, v220
	s_nop 1
	v_cndmask_b32_e32 v180, 0, v180, vcc
	v_cndmask_b32_e32 v181, 0, v181, vcc
	v_pk_fma_f32 v[202:203], v[138:139], v[172:173], v[150:151]
	v_pk_fma_f32 v[22:23], v[22:23], v[142:143], v[202:203]
	v_pk_fma_f32 v[22:23], v[146:147], v[180:181], v[22:23]
	ds_read_b64 v[172:173], v244 offset:256
	ds_read_b64 v[180:181], v243 offset:272
	s_waitcnt lgkmcnt(10)
; #define PG8_LAS __attribute__((address_space(3)))
; __device__ __forceinline__ float dpp_ror1(float v) { return __builtin_bit_cast(float, __builtin_amdgcn_update_dpp(0, __builtin_bit_cast(int, v), 0x121, 0xf, 0xf, false)); }
; __device__ __forceinline__ float dpp_ror15(float v) { return __builtin_bit_cast(float, __builtin_amdgcn_update_dpp(0, __builtin_bit_cast(int, v), 0x12F, 0xf, 0xf, false)); }
;     __device__ __forceinline__ void operator()(const f32x4 (&acc)[2][2][4][2], const Unit& u, int wr, int wc, int fr, int fq) const {
;     ...
;                 for (int m = 0; m < 4; ++m) { const int r = 128 * ai + 64 * wr + 16 * m + fr, t = tstart + r;
;                     const bool upok = t >= 1, dnok = (t + 1) < T, store_ok = (r >= vlo) && (r < vhi) && (t < T);
;                     f32x4 res[2];
; #pragma unroll
;                     for (int bj = 0; bj < 2; ++bj) { const f32x4 cur = acc[ai][bj][m][n];
;                         f32x4 su = cur, sd = cur;
;                         if (m > 0) { if (fr == 15) su = acc[ai][bj][m > 0 ? m - 1 : 0][n]; }
;                         if (m < 3) { if (fr == 0) sd = acc[ai][bj][m < 3 ? m + 1 : 3][n]; }
;                         f32x4 up, dn;
;                         up[0] = dpp_ror1(su[0]); up[1] = dpp_ror1(su[1]); up[2] = dpp_ror1(su[2]); up[3] = dpp_ror1(su[3]);
;                         dn[0] = dpp_ror15(sd[0]); dn[1] = dpp_ror15(sd[1]); dn[2] = dpp_ror15(sd[2]); dn[3] = dpp_ror15(sd[3]);
;                         if (m == 0) { f32x4 halo = zero4; if (blk > 0) halo = *(const PG8_LAS f32x4*)(xb + (((((blk - 1) * 2 + 1) * 4 + wc) * 4 + fq) * 16 + (bj * 2 + n) * 4)); if (fr == 0) up = halo; }
;                         if (m == 3) { f32x4 halo = zero4; if (blk < 3) halo = *(const PG8_LAS f32x4*)(xb + (((((blk + 1) * 2 + 0) * 4 + wc) * 4 + fq) * 16 + (bj * 2 + n) * 4)); if (fr == 15) dn = halo; }
;                         if (edge) { if (!upok) up = zero4; if (!dnok) dn = zero4; }
;                         res[bj] = bb[bj] + w0[bj] * up + w1[bj] * cur + w2[bj] * dn; }
	v_add_u32_e32 v220, s48, v236
	v_cmp_lt_i32_e32 vcc, 0, v220
	s_nop 1
	v_cndmask_b32_e32 v174, 0, v174, vcc
	v_cndmask_b32_e32 v175, 0, v175, vcc
	v_cmp_gt_i32_e32 vcc, s28, v220
	s_nop 1
	v_cndmask_b32_e32 v194, 0, v194, vcc
	v_cndmask_b32_e32 v195, 0, v195, vcc
	v_pk_fma_f32 v[202:203], v[138:139], v[174:175], v[150:151]
	v_pk_fma_f32 v[14:15], v[14:15], v[142:143], v[202:203]
	v_pk_fma_f32 v[14:15], v[146:147], v[194:195], v[14:15]
	ds_read_b64 v[174:175], v244 offset:512
	ds_read_b64 v[194:195], v243 offset:528
	s_waitcnt lgkmcnt(10)
	v_add_u32_e32 v220, s48, v237
	v_cmp_lt_i32_e32 vcc, 0, v220
	s_nop 1
	v_cndmask_b32_e32 v176, 0, v176, vcc
	v_cndmask_b32_e32 v177, 0, v177, vcc
	v_cmp_gt_i32_e32 vcc, s28, v220
	s_nop 1
	v_cndmask_b32_e32 v196, 0, v196, vcc
	v_cndmask_b32_e32 v197, 0, v197, vcc
	v_pk_fma_f32 v[202:203], v[138:139], v[176:177], v[150:151]
	v_pk_fma_f32 v[6:7], v[6:7], v[142:143], v[202:203]
	v_pk_fma_f32 v[6:7], v[146:147], v[196:197], v[6:7]
	ds_read_b64 v[176:177], v244 offset:768
	v_mad_u32_u24 v251, v39, 24, v201
	ds_read_b64 v[196:197], v251
	ds_write_b64 v243, v[26:27]
	ds_write_b64 v243, v[18:19] offset:256
	ds_write_b64 v243, v[10:11] offset:512
	ds_write_b64 v243, v[2:3] offset:768
	s_waitcnt lgkmcnt(10)
	v_add_u32_e32 v220, s48, v234
	v_cmp_lt_i32_e32 vcc, 0, v220
	s_nop 1
	v_cndmask_b32_e32 v170, 0, v170, vcc
	v_cndmask_b32_e32 v171, 0, v171, vcc
	v_cmp_gt_i32_e32 vcc, s28, v220
	s_nop 1
	v_cndmask_b32_e32 v178, 0, v178, vcc
	v_cndmask_b32_e32 v179, 0, v179, vcc
	v_pk_fma_f32 v[202:203], v[140:141], v[170:171], v[152:153]
	v_pk_fma_f32 v[32:33], v[32:33], v[144:145], v[202:203]
	v_pk_fma_f32 v[32:33], v[148:149], v[178:179], v[32:33]
	v_mad_u32_u24 v250, v38, 48, v199
	ds_read_b64 v[170:171], v250
	ds_read_b64 v[178:179], v243 offset:16
	s_waitcnt lgkmcnt(10)
	v_add_u32_e32 v220, s48, v235
	v_cmp_lt_i32_e32 vcc, 0, v220
	s_nop 1
	v_cndmask_b32_e32 v172, 0, v172, vcc
	v_cndmask_b32_e32 v173, 0, v173, vcc
	v_cmp_gt_i32_e32 vcc, s28, v220
	s_nop 1
	v_cndmask_b32_e32 v180, 0, v180, vcc
	v_cndmask_b32_e32 v181, 0, v181, vcc
	v_pk_fma_f32 v[202:203], v[140:141], v[172:173], v[152:153]
	v_pk_fma_f32 v[24:25], v[24:25], v[144:145], v[202:203]
	v_pk_fma_f32 v[24:25], v[148:149], v[180:181], v[24:25]
	ds_read_b64 v[172:173], v244 offset:256
	ds_read_b64 v[180:181], v243 offset:272
	s_waitcnt lgkmcnt(10)
	v_add_u32_e32 v220, s48, v236
	v_cmp_lt_i32_e32 vcc, 0, v220
	s_nop 1
	v_cndmask_b32_e32 v174, 0, v174, vcc
	v_cndmask_b32_e32 v175, 0, v175, vcc
	v_cmp_gt_i32_e32 vcc, s28, v220
	s_nop 1
	v_cndmask_b32_e32 v194, 0, v194, vcc
	v_cndmask_b32_e32 v195, 0, v195, vcc
	v_pk_fma_f32 v[202:203], v[140:141], v[174:175], v[152:153]
	v_pk_fma_f32 v[16:17], v[16:17], v[144:145], v[202:203]
	v_pk_fma_f32 v[16:17], v[148:149], v[194:195], v[16:17]
	ds_read_b64 v[174:175], v244 offset:512
	ds_read_b64 v[194:195], v243 offset:528
	s_waitcnt lgkmcnt(10)
	v_add_u32_e32 v220, s48, v237
	v_cmp_lt_i32_e32 vcc, 0, v220
	s_nop 1
	v_cndmask_b32_e32 v176, 0, v176, vcc
	v_cndmask_b32_e32 v177, 0, v177, vcc
	v_cmp_gt_i32_e32 vcc, s28, v220
	s_nop 1
	v_cndmask_b32_e32 v196, 0, v196, vcc
	v_cndmask_b32_e32 v197, 0, v197, vcc
	v_pk_fma_f32 v[202:203], v[140:141], v[176:177], v[152:153]
	v_pk_fma_f32 v[8:9], v[8:9], v[144:145], v[202:203]
	v_pk_fma_f32 v[8:9], v[148:149], v[196:197], v[8:9]
	ds_read_b64 v[176:177], v244 offset:768
	v_mad_u32_u24 v251, v39, 48, v201
	ds_read_b64 v[196:197], v251
	ds_write_b64 v243, v[28:29]
	ds_write_b64 v243, v[20:21] offset:256
	ds_write_b64 v243, v[12:13] offset:512
	ds_write_b64 v243, v[4:5] offset:768
	s_waitcnt lgkmcnt(10)
	v_add_u32_e32 v220, s48, v234
	v_cmp_lt_i32_e32 vcc, 0, v220
	s_nop 1
	v_cndmask_b32_e32 v170, 0, v170, vcc
	v_cndmask_b32_e32 v171, 0, v171, vcc
	v_cmp_gt_i32_e32 vcc, s28, v220
	s_nop 1
	v_cndmask_b32_e32 v178, 0, v178, vcc
	v_cndmask_b32_e32 v179, 0, v179, vcc
	v_pk_fma_f32 v[202:203], v[154:155], v[170:171], v[166:167]
	v_pk_fma_f32 v[26:27], v[26:27], v[158:159], v[202:203]
	v_pk_fma_f32 v[26:27], v[162:163], v[178:179], v[26:27]
	v_mad_u32_u24 v250, v38, 56, v199
	ds_read_b64 v[170:171], v250
	ds_read_b64 v[178:179], v243 offset:16
	s_waitcnt lgkmcnt(10)
	v_add_u32_e32 v220, s48, v235
	v_cmp_lt_i32_e32 vcc, 0, v220
	s_nop 1
	v_cndmask_b32_e32 v172, 0, v172, vcc
	v_cndmask_b32_e32 v173, 0, v173, vcc
	v_cmp_gt_i32_e32 vcc, s28, v220
	s_nop 1
	v_cndmask_b32_e32 v180, 0, v180, vcc
	v_cndmask_b32_e32 v181, 0, v181, vcc
	v_pk_fma_f32 v[202:203], v[154:155], v[172:173], v[166:167]
	v_pk_fma_f32 v[18:19], v[18:19], v[158:159], v[202:203]
	v_pk_fma_f32 v[18:19], v[162:163], v[180:181], v[18:19]
	ds_read_b64 v[172:173], v244 offset:256
	ds_read_b64 v[180:181], v243 offset:272
	s_waitcnt lgkmcnt(10)
	v_add_u32_e32 v220, s48, v236
	v_cmp_lt_i32_e32 vcc, 0, v220
	s_nop 1
	v_cndmask_b32_e32 v174, 0, v174, vcc
	v_cndmask_b32_e32 v175, 0, v175, vcc
	v_cmp_gt_i32_e32 vcc, s28, v220
	s_nop 1
	v_cndmask_b32_e32 v194, 0, v194, vcc
	v_cndmask_b32_e32 v195, 0, v195, vcc
	v_pk_fma_f32 v[202:203], v[154:155], v[174:175], v[166:167]
	v_pk_fma_f32 v[10:11], v[10:11], v[158:159], v[202:203]
	v_pk_fma_f32 v[10:11], v[162:163], v[194:195], v[10:11]
	ds_read_b64 v[174:175], v244 offset:512
	ds_read_b64 v[194:195], v243 offset:528
	s_waitcnt lgkmcnt(10)
	v_add_u32_e32 v220, s48, v237
	v_cmp_lt_i32_e32 vcc, 0, v220
	s_nop 1
	v_cndmask_b32_e32 v176, 0, v176, vcc
	v_cndmask_b32_e32 v177, 0, v177, vcc
	v_cmp_gt_i32_e32 vcc, s28, v220
	s_nop 1
	v_cndmask_b32_e32 v196, 0, v196, vcc
	v_cndmask_b32_e32 v197, 0, v197, vcc
	v_pk_fma_f32 v[202:203], v[154:155], v[176:177], v[166:167]
	v_pk_fma_f32 v[2:3], v[2:3], v[158:159], v[202:203]
	v_pk_fma_f32 v[2:3], v[162:163], v[196:197], v[2:3]
	ds_read_b64 v[176:177], v244 offset:768
	v_mad_u32_u24 v251, v39, 56, v201
	ds_read_b64 v[196:197], v251
	s_waitcnt lgkmcnt(6)
; #define PG8_LAS __attribute__((address_space(3)))
; __device__ __forceinline__ unsigned cvt_pk_bf16(float lo, float hi) { unsigned r; asm volatile("v_cvt_pk_bf16_f32 %0, %1, %2" : "=v"(r) : "v"(lo), "v"(hi)); return r; }
;     __device__ __forceinline__ void operator()(const f32x4 (&acc)[2][2][4][2], const Unit& u, int wr, int wc, int fr, int fq) const {
;     ...
;                 for (int m = 0; m < 4; ++m) { const int r = 128 * ai + 64 * wr + 16 * m + fr, t = tstart + r;
;                     const bool upok = t >= 1, dnok = (t + 1) < T, store_ok = (r >= vlo) && (r < vhi) && (t < T);
;                     f32x4 res[2];
; #pragma unroll
;                     for (int bj = 0; bj < 2; ++bj) { const f32x4 cur = acc[ai][bj][m][n];
;                         f32x4 su = cur, sd = cur;
;                         if (m > 0) { if (fr == 15) su = acc[ai][bj][m > 0 ? m - 1 : 0][n]; }
;                         if (m < 3) { if (fr == 0) sd = acc[ai][bj][m < 3 ? m + 1 : 3][n]; }
;                         f32x4 up, dn;
;                         up[0] = dpp_ror1(su[0]); up[1] = dpp_ror1(su[1]); up[2] = dpp_ror1(su[2]); up[3] = dpp_ror1(su[3]);
;                         dn[0] = dpp_ror15(sd[0]); dn[1] = dpp_ror15(sd[1]); dn[2] = dpp_ror15(sd[2]); dn[3] = dpp_ror15(sd[3]);
;                         if (m == 0) { f32x4 halo = zero4; if (blk > 0) halo = *(const PG8_LAS f32x4*)(xb + (((((blk - 1) * 2 + 1) * 4 + wc) * 4 + fq) * 16 + (bj * 2 + n) * 4)); if (fr == 0) up = halo; }
;                         if (m == 3) { f32x4 halo = zero4; if (blk < 3) halo = *(const PG8_LAS f32x4*)(xb + (((((blk + 1) * 2 + 0) * 4 + wc) * 4 + fq) * 16 + (bj * 2 + n) * 4)); if (fr == 15) dn = halo; }
;                         if (edge) { if (!upok) up = zero4; if (!dnok) dn = zero4; }
;                         res[bj] = bb[bj] + w0[bj] * up + w1[bj] * cur + w2[bj] * dn; }
;                     if (store_ok) {
;                         float o[4];
; #pragma unroll
;                         for (int j = 0; j < 4; ++j) { const float gg = res[1][j]; o[j] = gg * __builtin_amdgcn_rcpf(1.f + __expf(-gg)) * res[0][j]; }
;                         u32x2 w; w.x = cvt_pk_bf16(o[0], o[1]); w.y = cvt_pk_bf16(o[2], o[3]);
;                         *(u32x2*)(ACT + (size_t)(seqrow + t) * 2816 + ch0 + 4 * n) = w; } } }
	v_add_u32_e32 v220, s48, v234
	v_cmp_lt_i32_e32 vcc, 0, v220
	s_nop 1
	v_cndmask_b32_e32 v170, 0, v170, vcc
	v_cndmask_b32_e32 v171, 0, v171, vcc
	v_cmp_gt_i32_e32 vcc, s28, v220
	s_nop 1
	v_cndmask_b32_e32 v178, 0, v178, vcc
	v_cndmask_b32_e32 v179, 0, v179, vcc
	v_pk_fma_f32 v[202:203], v[156:157], v[170:171], v[168:169]
	v_pk_fma_f32 v[28:29], v[28:29], v[160:161], v[202:203]
	v_pk_fma_f32 v[28:29], v[164:165], v[178:179], v[28:29]
	s_waitcnt lgkmcnt(4)
	v_add_u32_e32 v220, s48, v235
	v_cmp_lt_i32_e32 vcc, 0, v220
	s_nop 1
	v_cndmask_b32_e32 v172, 0, v172, vcc
	v_cndmask_b32_e32 v173, 0, v173, vcc
	v_cmp_gt_i32_e32 vcc, s28, v220
	s_nop 1
	v_cndmask_b32_e32 v180, 0, v180, vcc
	v_cndmask_b32_e32 v181, 0, v181, vcc
	v_pk_fma_f32 v[202:203], v[156:157], v[172:173], v[168:169]
	v_pk_fma_f32 v[20:21], v[20:21], v[160:161], v[202:203]
	v_pk_fma_f32 v[20:21], v[164:165], v[180:181], v[20:21]
	s_waitcnt lgkmcnt(2)
	v_add_u32_e32 v220, s48, v236
	v_cmp_lt_i32_e32 vcc, 0, v220
	s_nop 1
	v_cndmask_b32_e32 v174, 0, v174, vcc
	v_cndmask_b32_e32 v175, 0, v175, vcc
	v_cmp_gt_i32_e32 vcc, s28, v220
	s_nop 1
	v_cndmask_b32_e32 v194, 0, v194, vcc
	v_cndmask_b32_e32 v195, 0, v195, vcc
	v_pk_fma_f32 v[202:203], v[156:157], v[174:175], v[168:169]
	v_pk_fma_f32 v[12:13], v[12:13], v[160:161], v[202:203]
	v_pk_fma_f32 v[12:13], v[164:165], v[194:195], v[12:13]
	s_waitcnt lgkmcnt(0)
	v_add_u32_e32 v220, s48, v237
	v_cmp_lt_i32_e32 vcc, 0, v220
	s_nop 1
	v_cndmask_b32_e32 v176, 0, v176, vcc
	v_cndmask_b32_e32 v177, 0, v177, vcc
	v_cmp_gt_i32_e32 vcc, s28, v220
	s_nop 1
	v_cndmask_b32_e32 v196, 0, v196, vcc
	v_cndmask_b32_e32 v197, 0, v197, vcc
	v_pk_fma_f32 v[202:203], v[156:157], v[176:177], v[168:169]
	v_pk_fma_f32 v[4:5], v[4:5], v[160:161], v[202:203]
	v_pk_fma_f32 v[4:5], v[164:165], v[196:197], v[4:5]
	v_mul_f32_e32 v208, 0xbfb8aa3b, v26
	v_mul_f32_e32 v209, 0xbfb8aa3b, v27
	v_mul_f32_e32 v210, 0xbfb8aa3b, v28
	v_mul_f32_e32 v211, 0xbfb8aa3b, v29
	v_exp_f32_e32 v208, v208
	v_exp_f32_e32 v209, v209
	v_exp_f32_e32 v210, v210
	v_exp_f32_e32 v211, v211
	v_add_f32_e32 v208, 1.0, v208
	v_add_f32_e32 v209, 1.0, v209
	v_add_f32_e32 v210, 1.0, v210
	v_add_f32_e32 v211, 1.0, v211
	v_rcp_f32_e32 v208, v208
	v_rcp_f32_e32 v209, v209
	v_rcp_f32_e32 v210, v210
	v_rcp_f32_e32 v211, v211
	v_mul_f32_e32 v26, v26, v208
	v_mul_f32_e32 v27, v27, v209
	v_mul_f32_e32 v28, v28, v210
	v_mul_f32_e32 v29, v29, v211
	v_mul_f32_e32 v26, v30, v26
	v_mul_f32_e32 v27, v31, v27
	v_mul_f32_e32 v28, v32, v28
	v_mul_f32_e32 v29, v33, v29
	v_cvt_pk_bf16_f32 v212, v26, v27
	v_cvt_pk_bf16_f32 v213, v28, v29
	v_mad_u32_u24 v221, v234, s29, v247
	s_and_saveexec_b64 s[30:31], s[20:21]
	global_store_dwordx2 v221, v[212:213], s[10:11] offset:8
	s_mov_b64 exec, s[30:31]
	v_mul_f32_e32 v208, 0xbfb8aa3b, v18
	v_mul_f32_e32 v209, 0xbfb8aa3b, v19
	v_mul_f32_e32 v210, 0xbfb8aa3b, v20
	v_mul_f32_e32 v211, 0xbfb8aa3b, v21
	v_exp_f32_e32 v208, v208
	v_exp_f32_e32 v209, v209
	v_exp_f32_e32 v210, v210
	v_exp_f32_e32 v211, v211
	v_add_f32_e32 v208, 1.0, v208
	v_add_f32_e32 v209, 1.0, v209
	v_add_f32_e32 v210, 1.0, v210
	v_add_f32_e32 v211, 1.0, v211
	v_rcp_f32_e32 v208, v208
	v_rcp_f32_e32 v209, v209
	v_rcp_f32_e32 v210, v210
	v_rcp_f32_e32 v211, v211
	v_mul_f32_e32 v18, v18, v208
	v_mul_f32_e32 v19, v19, v209
	v_mul_f32_e32 v20, v20, v210
	v_mul_f32_e32 v21, v21, v211
	v_mul_f32_e32 v18, v22, v18
	v_mul_f32_e32 v19, v23, v19
	v_mul_f32_e32 v20, v24, v20
	v_mul_f32_e32 v21, v25, v21
	v_cvt_pk_bf16_f32 v218, v18, v19
	v_cvt_pk_bf16_f32 v219, v20, v21
	v_mad_u32_u24 v40, v235, s29, v247
	s_and_saveexec_b64 s[30:31], s[22:23]
	global_store_dwordx2 v40, v[218:219], s[10:11] offset:8
	s_mov_b64 exec, s[30:31]
	v_mul_f32_e32 v208, 0xbfb8aa3b, v10
	v_mul_f32_e32 v209, 0xbfb8aa3b, v11
	v_mul_f32_e32 v210, 0xbfb8aa3b, v12
	v_mul_f32_e32 v211, 0xbfb8aa3b, v13
	v_exp_f32_e32 v208, v208
	v_exp_f32_e32 v209, v209
	v_exp_f32_e32 v210, v210
	v_exp_f32_e32 v211, v211
	v_add_f32_e32 v208, 1.0, v208
	v_add_f32_e32 v209, 1.0, v209
	v_add_f32_e32 v210, 1.0, v210
	v_add_f32_e32 v211, 1.0, v211
	v_rcp_f32_e32 v208, v208
	v_rcp_f32_e32 v209, v209
	v_rcp_f32_e32 v210, v210
	v_rcp_f32_e32 v211, v211
	v_mul_f32_e32 v10, v10, v208
	v_mul_f32_e32 v11, v11, v209
	v_mul_f32_e32 v12, v12, v210
	v_mul_f32_e32 v13, v13, v211
	v_mul_f32_e32 v10, v14, v10
	v_mul_f32_e32 v11, v15, v11
	v_mul_f32_e32 v12, v16, v12
	v_mul_f32_e32 v13, v17, v13
	v_cvt_pk_bf16_f32 v212, v10, v11
	v_cvt_pk_bf16_f32 v213, v12, v13
	v_mad_u32_u24 v221, v236, s29, v247
	s_and_saveexec_b64 s[30:31], s[24:25]
	global_store_dwordx2 v221, v[212:213], s[10:11] offset:8
	s_mov_b64 exec, s[30:31]
	v_mul_f32_e32 v208, 0xbfb8aa3b, v2
	v_mul_f32_e32 v209, 0xbfb8aa3b, v3
	v_mul_f32_e32 v210, 0xbfb8aa3b, v4
	v_mul_f32_e32 v211, 0xbfb8aa3b, v5
	v_exp_f32_e32 v208, v208
	v_exp_f32_e32 v209, v209
	v_exp_f32_e32 v210, v210
	v_exp_f32_e32 v211, v211
	v_add_f32_e32 v208, 1.0, v208
	v_add_f32_e32 v209, 1.0, v209
	v_add_f32_e32 v210, 1.0, v210
	v_add_f32_e32 v211, 1.0, v211
	v_rcp_f32_e32 v208, v208
	v_rcp_f32_e32 v209, v209
	v_rcp_f32_e32 v210, v210
	v_rcp_f32_e32 v211, v211
	v_mul_f32_e32 v2, v2, v208
	v_mul_f32_e32 v3, v3, v209
	v_mul_f32_e32 v4, v4, v210
	v_mul_f32_e32 v5, v5, v211
	v_mul_f32_e32 v2, v6, v2
	v_mul_f32_e32 v3, v7, v3
	v_mul_f32_e32 v4, v8, v4
	v_mul_f32_e32 v5, v9, v5
	v_cvt_pk_bf16_f32 v218, v2, v3
	v_cvt_pk_bf16_f32 v219, v4, v5
	v_mad_u32_u24 v40, v237, s29, v247
	s_and_saveexec_b64 s[30:31], s[26:27]
	global_store_dwordx2 v40, v[218:219], s[10:11] offset:8
	s_mov_b64 exec, s[30:31]
